# P1: pairs of adjacent column tiles as one 256x256 block per workgroup (hand-written LDS-DMA double-buffered MFMA loop, 64x128 per wave), XCD-aware job assignment for pairs and remaining single tiles
# speedup vs baseline: 1.0195x; 1.0195x over previous
; template <bool SWAP, class Epi>
; DI void gemm_tile(const u16* __restrict__ A, int lda, const u16* __restrict__ Bw, int ldb, int K, char* lds, Epi epi) {
;     ...
;   const int lrow = tid >> 3, lkc = tid & 7;
;   u32x4 ra0[4], rb0[2], ra1[4], rb1[2];
;   const u16* ap = A + (size_t)lrow * lda + lkc * 8;
;   const u16* bp = Bw + (size_t)lrow * ldb + lkc * 8;
;   const int nk = K >> 6;
;   auto gload = [&](int kt, u32x4* ra, u32x4* rb) {
; #pragma unroll
;     for (int j = 0; j < 4; ++j) ra[j] = *(const u32x4*)(ap + (size_t)(64 * j) * lda + kt * 64);
; #pragma unroll
;     for (int j = 0; j < 2; ++j) rb[j] = *(const u32x4*)(bp + (size_t)(64 * j) * ldb + kt * 64);
;   };
;   auto lstore = [&](int st, const u32x4* ra, const u32x4* rb) {
;     char* base = lds + st * GEMM_STAGE;
; #pragma unroll
;     for (int j = 0; j < 4; ++j) *(u32x4*)(base + ((lrow + 64 * j) * 72 + lkc * 8) * 2) = ra[j];
; #pragma unroll
;     for (int j = 0; j < 2; ++j) *(u32x4*)(base + 36864 + ((lrow + 64 * j) * 72 + lkc * 8) * 2) = rb[j];
;   };
;   auto compute = [&](int st) {
;     const char* as = lds + st * GEMM_STAGE;
;     const char* bs = as + 36864;
; #pragma unroll
;     for (int ks = 0; ks < 4; ++ks) {
;       bf16x8 af[2], bfr[2];
; #pragma unroll
;       for (int mi = 0; mi < 2; ++mi) af[mi] = *(const bf16x8*)(as + ((wm * 64 + mi * 32 + r) * 72 + ks * 16 + 8 * h) * 2);
; #pragma unroll
;       for (int ni = 0; ni < 2; ++ni) bfr[ni] = *(const bf16x8*)(bs + ((wn * 64 + ni * 32 + r) * 72 + ks * 16 + 8 * h) * 2);
; #pragma unroll
;       for (int mi = 0; mi < 2; ++mi)
; #pragma unroll
;         for (int ni = 0; ni < 2; ++ni) {
;           if (SWAP) acc[mi][ni] = MFMA32(bfr[ni], af[mi], acc[mi][ni]);
;           else acc[mi][ni] = MFMA32(af[mi], bfr[ni], acc[mi][ni]);
; DI void inproj_tile(const Params& p, int l, int mt, int nt, char* lds) {
;   const int tid = opaque_tid(), lane = tid & 63, w = tid >> 6, r = lane & 31, h = lane >> 5;
;   const int wm = w & 3, wn = w >> 2;
;   const int m0 = mt * 256;
;   const u16* A = p.Xb + (size_t)m0 * DM;
;   const u16* Bw = p.Wt_in + (size_t)(l & 1) * NIN * DM + (size_t)nt * 128 * DM;
;   if (nt < 42) {
;     float ssq = 0.f;
;     gemm_tile<true>(A, DM, Bw, DM, DM, lds, [&](int mi, int ni, const f32x16& a) {
;       const int tok = m0 + wm * 64 + mi * 32 + r;
;       store_rowmajor(p.H + (size_t)tok * LDH + nt * 128 + wn * 64 + ni * 32, a, h, 1.f);
.LBB0_320:
	v_readlane_b32 s0, v240, 17
	v_readlane_b32 s1, v240, 18
	s_andn2_b64 vcc, exec, s[0:1]
	s_lshl_b32 s0, s38, 4
	s_lshl_b32 s50, s38, 3
	v_writelane_b32 v238, s0, 45
	s_nop 1
	v_writelane_b32 v238, s1, 46
	s_cbranch_vccnz .LBB0_370
	s_bitcmp1_b32 s38, 0
	v_readlane_b32 s4, v241, 16
	s_cselect_b32 s0, 0xc00000, 0
	s_add_u32 s18, s4, s0
	v_readlane_b32 s0, v238, 45
	v_readlane_b32 s5, v241, 17
	s_addc_u32 s19, s5, 0
	s_mov_b32 s1, s61
	s_mov_b32 s2, s0
	v_writelane_b32 v238, s2, 45
	s_lshl_b64 s[0:1], s[0:1], 2
	v_readlane_b32 s6, v241, 42
	v_writelane_b32 v238, s3, 46
	v_readlane_b32 s7, v241, 43
	v_readlane_b32 s10, v241, 46
	s_add_u32 s20, s6, s0
	s_addc_u32 s21, s7, s1
	s_lshl_b32 s22, s10, 7
	v_readlane_b32 s23, v238, 17
	v_readlane_b32 s0, v238, 16
	s_and_b32 s41, s0, 7
	s_lshr_b32 s101, s0, 3
	s_cmp_gt_u32 s41, 5
	s_cbranch_scc1 .Lpp_done
.Lpp_loop:
	s_cmpk_ge_u32 s101, 0xd1
	s_cbranch_scc1 .Lpp_done
	s_mul_i32 s0, s101, 0x5556
	s_lshr_b32 s26, s0, 16
	s_mul_i32 s0, s26, 3
	s_sub_i32 s0, s101, s0
	s_mul_i32 s0, s0, 6
	s_add_i32 s0, s0, s41
	s_cmpk_lt_u32 s101, 0xc6
	s_cbranch_scc1 .Lpp_col
	s_mul_i32 s1, s41, 11
	s_add_i32 s1, s1, s101
	s_sub_i32 s26, s1, 0xc6
	s_movk_i32 s0, 18
.Lpp_col:
	s_lshl_b32 s1, s0, 1
	s_cmp_gt_u32 s0, 1
	s_cselect_b32 s2, 4, 0
	s_add_i32 s2, s1, s2
	v_readlane_b32 s4, v241, 26
	v_readlane_b32 s5, v241, 27
	v_readlane_b32 s8, v241, 24
	v_readlane_b32 s9, v241, 25
	v_lshrrev_b32_e32 v0, 6, v152
	v_and_b32_e32 v1, 63, v152
	s_lshl_b32 s0, s26, 19
	s_add_u32 s4, s4, s0
	s_addc_u32 s5, s5, 0
	s_lshl_b32 s0, s2, 18
	s_add_u32 s6, s18, s0
	s_addc_u32 s7, s19, 0
	v_readfirstlane_b32 s3, v0
	s_lshl_b32 s0, s3, 16
	s_add_u32 s68, s4, s0
	s_addc_u32 s69, s5, 0
	s_add_u32 s70, s68, 0x3c00
	s_addc_u32 s71, s69, 0
	s_add_u32 s72, s70, 0x3c00
	s_addc_u32 s73, s71, 0
	s_add_u32 s74, s72, 0x3c00
	s_addc_u32 s75, s73, 0
	s_add_u32 s76, s6, s0
	s_addc_u32 s77, s7, 0
	s_add_u32 s78, s76, 0x3c00
	s_addc_u32 s79, s77, 0
	s_add_u32 s80, s78, 0x3c00
	s_addc_u32 s81, s79, 0
	s_add_u32 s82, s80, 0x3c00
	s_addc_u32 s83, s81, 0
	s_lshl_b32 s40, s3, 12
	s_add_i32 s44, s40, 0
	s_add_i32 s45, s40, 0x8000
	s_add_i32 s46, s40, 0x10000
	s_add_i32 s47, s40, 0x18000
	v_lshrrev_b32_e32 v2, 4, v1
	v_and_b32_e32 v0, 7, v1
	v_xor_b32_e32 v2, v2, v0
	v_lshlrev_b32_e32 v2, 4, v2
	v_lshrrev_b32_e32 v0, 3, v1
	v_lshlrev_b32_e32 v0, 11, v0
	v_add_u32_e32 v208, v2, v0
	v_xor_b32_e32 v209, 64, v208
	s_mov_b32 m0, s44
	s_nop 0
	global_load_lds_dwordx4 v208, s[68:69]
	global_load_lds_dwordx4 v209, s[70:71] offset:1024
	global_load_lds_dwordx4 v208, s[72:73] offset:2048
	global_load_lds_dwordx4 v209, s[74:75] offset:3072
	s_mov_b32 m0, s46
	s_nop 0
	global_load_lds_dwordx4 v208, s[76:77]
	global_load_lds_dwordx4 v209, s[78:79] offset:1024
	global_load_lds_dwordx4 v208, s[80:81] offset:2048
	global_load_lds_dwordx4 v209, s[82:83] offset:3072
	v_add_u32_e32 v208, 0x80, v208
	v_add_u32_e32 v209, 0x80, v209
	v_and_b32_e32 v0, 31, v1
	v_lshrrev_b32_e32 v2, 1, v0
	v_and_b32_e32 v2, 7, v2
	v_lshrrev_b32_e32 v1, 5, v1
	v_xor_b32_e32 v2, v2, v1
	v_lshlrev_b32_e32 v0, 7, v0
	s_and_b32 s0, s3, 3
	s_lshr_b32 s1, s3, 2
	s_lshl_b32 s10, s0, 13
	s_lshl_b32 s11, s1, 13
	s_add_i32 s11, s11, 0x10000
	v_xor_b32_e32 v214, 0, v2
	v_lshl_add_u32 v214, v214, 4, v0
	v_add_u32_e32 v210, s10, v214
	v_add_u32_e32 v214, s11, v214
	v_xor_b32_e32 v215, 2, v2
	v_lshl_add_u32 v215, v215, 4, v0
	v_add_u32_e32 v211, s10, v215
	v_add_u32_e32 v215, s11, v215
	v_xor_b32_e32 v216, 4, v2
	v_lshl_add_u32 v216, v216, 4, v0
	v_add_u32_e32 v212, s10, v216
	v_add_u32_e32 v216, s11, v216
	v_xor_b32_e32 v217, 6, v2
	v_lshl_add_u32 v217, v217, 4, v0
	v_add_u32_e32 v213, s10, v217
	v_add_u32_e32 v217, s11, v217
	s_lshl_b32 s12, s26, 8
	s_lshl_b32 s0, s0, 6
	s_add_i32 s12, s12, s0
	v_lshrrev_b32_e32 v0, 7, v0
	v_add_u32_e32 v0, s12, v0
	v_mul_u32_u24_e32 v0, 0x2a00, v0
	s_lshl_b32 s12, s2, 8
	s_lshl_b32 s1, s1, 7
	s_add_i32 s12, s12, s1
	v_lshlrev_b32_e32 v1, 4, v1
	v_add3_u32 v218, v0, v1, s12
	v_add_u32_e32 v219, 0x54000, v218
	s_waitcnt vmcnt(0) lgkmcnt(0)
	s_barrier
	ds_read_b128 v[132:135], v210 offset:0
	ds_read_b128 v[136:139], v210 offset:4096
	ds_read_b128 v[140:143], v214 offset:0
	ds_read_b128 v[144:147], v214 offset:4096
	ds_read_b128 v[148:151], v214 offset:16384
	ds_read_b128 v[158:161], v214 offset:20480
	s_mov_b32 m0, s45
	s_nop 0
	global_load_lds_dwordx4 v208, s[68:69]
	global_load_lds_dwordx4 v209, s[70:71] offset:1024
	global_load_lds_dwordx4 v208, s[72:73] offset:2048
	global_load_lds_dwordx4 v209, s[74:75] offset:3072
	ds_read_b128 v[162:165], v211 offset:0
	ds_read_b128 v[168:171], v211 offset:4096
	ds_read_b128 v[172:175], v215 offset:0
	ds_read_b128 v[176:179], v215 offset:4096
	ds_read_b128 v[180:183], v215 offset:16384
	ds_read_b128 v[184:187], v215 offset:20480
	s_waitcnt lgkmcnt(6)
	v_mfma_f32_32x32x16_bf16 v[4:19], v[140:143], v[132:135], 0
	v_mfma_f32_32x32x16_bf16 v[68:83], v[140:143], v[136:139], 0
	v_mfma_f32_32x32x16_bf16 v[20:35], v[144:147], v[132:135], 0
	v_mfma_f32_32x32x16_bf16 v[84:99], v[144:147], v[136:139], 0
	v_mfma_f32_32x32x16_bf16 v[36:51], v[148:151], v[132:135], 0
	v_mfma_f32_32x32x16_bf16 v[100:115], v[148:151], v[136:139], 0
	v_mfma_f32_32x32x16_bf16 v[52:67], v[158:161], v[132:135], 0
	v_mfma_f32_32x32x16_bf16 v[116:131], v[158:161], v[136:139], 0
	s_mov_b32 m0, s47
	s_nop 0
	global_load_lds_dwordx4 v208, s[76:77]
	global_load_lds_dwordx4 v209, s[78:79] offset:1024
	global_load_lds_dwordx4 v208, s[80:81] offset:2048
	global_load_lds_dwordx4 v209, s[82:83] offset:3072
	v_add_u32_e32 v208, 0x80, v208
	v_add_u32_e32 v209, 0x80, v209
	ds_read_b128 v[132:135], v212 offset:0
	ds_read_b128 v[136:139], v212 offset:4096
	ds_read_b128 v[140:143], v216 offset:0
	ds_read_b128 v[144:147], v216 offset:4096
	ds_read_b128 v[148:151], v216 offset:16384
	ds_read_b128 v[158:161], v216 offset:20480
	s_waitcnt lgkmcnt(6)
; #define MFMA32(a, b, c) __builtin_amdgcn_mfma_f32_32x32x16_bf16((a), (b), (c), 0, 0, 0)
; template <bool SWAP, class Epi>
; DI void gemm_tile(const u16* __restrict__ A, int lda, const u16* __restrict__ Bw, int ldb, int K, char* lds, Epi epi) {
;     ...
;   auto compute = [&](int st) {
;     const char* as = lds + st * GEMM_STAGE;
;     const char* bs = as + 36864;
; #pragma unroll
;     for (int ks = 0; ks < 4; ++ks) {
;       bf16x8 af[2], bfr[2];
; #pragma unroll
;       for (int mi = 0; mi < 2; ++mi) af[mi] = *(const bf16x8*)(as + ((wm * 64 + mi * 32 + r) * 72 + ks * 16 + 8 * h) * 2);
; #pragma unroll
;       for (int ni = 0; ni < 2; ++ni) bfr[ni] = *(const bf16x8*)(bs + ((wn * 64 + ni * 32 + r) * 72 + ks * 16 + 8 * h) * 2);
; #pragma unroll
;       for (int mi = 0; mi < 2; ++mi)
; #pragma unroll
;         for (int ni = 0; ni < 2; ++ni) {
;           if (SWAP) acc[mi][ni] = MFMA32(bfr[ni], af[mi], acc[mi][ni]);
;           else acc[mi][ni] = MFMA32(af[mi], bfr[ni], acc[mi][ni]);
;         }
;     }
;   };
;   gload(0, ra0, rb0);
;   lstore(0, ra0, rb0);
;   gload(1, ra1, rb1);
;   __syncthreads();
;   for (int kt = 0; kt < nk; kt += 2) {
;     if (kt + 2 < nk) gload(kt + 2, ra0, rb0);
;     compute(0);
;     lstore(1, ra1, rb1);
;     __syncthreads();
;     if (kt + 3 < nk) gload(kt + 3, ra1, rb1);
;     compute(1);
;     if (kt + 2 < nk) lstore(0, ra0, rb0);
;     __syncthreads();
	v_mfma_f32_32x32x16_bf16 v[4:19], v[172:175], v[162:165], v[4:19]
	v_mfma_f32_32x32x16_bf16 v[68:83], v[172:175], v[168:171], v[68:83]
	v_mfma_f32_32x32x16_bf16 v[20:35], v[176:179], v[162:165], v[20:35]
	v_mfma_f32_32x32x16_bf16 v[84:99], v[176:179], v[168:171], v[84:99]
	v_mfma_f32_32x32x16_bf16 v[36:51], v[180:183], v[162:165], v[36:51]
	v_mfma_f32_32x32x16_bf16 v[100:115], v[180:183], v[168:171], v[100:115]
	v_mfma_f32_32x32x16_bf16 v[52:67], v[184:187], v[162:165], v[52:67]
	v_mfma_f32_32x32x16_bf16 v[116:131], v[184:187], v[168:171], v[116:131]
	ds_read_b128 v[162:165], v213 offset:0
	ds_read_b128 v[168:171], v213 offset:4096
	ds_read_b128 v[172:175], v217 offset:0
	ds_read_b128 v[176:179], v217 offset:4096
	ds_read_b128 v[180:183], v217 offset:16384
	ds_read_b128 v[184:187], v217 offset:20480
	s_waitcnt lgkmcnt(6)
	v_mfma_f32_32x32x16_bf16 v[4:19], v[140:143], v[132:135], v[4:19]
	v_mfma_f32_32x32x16_bf16 v[68:83], v[140:143], v[136:139], v[68:83]
	v_mfma_f32_32x32x16_bf16 v[20:35], v[144:147], v[132:135], v[20:35]
	v_mfma_f32_32x32x16_bf16 v[84:99], v[144:147], v[136:139], v[84:99]
	v_mfma_f32_32x32x16_bf16 v[36:51], v[148:151], v[132:135], v[36:51]
	v_mfma_f32_32x32x16_bf16 v[100:115], v[148:151], v[136:139], v[100:115]
	v_mfma_f32_32x32x16_bf16 v[52:67], v[158:161], v[132:135], v[52:67]
	v_mfma_f32_32x32x16_bf16 v[116:131], v[158:161], v[136:139], v[116:131]
	s_waitcnt lgkmcnt(0)
	v_mfma_f32_32x32x16_bf16 v[4:19], v[172:175], v[162:165], v[4:19]
	v_mfma_f32_32x32x16_bf16 v[68:83], v[172:175], v[168:171], v[68:83]
	v_mfma_f32_32x32x16_bf16 v[20:35], v[176:179], v[162:165], v[20:35]
	v_mfma_f32_32x32x16_bf16 v[84:99], v[176:179], v[168:171], v[84:99]
	v_mfma_f32_32x32x16_bf16 v[36:51], v[180:183], v[162:165], v[36:51]
	v_mfma_f32_32x32x16_bf16 v[100:115], v[180:183], v[168:171], v[100:115]
	v_mfma_f32_32x32x16_bf16 v[52:67], v[184:187], v[162:165], v[52:67]
	v_mfma_f32_32x32x16_bf16 v[116:131], v[184:187], v[168:171], v[116:131]
	s_waitcnt vmcnt(0) lgkmcnt(0)
	s_barrier
	ds_read_b128 v[132:135], v210 offset:32768
	ds_read_b128 v[136:139], v210 offset:36864
	ds_read_b128 v[140:143], v214 offset:32768
	ds_read_b128 v[144:147], v214 offset:36864
	ds_read_b128 v[148:151], v214 offset:49152
	ds_read_b128 v[158:161], v214 offset:53248
	s_mov_b32 m0, s44
	s_nop 0
	global_load_lds_dwordx4 v208, s[68:69]
	global_load_lds_dwordx4 v209, s[70:71] offset:1024
	global_load_lds_dwordx4 v208, s[72:73] offset:2048
	global_load_lds_dwordx4 v209, s[74:75] offset:3072
	ds_read_b128 v[162:165], v211 offset:32768
	ds_read_b128 v[168:171], v211 offset:36864
	ds_read_b128 v[172:175], v215 offset:32768
	ds_read_b128 v[176:179], v215 offset:36864
	ds_read_b128 v[180:183], v215 offset:49152
	ds_read_b128 v[184:187], v215 offset:53248
	s_waitcnt lgkmcnt(6)
	v_mfma_f32_32x32x16_bf16 v[4:19], v[140:143], v[132:135], v[4:19]
	v_mfma_f32_32x32x16_bf16 v[68:83], v[140:143], v[136:139], v[68:83]
	v_mfma_f32_32x32x16_bf16 v[20:35], v[144:147], v[132:135], v[20:35]
	v_mfma_f32_32x32x16_bf16 v[84:99], v[144:147], v[136:139], v[84:99]
	v_mfma_f32_32x32x16_bf16 v[36:51], v[148:151], v[132:135], v[36:51]
	v_mfma_f32_32x32x16_bf16 v[100:115], v[148:151], v[136:139], v[100:115]
	v_mfma_f32_32x32x16_bf16 v[52:67], v[158:161], v[132:135], v[52:67]
	v_mfma_f32_32x32x16_bf16 v[116:131], v[158:161], v[136:139], v[116:131]
	s_mov_b32 m0, s46
	s_nop 0
	global_load_lds_dwordx4 v208, s[76:77]
	global_load_lds_dwordx4 v209, s[78:79] offset:1024
	global_load_lds_dwordx4 v208, s[80:81] offset:2048
	global_load_lds_dwordx4 v209, s[82:83] offset:3072
	v_add_u32_e32 v208, 0x80, v208
	v_add_u32_e32 v209, 0x80, v209
	ds_read_b128 v[132:135], v212 offset:32768
	ds_read_b128 v[136:139], v212 offset:36864
	ds_read_b128 v[140:143], v216 offset:32768
	ds_read_b128 v[144:147], v216 offset:36864
	ds_read_b128 v[148:151], v216 offset:49152
	ds_read_b128 v[158:161], v216 offset:53248
	s_waitcnt lgkmcnt(6)
	v_mfma_f32_32x32x16_bf16 v[4:19], v[172:175], v[162:165], v[4:19]
	v_mfma_f32_32x32x16_bf16 v[68:83], v[172:175], v[168:171], v[68:83]
	v_mfma_f32_32x32x16_bf16 v[20:35], v[176:179], v[162:165], v[20:35]
	v_mfma_f32_32x32x16_bf16 v[84:99], v[176:179], v[168:171], v[84:99]
	v_mfma_f32_32x32x16_bf16 v[36:51], v[180:183], v[162:165], v[36:51]
	v_mfma_f32_32x32x16_bf16 v[100:115], v[180:183], v[168:171], v[100:115]
	v_mfma_f32_32x32x16_bf16 v[52:67], v[184:187], v[162:165], v[52:67]
	v_mfma_f32_32x32x16_bf16 v[116:131], v[184:187], v[168:171], v[116:131]
	ds_read_b128 v[162:165], v213 offset:32768
	ds_read_b128 v[168:171], v213 offset:36864
	ds_read_b128 v[172:175], v217 offset:32768
	ds_read_b128 v[176:179], v217 offset:36864
	ds_read_b128 v[180:183], v217 offset:49152
	ds_read_b128 v[184:187], v217 offset:53248
	s_waitcnt lgkmcnt(6)
	v_mfma_f32_32x32x16_bf16 v[4:19], v[140:143], v[132:135], v[4:19]
	v_mfma_f32_32x32x16_bf16 v[68:83], v[140:143], v[136:139], v[68:83]
	v_mfma_f32_32x32x16_bf16 v[20:35], v[144:147], v[132:135], v[20:35]
	v_mfma_f32_32x32x16_bf16 v[84:99], v[144:147], v[136:139], v[84:99]
	v_mfma_f32_32x32x16_bf16 v[36:51], v[148:151], v[132:135], v[36:51]
	v_mfma_f32_32x32x16_bf16 v[100:115], v[148:151], v[136:139], v[100:115]
	v_mfma_f32_32x32x16_bf16 v[52:67], v[158:161], v[132:135], v[52:67]
	v_mfma_f32_32x32x16_bf16 v[116:131], v[158:161], v[136:139], v[116:131]
	s_waitcnt lgkmcnt(0)
	v_mfma_f32_32x32x16_bf16 v[4:19], v[172:175], v[162:165], v[4:19]
	v_mfma_f32_32x32x16_bf16 v[68:83], v[172:175], v[168:171], v[68:83]
	v_mfma_f32_32x32x16_bf16 v[20:35], v[176:179], v[162:165], v[20:35]
	v_mfma_f32_32x32x16_bf16 v[84:99], v[176:179], v[168:171], v[84:99]
	v_mfma_f32_32x32x16_bf16 v[36:51], v[180:183], v[162:165], v[36:51]
	v_mfma_f32_32x32x16_bf16 v[100:115], v[180:183], v[168:171], v[100:115]
	v_mfma_f32_32x32x16_bf16 v[52:67], v[184:187], v[162:165], v[52:67]
	v_mfma_f32_32x32x16_bf16 v[116:131], v[184:187], v[168:171], v[116:131]
	s_waitcnt vmcnt(0) lgkmcnt(0)
	s_barrier
; #define MFMA32(a, b, c) __builtin_amdgcn_mfma_f32_32x32x16_bf16((a), (b), (c), 0, 0, 0)
; template <bool SWAP, class Epi>
; DI void gemm_tile(const u16* __restrict__ A, int lda, const u16* __restrict__ Bw, int ldb, int K, char* lds, Epi epi) {
;     ...
;   auto compute = [&](int st) {
;     const char* as = lds + st * GEMM_STAGE;
;     const char* bs = as + 36864;
; #pragma unroll
;     for (int ks = 0; ks < 4; ++ks) {
;       bf16x8 af[2], bfr[2];
; #pragma unroll
;       for (int mi = 0; mi < 2; ++mi) af[mi] = *(const bf16x8*)(as + ((wm * 64 + mi * 32 + r) * 72 + ks * 16 + 8 * h) * 2);
; #pragma unroll
;       for (int ni = 0; ni < 2; ++ni) bfr[ni] = *(const bf16x8*)(bs + ((wn * 64 + ni * 32 + r) * 72 + ks * 16 + 8 * h) * 2);
; #pragma unroll
;       for (int mi = 0; mi < 2; ++mi)
; #pragma unroll
;         for (int ni = 0; ni < 2; ++ni) {
;           if (SWAP) acc[mi][ni] = MFMA32(bfr[ni], af[mi], acc[mi][ni]);
;           else acc[mi][ni] = MFMA32(af[mi], bfr[ni], acc[mi][ni]);
;         }
;     }
;   };
;   gload(0, ra0, rb0);
;   lstore(0, ra0, rb0);
;   gload(1, ra1, rb1);
;   __syncthreads();
;   for (int kt = 0; kt < nk; kt += 2) {
;     if (kt + 2 < nk) gload(kt + 2, ra0, rb0);
;     compute(0);
;     lstore(1, ra1, rb1);
;     __syncthreads();
;     if (kt + 3 < nk) gload(kt + 3, ra1, rb1);
;     compute(1);
;     if (kt + 2 < nk) lstore(0, ra0, rb0);
;     __syncthreads();
	ds_read_b128 v[132:135], v210 offset:0
	ds_read_b128 v[136:139], v210 offset:4096
	ds_read_b128 v[140:143], v214 offset:0
	ds_read_b128 v[144:147], v214 offset:4096
	ds_read_b128 v[148:151], v214 offset:16384
	ds_read_b128 v[158:161], v214 offset:20480
	s_mov_b32 m0, s45
	s_nop 0
	global_load_lds_dwordx4 v208, s[68:69]
	global_load_lds_dwordx4 v209, s[70:71] offset:1024
	global_load_lds_dwordx4 v208, s[72:73] offset:2048
	global_load_lds_dwordx4 v209, s[74:75] offset:3072
	ds_read_b128 v[162:165], v211 offset:0
	ds_read_b128 v[168:171], v211 offset:4096
	ds_read_b128 v[172:175], v215 offset:0
	ds_read_b128 v[176:179], v215 offset:4096
	ds_read_b128 v[180:183], v215 offset:16384
	ds_read_b128 v[184:187], v215 offset:20480
	s_waitcnt lgkmcnt(6)
	v_mfma_f32_32x32x16_bf16 v[4:19], v[140:143], v[132:135], v[4:19]
	v_mfma_f32_32x32x16_bf16 v[68:83], v[140:143], v[136:139], v[68:83]
	v_mfma_f32_32x32x16_bf16 v[20:35], v[144:147], v[132:135], v[20:35]
	v_mfma_f32_32x32x16_bf16 v[84:99], v[144:147], v[136:139], v[84:99]
	v_mfma_f32_32x32x16_bf16 v[36:51], v[148:151], v[132:135], v[36:51]
	v_mfma_f32_32x32x16_bf16 v[100:115], v[148:151], v[136:139], v[100:115]
	v_mfma_f32_32x32x16_bf16 v[52:67], v[158:161], v[132:135], v[52:67]
	v_mfma_f32_32x32x16_bf16 v[116:131], v[158:161], v[136:139], v[116:131]
	s_mov_b32 m0, s47
	s_nop 0
	global_load_lds_dwordx4 v208, s[76:77]
	global_load_lds_dwordx4 v209, s[78:79] offset:1024
	global_load_lds_dwordx4 v208, s[80:81] offset:2048
	global_load_lds_dwordx4 v209, s[82:83] offset:3072
	v_add_u32_e32 v208, 0x80, v208
	v_add_u32_e32 v209, 0x80, v209
	ds_read_b128 v[132:135], v212 offset:0
	ds_read_b128 v[136:139], v212 offset:4096
	ds_read_b128 v[140:143], v216 offset:0
	ds_read_b128 v[144:147], v216 offset:4096
	ds_read_b128 v[148:151], v216 offset:16384
	ds_read_b128 v[158:161], v216 offset:20480
	s_waitcnt lgkmcnt(6)
	v_mfma_f32_32x32x16_bf16 v[4:19], v[172:175], v[162:165], v[4:19]
	v_mfma_f32_32x32x16_bf16 v[68:83], v[172:175], v[168:171], v[68:83]
	v_mfma_f32_32x32x16_bf16 v[20:35], v[176:179], v[162:165], v[20:35]
	v_mfma_f32_32x32x16_bf16 v[84:99], v[176:179], v[168:171], v[84:99]
	v_mfma_f32_32x32x16_bf16 v[36:51], v[180:183], v[162:165], v[36:51]
	v_mfma_f32_32x32x16_bf16 v[100:115], v[180:183], v[168:171], v[100:115]
	v_mfma_f32_32x32x16_bf16 v[52:67], v[184:187], v[162:165], v[52:67]
	v_mfma_f32_32x32x16_bf16 v[116:131], v[184:187], v[168:171], v[116:131]
	ds_read_b128 v[162:165], v213 offset:0
	ds_read_b128 v[168:171], v213 offset:4096
	ds_read_b128 v[172:175], v217 offset:0
	ds_read_b128 v[176:179], v217 offset:4096
	ds_read_b128 v[180:183], v217 offset:16384
	ds_read_b128 v[184:187], v217 offset:20480
	s_waitcnt lgkmcnt(6)
	v_mfma_f32_32x32x16_bf16 v[4:19], v[140:143], v[132:135], v[4:19]
	v_mfma_f32_32x32x16_bf16 v[68:83], v[140:143], v[136:139], v[68:83]
	v_mfma_f32_32x32x16_bf16 v[20:35], v[144:147], v[132:135], v[20:35]
	v_mfma_f32_32x32x16_bf16 v[84:99], v[144:147], v[136:139], v[84:99]
	v_mfma_f32_32x32x16_bf16 v[36:51], v[148:151], v[132:135], v[36:51]
	v_mfma_f32_32x32x16_bf16 v[100:115], v[148:151], v[136:139], v[100:115]
	v_mfma_f32_32x32x16_bf16 v[52:67], v[158:161], v[132:135], v[52:67]
	v_mfma_f32_32x32x16_bf16 v[116:131], v[158:161], v[136:139], v[116:131]
	s_waitcnt lgkmcnt(0)
	v_mfma_f32_32x32x16_bf16 v[4:19], v[172:175], v[162:165], v[4:19]
	v_mfma_f32_32x32x16_bf16 v[68:83], v[172:175], v[168:171], v[68:83]
	v_mfma_f32_32x32x16_bf16 v[20:35], v[176:179], v[162:165], v[20:35]
	v_mfma_f32_32x32x16_bf16 v[84:99], v[176:179], v[168:171], v[84:99]
	v_mfma_f32_32x32x16_bf16 v[36:51], v[180:183], v[162:165], v[36:51]
	v_mfma_f32_32x32x16_bf16 v[100:115], v[180:183], v[168:171], v[100:115]
	v_mfma_f32_32x32x16_bf16 v[52:67], v[184:187], v[162:165], v[52:67]
	v_mfma_f32_32x32x16_bf16 v[116:131], v[184:187], v[168:171], v[116:131]
	s_waitcnt vmcnt(0) lgkmcnt(0)
	s_barrier
	ds_read_b128 v[132:135], v210 offset:32768
	ds_read_b128 v[136:139], v210 offset:36864
	ds_read_b128 v[140:143], v214 offset:32768
	ds_read_b128 v[144:147], v214 offset:36864
	ds_read_b128 v[148:151], v214 offset:49152
	ds_read_b128 v[158:161], v214 offset:53248
	s_mov_b32 m0, s44
	s_nop 0
	global_load_lds_dwordx4 v208, s[68:69]
	global_load_lds_dwordx4 v209, s[70:71] offset:1024
	global_load_lds_dwordx4 v208, s[72:73] offset:2048
	global_load_lds_dwordx4 v209, s[74:75] offset:3072
	ds_read_b128 v[162:165], v211 offset:32768
	ds_read_b128 v[168:171], v211 offset:36864
	ds_read_b128 v[172:175], v215 offset:32768
	ds_read_b128 v[176:179], v215 offset:36864
	ds_read_b128 v[180:183], v215 offset:49152
	ds_read_b128 v[184:187], v215 offset:53248
	s_waitcnt lgkmcnt(6)
	v_mfma_f32_32x32x16_bf16 v[4:19], v[140:143], v[132:135], v[4:19]
	v_mfma_f32_32x32x16_bf16 v[68:83], v[140:143], v[136:139], v[68:83]
	v_mfma_f32_32x32x16_bf16 v[20:35], v[144:147], v[132:135], v[20:35]
	v_mfma_f32_32x32x16_bf16 v[84:99], v[144:147], v[136:139], v[84:99]
	v_mfma_f32_32x32x16_bf16 v[36:51], v[148:151], v[132:135], v[36:51]
	v_mfma_f32_32x32x16_bf16 v[100:115], v[148:151], v[136:139], v[100:115]
	v_mfma_f32_32x32x16_bf16 v[52:67], v[158:161], v[132:135], v[52:67]
	v_mfma_f32_32x32x16_bf16 v[116:131], v[158:161], v[136:139], v[116:131]
	s_mov_b32 m0, s46
	s_nop 0
	global_load_lds_dwordx4 v208, s[76:77]
	global_load_lds_dwordx4 v209, s[78:79] offset:1024
	global_load_lds_dwordx4 v208, s[80:81] offset:2048
	global_load_lds_dwordx4 v209, s[82:83] offset:3072
	v_add_u32_e32 v208, 0x80, v208
	v_add_u32_e32 v209, 0x80, v209
	ds_read_b128 v[132:135], v212 offset:32768
	ds_read_b128 v[136:139], v212 offset:36864
	ds_read_b128 v[140:143], v216 offset:32768
	ds_read_b128 v[144:147], v216 offset:36864
	ds_read_b128 v[148:151], v216 offset:49152
	ds_read_b128 v[158:161], v216 offset:53248
	s_waitcnt lgkmcnt(6)
; #define MFMA32(a, b, c) __builtin_amdgcn_mfma_f32_32x32x16_bf16((a), (b), (c), 0, 0, 0)
; template <bool SWAP, class Epi>
; DI void gemm_tile(const u16* __restrict__ A, int lda, const u16* __restrict__ Bw, int ldb, int K, char* lds, Epi epi) {
;     ...
;   auto compute = [&](int st) {
;     const char* as = lds + st * GEMM_STAGE;
;     const char* bs = as + 36864;
; #pragma unroll
;     for (int ks = 0; ks < 4; ++ks) {
;       bf16x8 af[2], bfr[2];
; #pragma unroll
;       for (int mi = 0; mi < 2; ++mi) af[mi] = *(const bf16x8*)(as + ((wm * 64 + mi * 32 + r) * 72 + ks * 16 + 8 * h) * 2);
; #pragma unroll
;       for (int ni = 0; ni < 2; ++ni) bfr[ni] = *(const bf16x8*)(bs + ((wn * 64 + ni * 32 + r) * 72 + ks * 16 + 8 * h) * 2);
; #pragma unroll
;       for (int mi = 0; mi < 2; ++mi)
; #pragma unroll
;         for (int ni = 0; ni < 2; ++ni) {
;           if (SWAP) acc[mi][ni] = MFMA32(bfr[ni], af[mi], acc[mi][ni]);
;           else acc[mi][ni] = MFMA32(af[mi], bfr[ni], acc[mi][ni]);
;         }
;     }
;   };
;   gload(0, ra0, rb0);
;   lstore(0, ra0, rb0);
;   gload(1, ra1, rb1);
;   __syncthreads();
;   for (int kt = 0; kt < nk; kt += 2) {
;     if (kt + 2 < nk) gload(kt + 2, ra0, rb0);
;     compute(0);
;     lstore(1, ra1, rb1);
;     __syncthreads();
;     if (kt + 3 < nk) gload(kt + 3, ra1, rb1);
;     compute(1);
;     if (kt + 2 < nk) lstore(0, ra0, rb0);
;     __syncthreads();
	v_mfma_f32_32x32x16_bf16 v[4:19], v[172:175], v[162:165], v[4:19]
	v_mfma_f32_32x32x16_bf16 v[68:83], v[172:175], v[168:171], v[68:83]
	v_mfma_f32_32x32x16_bf16 v[20:35], v[176:179], v[162:165], v[20:35]
	v_mfma_f32_32x32x16_bf16 v[84:99], v[176:179], v[168:171], v[84:99]
	v_mfma_f32_32x32x16_bf16 v[36:51], v[180:183], v[162:165], v[36:51]
	v_mfma_f32_32x32x16_bf16 v[100:115], v[180:183], v[168:171], v[100:115]
	v_mfma_f32_32x32x16_bf16 v[52:67], v[184:187], v[162:165], v[52:67]
	v_mfma_f32_32x32x16_bf16 v[116:131], v[184:187], v[168:171], v[116:131]
	ds_read_b128 v[162:165], v213 offset:32768
	ds_read_b128 v[168:171], v213 offset:36864
	ds_read_b128 v[172:175], v217 offset:32768
	ds_read_b128 v[176:179], v217 offset:36864
	ds_read_b128 v[180:183], v217 offset:49152
	ds_read_b128 v[184:187], v217 offset:53248
	s_waitcnt lgkmcnt(6)
	v_mfma_f32_32x32x16_bf16 v[4:19], v[140:143], v[132:135], v[4:19]
	v_mfma_f32_32x32x16_bf16 v[68:83], v[140:143], v[136:139], v[68:83]
	v_mfma_f32_32x32x16_bf16 v[20:35], v[144:147], v[132:135], v[20:35]
	v_mfma_f32_32x32x16_bf16 v[84:99], v[144:147], v[136:139], v[84:99]
	v_mfma_f32_32x32x16_bf16 v[36:51], v[148:151], v[132:135], v[36:51]
	v_mfma_f32_32x32x16_bf16 v[100:115], v[148:151], v[136:139], v[100:115]
	v_mfma_f32_32x32x16_bf16 v[52:67], v[158:161], v[132:135], v[52:67]
	v_mfma_f32_32x32x16_bf16 v[116:131], v[158:161], v[136:139], v[116:131]
	s_waitcnt lgkmcnt(0)
	v_mfma_f32_32x32x16_bf16 v[4:19], v[172:175], v[162:165], v[4:19]
	v_mfma_f32_32x32x16_bf16 v[68:83], v[172:175], v[168:171], v[68:83]
	v_mfma_f32_32x32x16_bf16 v[20:35], v[176:179], v[162:165], v[20:35]
	v_mfma_f32_32x32x16_bf16 v[84:99], v[176:179], v[168:171], v[84:99]
	v_mfma_f32_32x32x16_bf16 v[36:51], v[180:183], v[162:165], v[36:51]
	v_mfma_f32_32x32x16_bf16 v[100:115], v[180:183], v[168:171], v[100:115]
	v_mfma_f32_32x32x16_bf16 v[52:67], v[184:187], v[162:165], v[52:67]
	v_mfma_f32_32x32x16_bf16 v[116:131], v[184:187], v[168:171], v[116:131]
	s_waitcnt vmcnt(0) lgkmcnt(0)
	s_barrier
	ds_read_b128 v[132:135], v210 offset:0
	ds_read_b128 v[136:139], v210 offset:4096
	ds_read_b128 v[140:143], v214 offset:0
	ds_read_b128 v[144:147], v214 offset:4096
	ds_read_b128 v[148:151], v214 offset:16384
	ds_read_b128 v[158:161], v214 offset:20480
	s_mov_b32 m0, s45
	s_nop 0
	global_load_lds_dwordx4 v208, s[68:69]
	global_load_lds_dwordx4 v209, s[70:71] offset:1024
	global_load_lds_dwordx4 v208, s[72:73] offset:2048
	global_load_lds_dwordx4 v209, s[74:75] offset:3072
	ds_read_b128 v[162:165], v211 offset:0
	ds_read_b128 v[168:171], v211 offset:4096
	ds_read_b128 v[172:175], v215 offset:0
	ds_read_b128 v[176:179], v215 offset:4096
	ds_read_b128 v[180:183], v215 offset:16384
	ds_read_b128 v[184:187], v215 offset:20480
	s_waitcnt lgkmcnt(6)
	v_mfma_f32_32x32x16_bf16 v[4:19], v[140:143], v[132:135], v[4:19]
	v_mfma_f32_32x32x16_bf16 v[68:83], v[140:143], v[136:139], v[68:83]
	v_mfma_f32_32x32x16_bf16 v[20:35], v[144:147], v[132:135], v[20:35]
	v_mfma_f32_32x32x16_bf16 v[84:99], v[144:147], v[136:139], v[84:99]
	v_mfma_f32_32x32x16_bf16 v[36:51], v[148:151], v[132:135], v[36:51]
	v_mfma_f32_32x32x16_bf16 v[100:115], v[148:151], v[136:139], v[100:115]
	v_mfma_f32_32x32x16_bf16 v[52:67], v[158:161], v[132:135], v[52:67]
	v_mfma_f32_32x32x16_bf16 v[116:131], v[158:161], v[136:139], v[116:131]
	s_mov_b32 m0, s47
	s_nop 0
	global_load_lds_dwordx4 v208, s[76:77]
	global_load_lds_dwordx4 v209, s[78:79] offset:1024
	global_load_lds_dwordx4 v208, s[80:81] offset:2048
	global_load_lds_dwordx4 v209, s[82:83] offset:3072
	v_add_u32_e32 v208, 0x80, v208
	v_add_u32_e32 v209, 0x80, v209
	ds_read_b128 v[132:135], v212 offset:0
	ds_read_b128 v[136:139], v212 offset:4096
	ds_read_b128 v[140:143], v216 offset:0
	ds_read_b128 v[144:147], v216 offset:4096
	ds_read_b128 v[148:151], v216 offset:16384
	ds_read_b128 v[158:161], v216 offset:20480
	s_waitcnt lgkmcnt(6)
	v_mfma_f32_32x32x16_bf16 v[4:19], v[172:175], v[162:165], v[4:19]
	v_mfma_f32_32x32x16_bf16 v[68:83], v[172:175], v[168:171], v[68:83]
	v_mfma_f32_32x32x16_bf16 v[20:35], v[176:179], v[162:165], v[20:35]
	v_mfma_f32_32x32x16_bf16 v[84:99], v[176:179], v[168:171], v[84:99]
	v_mfma_f32_32x32x16_bf16 v[36:51], v[180:183], v[162:165], v[36:51]
	v_mfma_f32_32x32x16_bf16 v[100:115], v[180:183], v[168:171], v[100:115]
	v_mfma_f32_32x32x16_bf16 v[52:67], v[184:187], v[162:165], v[52:67]
	v_mfma_f32_32x32x16_bf16 v[116:131], v[184:187], v[168:171], v[116:131]
	ds_read_b128 v[162:165], v213 offset:0
	ds_read_b128 v[168:171], v213 offset:4096
	ds_read_b128 v[172:175], v217 offset:0
	ds_read_b128 v[176:179], v217 offset:4096
	ds_read_b128 v[180:183], v217 offset:16384
	ds_read_b128 v[184:187], v217 offset:20480
	s_waitcnt lgkmcnt(6)
	v_mfma_f32_32x32x16_bf16 v[4:19], v[140:143], v[132:135], v[4:19]
	v_mfma_f32_32x32x16_bf16 v[68:83], v[140:143], v[136:139], v[68:83]
	v_mfma_f32_32x32x16_bf16 v[20:35], v[144:147], v[132:135], v[20:35]
	v_mfma_f32_32x32x16_bf16 v[84:99], v[144:147], v[136:139], v[84:99]
	v_mfma_f32_32x32x16_bf16 v[36:51], v[148:151], v[132:135], v[36:51]
	v_mfma_f32_32x32x16_bf16 v[100:115], v[148:151], v[136:139], v[100:115]
	v_mfma_f32_32x32x16_bf16 v[52:67], v[158:161], v[132:135], v[52:67]
	v_mfma_f32_32x32x16_bf16 v[116:131], v[158:161], v[136:139], v[116:131]
	s_waitcnt lgkmcnt(0)
	v_mfma_f32_32x32x16_bf16 v[4:19], v[172:175], v[162:165], v[4:19]
	v_mfma_f32_32x32x16_bf16 v[68:83], v[172:175], v[168:171], v[68:83]
	v_mfma_f32_32x32x16_bf16 v[20:35], v[176:179], v[162:165], v[20:35]
	v_mfma_f32_32x32x16_bf16 v[84:99], v[176:179], v[168:171], v[84:99]
	v_mfma_f32_32x32x16_bf16 v[36:51], v[180:183], v[162:165], v[36:51]
	v_mfma_f32_32x32x16_bf16 v[100:115], v[180:183], v[168:171], v[100:115]
	v_mfma_f32_32x32x16_bf16 v[52:67], v[184:187], v[162:165], v[52:67]
	v_mfma_f32_32x32x16_bf16 v[116:131], v[184:187], v[168:171], v[116:131]
	s_waitcnt vmcnt(0) lgkmcnt(0)
	s_barrier
; #define MFMA32(a, b, c) __builtin_amdgcn_mfma_f32_32x32x16_bf16((a), (b), (c), 0, 0, 0)
; template <bool SWAP, class Epi>
; DI void gemm_tile(const u16* __restrict__ A, int lda, const u16* __restrict__ Bw, int ldb, int K, char* lds, Epi epi) {
;     ...
;   auto compute = [&](int st) {
;     const char* as = lds + st * GEMM_STAGE;
;     const char* bs = as + 36864;
; #pragma unroll
;     for (int ks = 0; ks < 4; ++ks) {
;       bf16x8 af[2], bfr[2];
; #pragma unroll
;       for (int mi = 0; mi < 2; ++mi) af[mi] = *(const bf16x8*)(as + ((wm * 64 + mi * 32 + r) * 72 + ks * 16 + 8 * h) * 2);
; #pragma unroll
;       for (int ni = 0; ni < 2; ++ni) bfr[ni] = *(const bf16x8*)(bs + ((wn * 64 + ni * 32 + r) * 72 + ks * 16 + 8 * h) * 2);
; #pragma unroll
;       for (int mi = 0; mi < 2; ++mi)
; #pragma unroll
;         for (int ni = 0; ni < 2; ++ni) {
;           if (SWAP) acc[mi][ni] = MFMA32(bfr[ni], af[mi], acc[mi][ni]);
;           else acc[mi][ni] = MFMA32(af[mi], bfr[ni], acc[mi][ni]);
;         }
;     }
;   };
;   gload(0, ra0, rb0);
;   lstore(0, ra0, rb0);
;   gload(1, ra1, rb1);
;   __syncthreads();
;   for (int kt = 0; kt < nk; kt += 2) {
;     if (kt + 2 < nk) gload(kt + 2, ra0, rb0);
;     compute(0);
;     lstore(1, ra1, rb1);
;     __syncthreads();
;     if (kt + 3 < nk) gload(kt + 3, ra1, rb1);
;     compute(1);
;     if (kt + 2 < nk) lstore(0, ra0, rb0);
;     __syncthreads();
	ds_read_b128 v[132:135], v210 offset:32768
	ds_read_b128 v[136:139], v210 offset:36864
	ds_read_b128 v[140:143], v214 offset:32768
	ds_read_b128 v[144:147], v214 offset:36864
	ds_read_b128 v[148:151], v214 offset:49152
	ds_read_b128 v[158:161], v214 offset:53248
	s_mov_b32 m0, s44
	s_nop 0
	global_load_lds_dwordx4 v208, s[68:69]
	global_load_lds_dwordx4 v209, s[70:71] offset:1024
	global_load_lds_dwordx4 v208, s[72:73] offset:2048
	global_load_lds_dwordx4 v209, s[74:75] offset:3072
	ds_read_b128 v[162:165], v211 offset:32768
	ds_read_b128 v[168:171], v211 offset:36864
	ds_read_b128 v[172:175], v215 offset:32768
	ds_read_b128 v[176:179], v215 offset:36864
	ds_read_b128 v[180:183], v215 offset:49152
	ds_read_b128 v[184:187], v215 offset:53248
	s_waitcnt lgkmcnt(6)
	v_mfma_f32_32x32x16_bf16 v[4:19], v[140:143], v[132:135], v[4:19]
	v_mfma_f32_32x32x16_bf16 v[68:83], v[140:143], v[136:139], v[68:83]
	v_mfma_f32_32x32x16_bf16 v[20:35], v[144:147], v[132:135], v[20:35]
	v_mfma_f32_32x32x16_bf16 v[84:99], v[144:147], v[136:139], v[84:99]
	v_mfma_f32_32x32x16_bf16 v[36:51], v[148:151], v[132:135], v[36:51]
	v_mfma_f32_32x32x16_bf16 v[100:115], v[148:151], v[136:139], v[100:115]
	v_mfma_f32_32x32x16_bf16 v[52:67], v[158:161], v[132:135], v[52:67]
	v_mfma_f32_32x32x16_bf16 v[116:131], v[158:161], v[136:139], v[116:131]
	s_mov_b32 m0, s46
	s_nop 0
	global_load_lds_dwordx4 v208, s[76:77]
	global_load_lds_dwordx4 v209, s[78:79] offset:1024
	global_load_lds_dwordx4 v208, s[80:81] offset:2048
	global_load_lds_dwordx4 v209, s[82:83] offset:3072
	v_add_u32_e32 v208, 0x80, v208
	v_add_u32_e32 v209, 0x80, v209
	ds_read_b128 v[132:135], v212 offset:32768
	ds_read_b128 v[136:139], v212 offset:36864
	ds_read_b128 v[140:143], v216 offset:32768
	ds_read_b128 v[144:147], v216 offset:36864
	ds_read_b128 v[148:151], v216 offset:49152
	ds_read_b128 v[158:161], v216 offset:53248
	s_waitcnt lgkmcnt(6)
	v_mfma_f32_32x32x16_bf16 v[4:19], v[172:175], v[162:165], v[4:19]
	v_mfma_f32_32x32x16_bf16 v[68:83], v[172:175], v[168:171], v[68:83]
	v_mfma_f32_32x32x16_bf16 v[20:35], v[176:179], v[162:165], v[20:35]
	v_mfma_f32_32x32x16_bf16 v[84:99], v[176:179], v[168:171], v[84:99]
	v_mfma_f32_32x32x16_bf16 v[36:51], v[180:183], v[162:165], v[36:51]
	v_mfma_f32_32x32x16_bf16 v[100:115], v[180:183], v[168:171], v[100:115]
	v_mfma_f32_32x32x16_bf16 v[52:67], v[184:187], v[162:165], v[52:67]
	v_mfma_f32_32x32x16_bf16 v[116:131], v[184:187], v[168:171], v[116:131]
	ds_read_b128 v[162:165], v213 offset:32768
	ds_read_b128 v[168:171], v213 offset:36864
	ds_read_b128 v[172:175], v217 offset:32768
	ds_read_b128 v[176:179], v217 offset:36864
	ds_read_b128 v[180:183], v217 offset:49152
	ds_read_b128 v[184:187], v217 offset:53248
	s_waitcnt lgkmcnt(6)
	v_mfma_f32_32x32x16_bf16 v[4:19], v[140:143], v[132:135], v[4:19]
	v_mfma_f32_32x32x16_bf16 v[68:83], v[140:143], v[136:139], v[68:83]
	v_mfma_f32_32x32x16_bf16 v[20:35], v[144:147], v[132:135], v[20:35]
	v_mfma_f32_32x32x16_bf16 v[84:99], v[144:147], v[136:139], v[84:99]
	v_mfma_f32_32x32x16_bf16 v[36:51], v[148:151], v[132:135], v[36:51]
	v_mfma_f32_32x32x16_bf16 v[100:115], v[148:151], v[136:139], v[100:115]
	v_mfma_f32_32x32x16_bf16 v[52:67], v[158:161], v[132:135], v[52:67]
	v_mfma_f32_32x32x16_bf16 v[116:131], v[158:161], v[136:139], v[116:131]
	s_waitcnt lgkmcnt(0)
	v_mfma_f32_32x32x16_bf16 v[4:19], v[172:175], v[162:165], v[4:19]
	v_mfma_f32_32x32x16_bf16 v[68:83], v[172:175], v[168:171], v[68:83]
	v_mfma_f32_32x32x16_bf16 v[20:35], v[176:179], v[162:165], v[20:35]
	v_mfma_f32_32x32x16_bf16 v[84:99], v[176:179], v[168:171], v[84:99]
	v_mfma_f32_32x32x16_bf16 v[36:51], v[180:183], v[162:165], v[36:51]
	v_mfma_f32_32x32x16_bf16 v[100:115], v[180:183], v[168:171], v[100:115]
	v_mfma_f32_32x32x16_bf16 v[52:67], v[184:187], v[162:165], v[52:67]
	v_mfma_f32_32x32x16_bf16 v[116:131], v[184:187], v[168:171], v[116:131]
	s_waitcnt vmcnt(0) lgkmcnt(0)
	s_barrier
	ds_read_b128 v[132:135], v210 offset:0
	ds_read_b128 v[136:139], v210 offset:4096
	ds_read_b128 v[140:143], v214 offset:0
	ds_read_b128 v[144:147], v214 offset:4096
	ds_read_b128 v[148:151], v214 offset:16384
	ds_read_b128 v[158:161], v214 offset:20480
	s_mov_b32 m0, s45
	s_nop 0
	global_load_lds_dwordx4 v208, s[68:69]
	global_load_lds_dwordx4 v209, s[70:71] offset:1024
	global_load_lds_dwordx4 v208, s[72:73] offset:2048
	global_load_lds_dwordx4 v209, s[74:75] offset:3072
	ds_read_b128 v[162:165], v211 offset:0
	ds_read_b128 v[168:171], v211 offset:4096
	ds_read_b128 v[172:175], v215 offset:0
	ds_read_b128 v[176:179], v215 offset:4096
	ds_read_b128 v[180:183], v215 offset:16384
	ds_read_b128 v[184:187], v215 offset:20480
	s_waitcnt lgkmcnt(6)
	v_mfma_f32_32x32x16_bf16 v[4:19], v[140:143], v[132:135], v[4:19]
	v_mfma_f32_32x32x16_bf16 v[68:83], v[140:143], v[136:139], v[68:83]
	v_mfma_f32_32x32x16_bf16 v[20:35], v[144:147], v[132:135], v[20:35]
	v_mfma_f32_32x32x16_bf16 v[84:99], v[144:147], v[136:139], v[84:99]
	v_mfma_f32_32x32x16_bf16 v[36:51], v[148:151], v[132:135], v[36:51]
	v_mfma_f32_32x32x16_bf16 v[100:115], v[148:151], v[136:139], v[100:115]
	v_mfma_f32_32x32x16_bf16 v[52:67], v[158:161], v[132:135], v[52:67]
	v_mfma_f32_32x32x16_bf16 v[116:131], v[158:161], v[136:139], v[116:131]
	s_mov_b32 m0, s47
	s_nop 0
	global_load_lds_dwordx4 v208, s[76:77]
	global_load_lds_dwordx4 v209, s[78:79] offset:1024
	global_load_lds_dwordx4 v208, s[80:81] offset:2048
	global_load_lds_dwordx4 v209, s[82:83] offset:3072
	v_add_u32_e32 v208, 0x80, v208
	v_add_u32_e32 v209, 0x80, v209
	ds_read_b128 v[132:135], v212 offset:0
	ds_read_b128 v[136:139], v212 offset:4096
	ds_read_b128 v[140:143], v216 offset:0
	ds_read_b128 v[144:147], v216 offset:4096
	ds_read_b128 v[148:151], v216 offset:16384
	ds_read_b128 v[158:161], v216 offset:20480
	s_waitcnt lgkmcnt(6)
; #define MFMA32(a, b, c) __builtin_amdgcn_mfma_f32_32x32x16_bf16((a), (b), (c), 0, 0, 0)
; template <bool SWAP, class Epi>
; DI void gemm_tile(const u16* __restrict__ A, int lda, const u16* __restrict__ Bw, int ldb, int K, char* lds, Epi epi) {
;     ...
;   auto compute = [&](int st) {
;     const char* as = lds + st * GEMM_STAGE;
;     const char* bs = as + 36864;
; #pragma unroll
;     for (int ks = 0; ks < 4; ++ks) {
;       bf16x8 af[2], bfr[2];
; #pragma unroll
;       for (int mi = 0; mi < 2; ++mi) af[mi] = *(const bf16x8*)(as + ((wm * 64 + mi * 32 + r) * 72 + ks * 16 + 8 * h) * 2);
; #pragma unroll
;       for (int ni = 0; ni < 2; ++ni) bfr[ni] = *(const bf16x8*)(bs + ((wn * 64 + ni * 32 + r) * 72 + ks * 16 + 8 * h) * 2);
; #pragma unroll
;       for (int mi = 0; mi < 2; ++mi)
; #pragma unroll
;         for (int ni = 0; ni < 2; ++ni) {
;           if (SWAP) acc[mi][ni] = MFMA32(bfr[ni], af[mi], acc[mi][ni]);
;           else acc[mi][ni] = MFMA32(af[mi], bfr[ni], acc[mi][ni]);
;         }
;     }
;   };
;   gload(0, ra0, rb0);
;   lstore(0, ra0, rb0);
;   gload(1, ra1, rb1);
;   __syncthreads();
;   for (int kt = 0; kt < nk; kt += 2) {
;     if (kt + 2 < nk) gload(kt + 2, ra0, rb0);
;     compute(0);
;     lstore(1, ra1, rb1);
;     __syncthreads();
;     if (kt + 3 < nk) gload(kt + 3, ra1, rb1);
;     compute(1);
;     if (kt + 2 < nk) lstore(0, ra0, rb0);
;     __syncthreads();
	v_mfma_f32_32x32x16_bf16 v[4:19], v[172:175], v[162:165], v[4:19]
	v_mfma_f32_32x32x16_bf16 v[68:83], v[172:175], v[168:171], v[68:83]
	v_mfma_f32_32x32x16_bf16 v[20:35], v[176:179], v[162:165], v[20:35]
	v_mfma_f32_32x32x16_bf16 v[84:99], v[176:179], v[168:171], v[84:99]
	v_mfma_f32_32x32x16_bf16 v[36:51], v[180:183], v[162:165], v[36:51]
	v_mfma_f32_32x32x16_bf16 v[100:115], v[180:183], v[168:171], v[100:115]
	v_mfma_f32_32x32x16_bf16 v[52:67], v[184:187], v[162:165], v[52:67]
	v_mfma_f32_32x32x16_bf16 v[116:131], v[184:187], v[168:171], v[116:131]
	ds_read_b128 v[162:165], v213 offset:0
	ds_read_b128 v[168:171], v213 offset:4096
	ds_read_b128 v[172:175], v217 offset:0
	ds_read_b128 v[176:179], v217 offset:4096
	ds_read_b128 v[180:183], v217 offset:16384
	ds_read_b128 v[184:187], v217 offset:20480
	s_waitcnt lgkmcnt(6)
	v_mfma_f32_32x32x16_bf16 v[4:19], v[140:143], v[132:135], v[4:19]
	v_mfma_f32_32x32x16_bf16 v[68:83], v[140:143], v[136:139], v[68:83]
	v_mfma_f32_32x32x16_bf16 v[20:35], v[144:147], v[132:135], v[20:35]
	v_mfma_f32_32x32x16_bf16 v[84:99], v[144:147], v[136:139], v[84:99]
	v_mfma_f32_32x32x16_bf16 v[36:51], v[148:151], v[132:135], v[36:51]
	v_mfma_f32_32x32x16_bf16 v[100:115], v[148:151], v[136:139], v[100:115]
	v_mfma_f32_32x32x16_bf16 v[52:67], v[158:161], v[132:135], v[52:67]
	v_mfma_f32_32x32x16_bf16 v[116:131], v[158:161], v[136:139], v[116:131]
	s_waitcnt lgkmcnt(0)
	v_mfma_f32_32x32x16_bf16 v[4:19], v[172:175], v[162:165], v[4:19]
	v_mfma_f32_32x32x16_bf16 v[68:83], v[172:175], v[168:171], v[68:83]
	v_mfma_f32_32x32x16_bf16 v[20:35], v[176:179], v[162:165], v[20:35]
	v_mfma_f32_32x32x16_bf16 v[84:99], v[176:179], v[168:171], v[84:99]
	v_mfma_f32_32x32x16_bf16 v[36:51], v[180:183], v[162:165], v[36:51]
	v_mfma_f32_32x32x16_bf16 v[100:115], v[180:183], v[168:171], v[100:115]
	v_mfma_f32_32x32x16_bf16 v[52:67], v[184:187], v[162:165], v[52:67]
	v_mfma_f32_32x32x16_bf16 v[116:131], v[184:187], v[168:171], v[116:131]
	s_waitcnt vmcnt(0) lgkmcnt(0)
	s_barrier
	ds_read_b128 v[132:135], v210 offset:32768
	ds_read_b128 v[136:139], v210 offset:36864
	ds_read_b128 v[140:143], v214 offset:32768
	ds_read_b128 v[144:147], v214 offset:36864
	ds_read_b128 v[148:151], v214 offset:49152
	ds_read_b128 v[158:161], v214 offset:53248
	s_mov_b32 m0, s44
	s_nop 0
	global_load_lds_dwordx4 v208, s[68:69]
	global_load_lds_dwordx4 v209, s[70:71] offset:1024
	global_load_lds_dwordx4 v208, s[72:73] offset:2048
	global_load_lds_dwordx4 v209, s[74:75] offset:3072
	ds_read_b128 v[162:165], v211 offset:32768
	ds_read_b128 v[168:171], v211 offset:36864
	ds_read_b128 v[172:175], v215 offset:32768
	ds_read_b128 v[176:179], v215 offset:36864
	ds_read_b128 v[180:183], v215 offset:49152
	ds_read_b128 v[184:187], v215 offset:53248
	s_waitcnt lgkmcnt(6)
	v_mfma_f32_32x32x16_bf16 v[4:19], v[140:143], v[132:135], v[4:19]
	v_mfma_f32_32x32x16_bf16 v[68:83], v[140:143], v[136:139], v[68:83]
	v_mfma_f32_32x32x16_bf16 v[20:35], v[144:147], v[132:135], v[20:35]
	v_mfma_f32_32x32x16_bf16 v[84:99], v[144:147], v[136:139], v[84:99]
	v_mfma_f32_32x32x16_bf16 v[36:51], v[148:151], v[132:135], v[36:51]
	v_mfma_f32_32x32x16_bf16 v[100:115], v[148:151], v[136:139], v[100:115]
	v_mfma_f32_32x32x16_bf16 v[52:67], v[158:161], v[132:135], v[52:67]
	v_mfma_f32_32x32x16_bf16 v[116:131], v[158:161], v[136:139], v[116:131]
	s_mov_b32 m0, s46
	s_nop 0
	global_load_lds_dwordx4 v208, s[76:77]
	global_load_lds_dwordx4 v209, s[78:79] offset:1024
	global_load_lds_dwordx4 v208, s[80:81] offset:2048
	global_load_lds_dwordx4 v209, s[82:83] offset:3072
	v_add_u32_e32 v208, 0x80, v208
	v_add_u32_e32 v209, 0x80, v209
	ds_read_b128 v[132:135], v212 offset:32768
	ds_read_b128 v[136:139], v212 offset:36864
	ds_read_b128 v[140:143], v216 offset:32768
	ds_read_b128 v[144:147], v216 offset:36864
	ds_read_b128 v[148:151], v216 offset:49152
	ds_read_b128 v[158:161], v216 offset:53248
	s_waitcnt lgkmcnt(6)
	v_mfma_f32_32x32x16_bf16 v[4:19], v[172:175], v[162:165], v[4:19]
	v_mfma_f32_32x32x16_bf16 v[68:83], v[172:175], v[168:171], v[68:83]
	v_mfma_f32_32x32x16_bf16 v[20:35], v[176:179], v[162:165], v[20:35]
	v_mfma_f32_32x32x16_bf16 v[84:99], v[176:179], v[168:171], v[84:99]
	v_mfma_f32_32x32x16_bf16 v[36:51], v[180:183], v[162:165], v[36:51]
	v_mfma_f32_32x32x16_bf16 v[100:115], v[180:183], v[168:171], v[100:115]
	v_mfma_f32_32x32x16_bf16 v[52:67], v[184:187], v[162:165], v[52:67]
	v_mfma_f32_32x32x16_bf16 v[116:131], v[184:187], v[168:171], v[116:131]
	ds_read_b128 v[162:165], v213 offset:32768
	ds_read_b128 v[168:171], v213 offset:36864
	ds_read_b128 v[172:175], v217 offset:32768
	ds_read_b128 v[176:179], v217 offset:36864
	ds_read_b128 v[180:183], v217 offset:49152
	ds_read_b128 v[184:187], v217 offset:53248
	s_waitcnt lgkmcnt(6)
	v_mfma_f32_32x32x16_bf16 v[4:19], v[140:143], v[132:135], v[4:19]
	v_mfma_f32_32x32x16_bf16 v[68:83], v[140:143], v[136:139], v[68:83]
	v_mfma_f32_32x32x16_bf16 v[20:35], v[144:147], v[132:135], v[20:35]
	v_mfma_f32_32x32x16_bf16 v[84:99], v[144:147], v[136:139], v[84:99]
	v_mfma_f32_32x32x16_bf16 v[36:51], v[148:151], v[132:135], v[36:51]
	v_mfma_f32_32x32x16_bf16 v[100:115], v[148:151], v[136:139], v[100:115]
	v_mfma_f32_32x32x16_bf16 v[52:67], v[158:161], v[132:135], v[52:67]
	v_mfma_f32_32x32x16_bf16 v[116:131], v[158:161], v[136:139], v[116:131]
	s_waitcnt lgkmcnt(0)
	v_mfma_f32_32x32x16_bf16 v[4:19], v[172:175], v[162:165], v[4:19]
	v_mfma_f32_32x32x16_bf16 v[68:83], v[172:175], v[168:171], v[68:83]
	v_mfma_f32_32x32x16_bf16 v[20:35], v[176:179], v[162:165], v[20:35]
	v_mfma_f32_32x32x16_bf16 v[84:99], v[176:179], v[168:171], v[84:99]
	v_mfma_f32_32x32x16_bf16 v[36:51], v[180:183], v[162:165], v[36:51]
	v_mfma_f32_32x32x16_bf16 v[100:115], v[180:183], v[168:171], v[100:115]
	v_mfma_f32_32x32x16_bf16 v[52:67], v[184:187], v[162:165], v[52:67]
	v_mfma_f32_32x32x16_bf16 v[116:131], v[184:187], v[168:171], v[116:131]
	s_waitcnt vmcnt(0) lgkmcnt(0)
	s_barrier
; #define MFMA32(a, b, c) __builtin_amdgcn_mfma_f32_32x32x16_bf16((a), (b), (c), 0, 0, 0)
; template <bool SWAP, class Epi>
; DI void gemm_tile(const u16* __restrict__ A, int lda, const u16* __restrict__ Bw, int ldb, int K, char* lds, Epi epi) {
;     ...
;   auto compute = [&](int st) {
;     const char* as = lds + st * GEMM_STAGE;
;     const char* bs = as + 36864;
; #pragma unroll
;     for (int ks = 0; ks < 4; ++ks) {
;       bf16x8 af[2], bfr[2];
; #pragma unroll
;       for (int mi = 0; mi < 2; ++mi) af[mi] = *(const bf16x8*)(as + ((wm * 64 + mi * 32 + r) * 72 + ks * 16 + 8 * h) * 2);
; #pragma unroll
;       for (int ni = 0; ni < 2; ++ni) bfr[ni] = *(const bf16x8*)(bs + ((wn * 64 + ni * 32 + r) * 72 + ks * 16 + 8 * h) * 2);
; #pragma unroll
;       for (int mi = 0; mi < 2; ++mi)
; #pragma unroll
;         for (int ni = 0; ni < 2; ++ni) {
;           if (SWAP) acc[mi][ni] = MFMA32(bfr[ni], af[mi], acc[mi][ni]);
;           else acc[mi][ni] = MFMA32(af[mi], bfr[ni], acc[mi][ni]);
;         }
;     }
;   };
;   gload(0, ra0, rb0);
;   lstore(0, ra0, rb0);
;   gload(1, ra1, rb1);
;   __syncthreads();
;   for (int kt = 0; kt < nk; kt += 2) {
;     if (kt + 2 < nk) gload(kt + 2, ra0, rb0);
;     compute(0);
;     lstore(1, ra1, rb1);
;     __syncthreads();
;     if (kt + 3 < nk) gload(kt + 3, ra1, rb1);
;     compute(1);
;     if (kt + 2 < nk) lstore(0, ra0, rb0);
;     __syncthreads();
	ds_read_b128 v[132:135], v210 offset:0
	ds_read_b128 v[136:139], v210 offset:4096
	ds_read_b128 v[140:143], v214 offset:0
	ds_read_b128 v[144:147], v214 offset:4096
	ds_read_b128 v[148:151], v214 offset:16384
	ds_read_b128 v[158:161], v214 offset:20480
	s_mov_b32 m0, s45
	s_nop 0
	global_load_lds_dwordx4 v208, s[68:69]
	global_load_lds_dwordx4 v209, s[70:71] offset:1024
	global_load_lds_dwordx4 v208, s[72:73] offset:2048
	global_load_lds_dwordx4 v209, s[74:75] offset:3072
	ds_read_b128 v[162:165], v211 offset:0
	ds_read_b128 v[168:171], v211 offset:4096
	ds_read_b128 v[172:175], v215 offset:0
	ds_read_b128 v[176:179], v215 offset:4096
	ds_read_b128 v[180:183], v215 offset:16384
	ds_read_b128 v[184:187], v215 offset:20480
	s_waitcnt lgkmcnt(6)
	v_mfma_f32_32x32x16_bf16 v[4:19], v[140:143], v[132:135], v[4:19]
	v_mfma_f32_32x32x16_bf16 v[68:83], v[140:143], v[136:139], v[68:83]
	v_mfma_f32_32x32x16_bf16 v[20:35], v[144:147], v[132:135], v[20:35]
	v_mfma_f32_32x32x16_bf16 v[84:99], v[144:147], v[136:139], v[84:99]
	v_mfma_f32_32x32x16_bf16 v[36:51], v[148:151], v[132:135], v[36:51]
	v_mfma_f32_32x32x16_bf16 v[100:115], v[148:151], v[136:139], v[100:115]
	v_mfma_f32_32x32x16_bf16 v[52:67], v[158:161], v[132:135], v[52:67]
	v_mfma_f32_32x32x16_bf16 v[116:131], v[158:161], v[136:139], v[116:131]
	s_mov_b32 m0, s47
	s_nop 0
	global_load_lds_dwordx4 v208, s[76:77]
	global_load_lds_dwordx4 v209, s[78:79] offset:1024
	global_load_lds_dwordx4 v208, s[80:81] offset:2048
	global_load_lds_dwordx4 v209, s[82:83] offset:3072
	v_add_u32_e32 v208, 0x80, v208
	v_add_u32_e32 v209, 0x80, v209
	ds_read_b128 v[132:135], v212 offset:0
	ds_read_b128 v[136:139], v212 offset:4096
	ds_read_b128 v[140:143], v216 offset:0
	ds_read_b128 v[144:147], v216 offset:4096
	ds_read_b128 v[148:151], v216 offset:16384
	ds_read_b128 v[158:161], v216 offset:20480
	s_waitcnt lgkmcnt(6)
	v_mfma_f32_32x32x16_bf16 v[4:19], v[172:175], v[162:165], v[4:19]
	v_mfma_f32_32x32x16_bf16 v[68:83], v[172:175], v[168:171], v[68:83]
	v_mfma_f32_32x32x16_bf16 v[20:35], v[176:179], v[162:165], v[20:35]
	v_mfma_f32_32x32x16_bf16 v[84:99], v[176:179], v[168:171], v[84:99]
	v_mfma_f32_32x32x16_bf16 v[36:51], v[180:183], v[162:165], v[36:51]
	v_mfma_f32_32x32x16_bf16 v[100:115], v[180:183], v[168:171], v[100:115]
	v_mfma_f32_32x32x16_bf16 v[52:67], v[184:187], v[162:165], v[52:67]
	v_mfma_f32_32x32x16_bf16 v[116:131], v[184:187], v[168:171], v[116:131]
	ds_read_b128 v[162:165], v213 offset:0
	ds_read_b128 v[168:171], v213 offset:4096
	ds_read_b128 v[172:175], v217 offset:0
	ds_read_b128 v[176:179], v217 offset:4096
	ds_read_b128 v[180:183], v217 offset:16384
	ds_read_b128 v[184:187], v217 offset:20480
	s_waitcnt lgkmcnt(6)
	v_mfma_f32_32x32x16_bf16 v[4:19], v[140:143], v[132:135], v[4:19]
	v_mfma_f32_32x32x16_bf16 v[68:83], v[140:143], v[136:139], v[68:83]
	v_mfma_f32_32x32x16_bf16 v[20:35], v[144:147], v[132:135], v[20:35]
	v_mfma_f32_32x32x16_bf16 v[84:99], v[144:147], v[136:139], v[84:99]
	v_mfma_f32_32x32x16_bf16 v[36:51], v[148:151], v[132:135], v[36:51]
	v_mfma_f32_32x32x16_bf16 v[100:115], v[148:151], v[136:139], v[100:115]
	v_mfma_f32_32x32x16_bf16 v[52:67], v[158:161], v[132:135], v[52:67]
	v_mfma_f32_32x32x16_bf16 v[116:131], v[158:161], v[136:139], v[116:131]
	s_waitcnt lgkmcnt(0)
	v_mfma_f32_32x32x16_bf16 v[4:19], v[172:175], v[162:165], v[4:19]
	v_mfma_f32_32x32x16_bf16 v[68:83], v[172:175], v[168:171], v[68:83]
	v_mfma_f32_32x32x16_bf16 v[20:35], v[176:179], v[162:165], v[20:35]
	v_mfma_f32_32x32x16_bf16 v[84:99], v[176:179], v[168:171], v[84:99]
	v_mfma_f32_32x32x16_bf16 v[36:51], v[180:183], v[162:165], v[36:51]
	v_mfma_f32_32x32x16_bf16 v[100:115], v[180:183], v[168:171], v[100:115]
	v_mfma_f32_32x32x16_bf16 v[52:67], v[184:187], v[162:165], v[52:67]
	v_mfma_f32_32x32x16_bf16 v[116:131], v[184:187], v[168:171], v[116:131]
	s_waitcnt vmcnt(0) lgkmcnt(0)
	s_barrier
	ds_read_b128 v[132:135], v210 offset:32768
	ds_read_b128 v[136:139], v210 offset:36864
	ds_read_b128 v[140:143], v214 offset:32768
	ds_read_b128 v[144:147], v214 offset:36864
	ds_read_b128 v[148:151], v214 offset:49152
	ds_read_b128 v[158:161], v214 offset:53248
	s_mov_b32 m0, s44
	s_nop 0
	global_load_lds_dwordx4 v208, s[68:69]
	global_load_lds_dwordx4 v209, s[70:71] offset:1024
	global_load_lds_dwordx4 v208, s[72:73] offset:2048
	global_load_lds_dwordx4 v209, s[74:75] offset:3072
	ds_read_b128 v[162:165], v211 offset:32768
	ds_read_b128 v[168:171], v211 offset:36864
	ds_read_b128 v[172:175], v215 offset:32768
	ds_read_b128 v[176:179], v215 offset:36864
	ds_read_b128 v[180:183], v215 offset:49152
	ds_read_b128 v[184:187], v215 offset:53248
	s_waitcnt lgkmcnt(6)
	v_mfma_f32_32x32x16_bf16 v[4:19], v[140:143], v[132:135], v[4:19]
	v_mfma_f32_32x32x16_bf16 v[68:83], v[140:143], v[136:139], v[68:83]
	v_mfma_f32_32x32x16_bf16 v[20:35], v[144:147], v[132:135], v[20:35]
	v_mfma_f32_32x32x16_bf16 v[84:99], v[144:147], v[136:139], v[84:99]
	v_mfma_f32_32x32x16_bf16 v[36:51], v[148:151], v[132:135], v[36:51]
	v_mfma_f32_32x32x16_bf16 v[100:115], v[148:151], v[136:139], v[100:115]
	v_mfma_f32_32x32x16_bf16 v[52:67], v[158:161], v[132:135], v[52:67]
	v_mfma_f32_32x32x16_bf16 v[116:131], v[158:161], v[136:139], v[116:131]
	s_mov_b32 m0, s46
	s_nop 0
	global_load_lds_dwordx4 v208, s[76:77]
	global_load_lds_dwordx4 v209, s[78:79] offset:1024
	global_load_lds_dwordx4 v208, s[80:81] offset:2048
	global_load_lds_dwordx4 v209, s[82:83] offset:3072
	v_add_u32_e32 v208, 0x80, v208
	v_add_u32_e32 v209, 0x80, v209
	ds_read_b128 v[132:135], v212 offset:32768
	ds_read_b128 v[136:139], v212 offset:36864
	ds_read_b128 v[140:143], v216 offset:32768
	ds_read_b128 v[144:147], v216 offset:36864
	ds_read_b128 v[148:151], v216 offset:49152
	ds_read_b128 v[158:161], v216 offset:53248
	s_waitcnt lgkmcnt(6)
; #define MFMA32(a, b, c) __builtin_amdgcn_mfma_f32_32x32x16_bf16((a), (b), (c), 0, 0, 0)
; template <bool SWAP, class Epi>
; DI void gemm_tile(const u16* __restrict__ A, int lda, const u16* __restrict__ Bw, int ldb, int K, char* lds, Epi epi) {
;     ...
;   auto compute = [&](int st) {
;     const char* as = lds + st * GEMM_STAGE;
;     const char* bs = as + 36864;
; #pragma unroll
;     for (int ks = 0; ks < 4; ++ks) {
;       bf16x8 af[2], bfr[2];
; #pragma unroll
;       for (int mi = 0; mi < 2; ++mi) af[mi] = *(const bf16x8*)(as + ((wm * 64 + mi * 32 + r) * 72 + ks * 16 + 8 * h) * 2);
; #pragma unroll
;       for (int ni = 0; ni < 2; ++ni) bfr[ni] = *(const bf16x8*)(bs + ((wn * 64 + ni * 32 + r) * 72 + ks * 16 + 8 * h) * 2);
; #pragma unroll
;       for (int mi = 0; mi < 2; ++mi)
; #pragma unroll
;         for (int ni = 0; ni < 2; ++ni) {
;           if (SWAP) acc[mi][ni] = MFMA32(bfr[ni], af[mi], acc[mi][ni]);
;           else acc[mi][ni] = MFMA32(af[mi], bfr[ni], acc[mi][ni]);
;         }
;     }
;   };
;   gload(0, ra0, rb0);
;   lstore(0, ra0, rb0);
;   gload(1, ra1, rb1);
;   __syncthreads();
;   for (int kt = 0; kt < nk; kt += 2) {
;     if (kt + 2 < nk) gload(kt + 2, ra0, rb0);
;     compute(0);
;     lstore(1, ra1, rb1);
;     __syncthreads();
;     if (kt + 3 < nk) gload(kt + 3, ra1, rb1);
;     compute(1);
;     if (kt + 2 < nk) lstore(0, ra0, rb0);
;     __syncthreads();
	v_mfma_f32_32x32x16_bf16 v[4:19], v[172:175], v[162:165], v[4:19]
	v_mfma_f32_32x32x16_bf16 v[68:83], v[172:175], v[168:171], v[68:83]
	v_mfma_f32_32x32x16_bf16 v[20:35], v[176:179], v[162:165], v[20:35]
	v_mfma_f32_32x32x16_bf16 v[84:99], v[176:179], v[168:171], v[84:99]
	v_mfma_f32_32x32x16_bf16 v[36:51], v[180:183], v[162:165], v[36:51]
	v_mfma_f32_32x32x16_bf16 v[100:115], v[180:183], v[168:171], v[100:115]
	v_mfma_f32_32x32x16_bf16 v[52:67], v[184:187], v[162:165], v[52:67]
	v_mfma_f32_32x32x16_bf16 v[116:131], v[184:187], v[168:171], v[116:131]
	ds_read_b128 v[162:165], v213 offset:32768
	ds_read_b128 v[168:171], v213 offset:36864
	ds_read_b128 v[172:175], v217 offset:32768
	ds_read_b128 v[176:179], v217 offset:36864
	ds_read_b128 v[180:183], v217 offset:49152
	ds_read_b128 v[184:187], v217 offset:53248
	s_waitcnt lgkmcnt(6)
	v_mfma_f32_32x32x16_bf16 v[4:19], v[140:143], v[132:135], v[4:19]
	v_mfma_f32_32x32x16_bf16 v[68:83], v[140:143], v[136:139], v[68:83]
	v_mfma_f32_32x32x16_bf16 v[20:35], v[144:147], v[132:135], v[20:35]
	v_mfma_f32_32x32x16_bf16 v[84:99], v[144:147], v[136:139], v[84:99]
	v_mfma_f32_32x32x16_bf16 v[36:51], v[148:151], v[132:135], v[36:51]
	v_mfma_f32_32x32x16_bf16 v[100:115], v[148:151], v[136:139], v[100:115]
	v_mfma_f32_32x32x16_bf16 v[52:67], v[158:161], v[132:135], v[52:67]
	v_mfma_f32_32x32x16_bf16 v[116:131], v[158:161], v[136:139], v[116:131]
	s_waitcnt lgkmcnt(0)
	v_mfma_f32_32x32x16_bf16 v[4:19], v[172:175], v[162:165], v[4:19]
	v_mfma_f32_32x32x16_bf16 v[68:83], v[172:175], v[168:171], v[68:83]
	v_mfma_f32_32x32x16_bf16 v[20:35], v[176:179], v[162:165], v[20:35]
	v_mfma_f32_32x32x16_bf16 v[84:99], v[176:179], v[168:171], v[84:99]
	v_mfma_f32_32x32x16_bf16 v[36:51], v[180:183], v[162:165], v[36:51]
	v_mfma_f32_32x32x16_bf16 v[100:115], v[180:183], v[168:171], v[100:115]
	v_mfma_f32_32x32x16_bf16 v[52:67], v[184:187], v[162:165], v[52:67]
	v_mfma_f32_32x32x16_bf16 v[116:131], v[184:187], v[168:171], v[116:131]
	s_waitcnt vmcnt(0) lgkmcnt(0)
	s_barrier
	ds_read_b128 v[132:135], v210 offset:0
	ds_read_b128 v[136:139], v210 offset:4096
	ds_read_b128 v[140:143], v214 offset:0
	ds_read_b128 v[144:147], v214 offset:4096
	ds_read_b128 v[148:151], v214 offset:16384
	ds_read_b128 v[158:161], v214 offset:20480
	s_mov_b32 m0, s45
	s_nop 0
	global_load_lds_dwordx4 v208, s[68:69]
	global_load_lds_dwordx4 v209, s[70:71] offset:1024
	global_load_lds_dwordx4 v208, s[72:73] offset:2048
	global_load_lds_dwordx4 v209, s[74:75] offset:3072
	ds_read_b128 v[162:165], v211 offset:0
	ds_read_b128 v[168:171], v211 offset:4096
	ds_read_b128 v[172:175], v215 offset:0
	ds_read_b128 v[176:179], v215 offset:4096
	ds_read_b128 v[180:183], v215 offset:16384
	ds_read_b128 v[184:187], v215 offset:20480
	s_waitcnt lgkmcnt(6)
	v_mfma_f32_32x32x16_bf16 v[4:19], v[140:143], v[132:135], v[4:19]
	v_mfma_f32_32x32x16_bf16 v[68:83], v[140:143], v[136:139], v[68:83]
	v_mfma_f32_32x32x16_bf16 v[20:35], v[144:147], v[132:135], v[20:35]
	v_mfma_f32_32x32x16_bf16 v[84:99], v[144:147], v[136:139], v[84:99]
	v_mfma_f32_32x32x16_bf16 v[36:51], v[148:151], v[132:135], v[36:51]
	v_mfma_f32_32x32x16_bf16 v[100:115], v[148:151], v[136:139], v[100:115]
	v_mfma_f32_32x32x16_bf16 v[52:67], v[158:161], v[132:135], v[52:67]
	v_mfma_f32_32x32x16_bf16 v[116:131], v[158:161], v[136:139], v[116:131]
	s_mov_b32 m0, s47
	s_nop 0
	global_load_lds_dwordx4 v208, s[76:77]
	global_load_lds_dwordx4 v209, s[78:79] offset:1024
	global_load_lds_dwordx4 v208, s[80:81] offset:2048
	global_load_lds_dwordx4 v209, s[82:83] offset:3072
	v_add_u32_e32 v208, 0x80, v208
	v_add_u32_e32 v209, 0x80, v209
	ds_read_b128 v[132:135], v212 offset:0
	ds_read_b128 v[136:139], v212 offset:4096
	ds_read_b128 v[140:143], v216 offset:0
	ds_read_b128 v[144:147], v216 offset:4096
	ds_read_b128 v[148:151], v216 offset:16384
	ds_read_b128 v[158:161], v216 offset:20480
	s_waitcnt lgkmcnt(6)
	v_mfma_f32_32x32x16_bf16 v[4:19], v[172:175], v[162:165], v[4:19]
	v_mfma_f32_32x32x16_bf16 v[68:83], v[172:175], v[168:171], v[68:83]
	v_mfma_f32_32x32x16_bf16 v[20:35], v[176:179], v[162:165], v[20:35]
	v_mfma_f32_32x32x16_bf16 v[84:99], v[176:179], v[168:171], v[84:99]
	v_mfma_f32_32x32x16_bf16 v[36:51], v[180:183], v[162:165], v[36:51]
	v_mfma_f32_32x32x16_bf16 v[100:115], v[180:183], v[168:171], v[100:115]
	v_mfma_f32_32x32x16_bf16 v[52:67], v[184:187], v[162:165], v[52:67]
	v_mfma_f32_32x32x16_bf16 v[116:131], v[184:187], v[168:171], v[116:131]
	ds_read_b128 v[162:165], v213 offset:0
	ds_read_b128 v[168:171], v213 offset:4096
	ds_read_b128 v[172:175], v217 offset:0
	ds_read_b128 v[176:179], v217 offset:4096
	ds_read_b128 v[180:183], v217 offset:16384
	ds_read_b128 v[184:187], v217 offset:20480
	s_waitcnt lgkmcnt(6)
	v_mfma_f32_32x32x16_bf16 v[4:19], v[140:143], v[132:135], v[4:19]
	v_mfma_f32_32x32x16_bf16 v[68:83], v[140:143], v[136:139], v[68:83]
	v_mfma_f32_32x32x16_bf16 v[20:35], v[144:147], v[132:135], v[20:35]
	v_mfma_f32_32x32x16_bf16 v[84:99], v[144:147], v[136:139], v[84:99]
	v_mfma_f32_32x32x16_bf16 v[36:51], v[148:151], v[132:135], v[36:51]
	v_mfma_f32_32x32x16_bf16 v[100:115], v[148:151], v[136:139], v[100:115]
	v_mfma_f32_32x32x16_bf16 v[52:67], v[158:161], v[132:135], v[52:67]
	v_mfma_f32_32x32x16_bf16 v[116:131], v[158:161], v[136:139], v[116:131]
	s_waitcnt lgkmcnt(0)
	v_mfma_f32_32x32x16_bf16 v[4:19], v[172:175], v[162:165], v[4:19]
	v_mfma_f32_32x32x16_bf16 v[68:83], v[172:175], v[168:171], v[68:83]
	v_mfma_f32_32x32x16_bf16 v[20:35], v[176:179], v[162:165], v[20:35]
	v_mfma_f32_32x32x16_bf16 v[84:99], v[176:179], v[168:171], v[84:99]
	v_mfma_f32_32x32x16_bf16 v[36:51], v[180:183], v[162:165], v[36:51]
	v_mfma_f32_32x32x16_bf16 v[100:115], v[180:183], v[168:171], v[100:115]
	v_mfma_f32_32x32x16_bf16 v[52:67], v[184:187], v[162:165], v[52:67]
	v_mfma_f32_32x32x16_bf16 v[116:131], v[184:187], v[168:171], v[116:131]
	s_waitcnt vmcnt(0) lgkmcnt(0)
	s_barrier
; #define MFMA32(a, b, c) __builtin_amdgcn_mfma_f32_32x32x16_bf16((a), (b), (c), 0, 0, 0)
; template <bool SWAP, class Epi>
; DI void gemm_tile(const u16* __restrict__ A, int lda, const u16* __restrict__ Bw, int ldb, int K, char* lds, Epi epi) {
;     ...
;   auto compute = [&](int st) {
;     const char* as = lds + st * GEMM_STAGE;
;     const char* bs = as + 36864;
; #pragma unroll
;     for (int ks = 0; ks < 4; ++ks) {
;       bf16x8 af[2], bfr[2];
; #pragma unroll
;       for (int mi = 0; mi < 2; ++mi) af[mi] = *(const bf16x8*)(as + ((wm * 64 + mi * 32 + r) * 72 + ks * 16 + 8 * h) * 2);
; #pragma unroll
;       for (int ni = 0; ni < 2; ++ni) bfr[ni] = *(const bf16x8*)(bs + ((wn * 64 + ni * 32 + r) * 72 + ks * 16 + 8 * h) * 2);
; #pragma unroll
;       for (int mi = 0; mi < 2; ++mi)
; #pragma unroll
;         for (int ni = 0; ni < 2; ++ni) {
;           if (SWAP) acc[mi][ni] = MFMA32(bfr[ni], af[mi], acc[mi][ni]);
;           else acc[mi][ni] = MFMA32(af[mi], bfr[ni], acc[mi][ni]);
;         }
;     }
;   };
;   gload(0, ra0, rb0);
;   lstore(0, ra0, rb0);
;   gload(1, ra1, rb1);
;   __syncthreads();
;   for (int kt = 0; kt < nk; kt += 2) {
;     if (kt + 2 < nk) gload(kt + 2, ra0, rb0);
;     compute(0);
;     lstore(1, ra1, rb1);
;     __syncthreads();
;     if (kt + 3 < nk) gload(kt + 3, ra1, rb1);
;     compute(1);
;     if (kt + 2 < nk) lstore(0, ra0, rb0);
;     __syncthreads();
	ds_read_b128 v[132:135], v210 offset:32768
	ds_read_b128 v[136:139], v210 offset:36864
	ds_read_b128 v[140:143], v214 offset:32768
	ds_read_b128 v[144:147], v214 offset:36864
	ds_read_b128 v[148:151], v214 offset:49152
	ds_read_b128 v[158:161], v214 offset:53248
	s_mov_b32 m0, s44
	s_nop 0
	global_load_lds_dwordx4 v208, s[68:69]
	global_load_lds_dwordx4 v209, s[70:71] offset:1024
	global_load_lds_dwordx4 v208, s[72:73] offset:2048
	global_load_lds_dwordx4 v209, s[74:75] offset:3072
	ds_read_b128 v[162:165], v211 offset:32768
	ds_read_b128 v[168:171], v211 offset:36864
	ds_read_b128 v[172:175], v215 offset:32768
	ds_read_b128 v[176:179], v215 offset:36864
	ds_read_b128 v[180:183], v215 offset:49152
	ds_read_b128 v[184:187], v215 offset:53248
	s_waitcnt lgkmcnt(6)
	v_mfma_f32_32x32x16_bf16 v[4:19], v[140:143], v[132:135], v[4:19]
	v_mfma_f32_32x32x16_bf16 v[68:83], v[140:143], v[136:139], v[68:83]
	v_mfma_f32_32x32x16_bf16 v[20:35], v[144:147], v[132:135], v[20:35]
	v_mfma_f32_32x32x16_bf16 v[84:99], v[144:147], v[136:139], v[84:99]
	v_mfma_f32_32x32x16_bf16 v[36:51], v[148:151], v[132:135], v[36:51]
	v_mfma_f32_32x32x16_bf16 v[100:115], v[148:151], v[136:139], v[100:115]
	v_mfma_f32_32x32x16_bf16 v[52:67], v[158:161], v[132:135], v[52:67]
	v_mfma_f32_32x32x16_bf16 v[116:131], v[158:161], v[136:139], v[116:131]
	s_mov_b32 m0, s46
	s_nop 0
	global_load_lds_dwordx4 v208, s[76:77]
	global_load_lds_dwordx4 v209, s[78:79] offset:1024
	global_load_lds_dwordx4 v208, s[80:81] offset:2048
	global_load_lds_dwordx4 v209, s[82:83] offset:3072
	v_add_u32_e32 v208, 0x80, v208
	v_add_u32_e32 v209, 0x80, v209
	ds_read_b128 v[132:135], v212 offset:32768
	ds_read_b128 v[136:139], v212 offset:36864
	ds_read_b128 v[140:143], v216 offset:32768
	ds_read_b128 v[144:147], v216 offset:36864
	ds_read_b128 v[148:151], v216 offset:49152
	ds_read_b128 v[158:161], v216 offset:53248
	s_waitcnt lgkmcnt(6)
	v_mfma_f32_32x32x16_bf16 v[4:19], v[172:175], v[162:165], v[4:19]
	v_mfma_f32_32x32x16_bf16 v[68:83], v[172:175], v[168:171], v[68:83]
	v_mfma_f32_32x32x16_bf16 v[20:35], v[176:179], v[162:165], v[20:35]
	v_mfma_f32_32x32x16_bf16 v[84:99], v[176:179], v[168:171], v[84:99]
	v_mfma_f32_32x32x16_bf16 v[36:51], v[180:183], v[162:165], v[36:51]
	v_mfma_f32_32x32x16_bf16 v[100:115], v[180:183], v[168:171], v[100:115]
	v_mfma_f32_32x32x16_bf16 v[52:67], v[184:187], v[162:165], v[52:67]
	v_mfma_f32_32x32x16_bf16 v[116:131], v[184:187], v[168:171], v[116:131]
	ds_read_b128 v[162:165], v213 offset:32768
	ds_read_b128 v[168:171], v213 offset:36864
	ds_read_b128 v[172:175], v217 offset:32768
	ds_read_b128 v[176:179], v217 offset:36864
	ds_read_b128 v[180:183], v217 offset:49152
	ds_read_b128 v[184:187], v217 offset:53248
	s_waitcnt lgkmcnt(6)
	v_mfma_f32_32x32x16_bf16 v[4:19], v[140:143], v[132:135], v[4:19]
	v_mfma_f32_32x32x16_bf16 v[68:83], v[140:143], v[136:139], v[68:83]
	v_mfma_f32_32x32x16_bf16 v[20:35], v[144:147], v[132:135], v[20:35]
	v_mfma_f32_32x32x16_bf16 v[84:99], v[144:147], v[136:139], v[84:99]
	v_mfma_f32_32x32x16_bf16 v[36:51], v[148:151], v[132:135], v[36:51]
	v_mfma_f32_32x32x16_bf16 v[100:115], v[148:151], v[136:139], v[100:115]
	v_mfma_f32_32x32x16_bf16 v[52:67], v[158:161], v[132:135], v[52:67]
	v_mfma_f32_32x32x16_bf16 v[116:131], v[158:161], v[136:139], v[116:131]
	s_waitcnt lgkmcnt(0)
	v_mfma_f32_32x32x16_bf16 v[4:19], v[172:175], v[162:165], v[4:19]
	v_mfma_f32_32x32x16_bf16 v[68:83], v[172:175], v[168:171], v[68:83]
	v_mfma_f32_32x32x16_bf16 v[20:35], v[176:179], v[162:165], v[20:35]
	v_mfma_f32_32x32x16_bf16 v[84:99], v[176:179], v[168:171], v[84:99]
	v_mfma_f32_32x32x16_bf16 v[36:51], v[180:183], v[162:165], v[36:51]
	v_mfma_f32_32x32x16_bf16 v[100:115], v[180:183], v[168:171], v[100:115]
	v_mfma_f32_32x32x16_bf16 v[52:67], v[184:187], v[162:165], v[52:67]
	v_mfma_f32_32x32x16_bf16 v[116:131], v[184:187], v[168:171], v[116:131]
	s_waitcnt vmcnt(0) lgkmcnt(0)
	s_barrier
	ds_read_b128 v[132:135], v210 offset:0
	ds_read_b128 v[136:139], v210 offset:4096
	ds_read_b128 v[140:143], v214 offset:0
	ds_read_b128 v[144:147], v214 offset:4096
	ds_read_b128 v[148:151], v214 offset:16384
	ds_read_b128 v[158:161], v214 offset:20480
	s_mov_b32 m0, s45
	s_nop 0
	global_load_lds_dwordx4 v208, s[68:69]
	global_load_lds_dwordx4 v209, s[70:71] offset:1024
	global_load_lds_dwordx4 v208, s[72:73] offset:2048
	global_load_lds_dwordx4 v209, s[74:75] offset:3072
	ds_read_b128 v[162:165], v211 offset:0
	ds_read_b128 v[168:171], v211 offset:4096
	ds_read_b128 v[172:175], v215 offset:0
	ds_read_b128 v[176:179], v215 offset:4096
	ds_read_b128 v[180:183], v215 offset:16384
	ds_read_b128 v[184:187], v215 offset:20480
	s_waitcnt lgkmcnt(6)
	v_mfma_f32_32x32x16_bf16 v[4:19], v[140:143], v[132:135], v[4:19]
	v_mfma_f32_32x32x16_bf16 v[68:83], v[140:143], v[136:139], v[68:83]
	v_mfma_f32_32x32x16_bf16 v[20:35], v[144:147], v[132:135], v[20:35]
	v_mfma_f32_32x32x16_bf16 v[84:99], v[144:147], v[136:139], v[84:99]
	v_mfma_f32_32x32x16_bf16 v[36:51], v[148:151], v[132:135], v[36:51]
	v_mfma_f32_32x32x16_bf16 v[100:115], v[148:151], v[136:139], v[100:115]
	v_mfma_f32_32x32x16_bf16 v[52:67], v[158:161], v[132:135], v[52:67]
	v_mfma_f32_32x32x16_bf16 v[116:131], v[158:161], v[136:139], v[116:131]
	s_mov_b32 m0, s47
	s_nop 0
	global_load_lds_dwordx4 v208, s[76:77]
	global_load_lds_dwordx4 v209, s[78:79] offset:1024
	global_load_lds_dwordx4 v208, s[80:81] offset:2048
	global_load_lds_dwordx4 v209, s[82:83] offset:3072
	v_add_u32_e32 v208, 0x80, v208
	v_add_u32_e32 v209, 0x80, v209
	ds_read_b128 v[132:135], v212 offset:0
	ds_read_b128 v[136:139], v212 offset:4096
	ds_read_b128 v[140:143], v216 offset:0
	ds_read_b128 v[144:147], v216 offset:4096
	ds_read_b128 v[148:151], v216 offset:16384
	ds_read_b128 v[158:161], v216 offset:20480
	s_waitcnt lgkmcnt(6)
; #define MFMA32(a, b, c) __builtin_amdgcn_mfma_f32_32x32x16_bf16((a), (b), (c), 0, 0, 0)
; template <bool SWAP, class Epi>
; DI void gemm_tile(const u16* __restrict__ A, int lda, const u16* __restrict__ Bw, int ldb, int K, char* lds, Epi epi) {
;     ...
;   auto compute = [&](int st) {
;     const char* as = lds + st * GEMM_STAGE;
;     const char* bs = as + 36864;
; #pragma unroll
;     for (int ks = 0; ks < 4; ++ks) {
;       bf16x8 af[2], bfr[2];
; #pragma unroll
;       for (int mi = 0; mi < 2; ++mi) af[mi] = *(const bf16x8*)(as + ((wm * 64 + mi * 32 + r) * 72 + ks * 16 + 8 * h) * 2);
; #pragma unroll
;       for (int ni = 0; ni < 2; ++ni) bfr[ni] = *(const bf16x8*)(bs + ((wn * 64 + ni * 32 + r) * 72 + ks * 16 + 8 * h) * 2);
; #pragma unroll
;       for (int mi = 0; mi < 2; ++mi)
; #pragma unroll
;         for (int ni = 0; ni < 2; ++ni) {
;           if (SWAP) acc[mi][ni] = MFMA32(bfr[ni], af[mi], acc[mi][ni]);
;           else acc[mi][ni] = MFMA32(af[mi], bfr[ni], acc[mi][ni]);
;         }
;     }
;   };
;   gload(0, ra0, rb0);
;   lstore(0, ra0, rb0);
;   gload(1, ra1, rb1);
;   __syncthreads();
;   for (int kt = 0; kt < nk; kt += 2) {
;     if (kt + 2 < nk) gload(kt + 2, ra0, rb0);
;     compute(0);
;     lstore(1, ra1, rb1);
;     __syncthreads();
;     if (kt + 3 < nk) gload(kt + 3, ra1, rb1);
;     compute(1);
;     if (kt + 2 < nk) lstore(0, ra0, rb0);
;     __syncthreads();
	v_mfma_f32_32x32x16_bf16 v[4:19], v[172:175], v[162:165], v[4:19]
	v_mfma_f32_32x32x16_bf16 v[68:83], v[172:175], v[168:171], v[68:83]
	v_mfma_f32_32x32x16_bf16 v[20:35], v[176:179], v[162:165], v[20:35]
	v_mfma_f32_32x32x16_bf16 v[84:99], v[176:179], v[168:171], v[84:99]
	v_mfma_f32_32x32x16_bf16 v[36:51], v[180:183], v[162:165], v[36:51]
	v_mfma_f32_32x32x16_bf16 v[100:115], v[180:183], v[168:171], v[100:115]
	v_mfma_f32_32x32x16_bf16 v[52:67], v[184:187], v[162:165], v[52:67]
	v_mfma_f32_32x32x16_bf16 v[116:131], v[184:187], v[168:171], v[116:131]
	ds_read_b128 v[162:165], v213 offset:0
	ds_read_b128 v[168:171], v213 offset:4096
	ds_read_b128 v[172:175], v217 offset:0
	ds_read_b128 v[176:179], v217 offset:4096
	ds_read_b128 v[180:183], v217 offset:16384
	ds_read_b128 v[184:187], v217 offset:20480
	s_waitcnt lgkmcnt(6)
	v_mfma_f32_32x32x16_bf16 v[4:19], v[140:143], v[132:135], v[4:19]
	v_mfma_f32_32x32x16_bf16 v[68:83], v[140:143], v[136:139], v[68:83]
	v_mfma_f32_32x32x16_bf16 v[20:35], v[144:147], v[132:135], v[20:35]
	v_mfma_f32_32x32x16_bf16 v[84:99], v[144:147], v[136:139], v[84:99]
	v_mfma_f32_32x32x16_bf16 v[36:51], v[148:151], v[132:135], v[36:51]
	v_mfma_f32_32x32x16_bf16 v[100:115], v[148:151], v[136:139], v[100:115]
	v_mfma_f32_32x32x16_bf16 v[52:67], v[158:161], v[132:135], v[52:67]
	v_mfma_f32_32x32x16_bf16 v[116:131], v[158:161], v[136:139], v[116:131]
	s_waitcnt lgkmcnt(0)
	v_mfma_f32_32x32x16_bf16 v[4:19], v[172:175], v[162:165], v[4:19]
	v_mfma_f32_32x32x16_bf16 v[68:83], v[172:175], v[168:171], v[68:83]
	v_mfma_f32_32x32x16_bf16 v[20:35], v[176:179], v[162:165], v[20:35]
	v_mfma_f32_32x32x16_bf16 v[84:99], v[176:179], v[168:171], v[84:99]
	v_mfma_f32_32x32x16_bf16 v[36:51], v[180:183], v[162:165], v[36:51]
	v_mfma_f32_32x32x16_bf16 v[100:115], v[180:183], v[168:171], v[100:115]
	v_mfma_f32_32x32x16_bf16 v[52:67], v[184:187], v[162:165], v[52:67]
	v_mfma_f32_32x32x16_bf16 v[116:131], v[184:187], v[168:171], v[116:131]
	s_waitcnt vmcnt(0) lgkmcnt(0)
	s_barrier
	ds_read_b128 v[132:135], v210 offset:32768
	ds_read_b128 v[136:139], v210 offset:36864
	ds_read_b128 v[140:143], v214 offset:32768
	ds_read_b128 v[144:147], v214 offset:36864
	ds_read_b128 v[148:151], v214 offset:49152
	ds_read_b128 v[158:161], v214 offset:53248
	s_mov_b32 m0, s44
	s_nop 0
	global_load_lds_dwordx4 v208, s[68:69]
	global_load_lds_dwordx4 v209, s[70:71] offset:1024
	global_load_lds_dwordx4 v208, s[72:73] offset:2048
	global_load_lds_dwordx4 v209, s[74:75] offset:3072
	ds_read_b128 v[162:165], v211 offset:32768
	ds_read_b128 v[168:171], v211 offset:36864
	ds_read_b128 v[172:175], v215 offset:32768
	ds_read_b128 v[176:179], v215 offset:36864
	ds_read_b128 v[180:183], v215 offset:49152
	ds_read_b128 v[184:187], v215 offset:53248
	s_waitcnt lgkmcnt(6)
	v_mfma_f32_32x32x16_bf16 v[4:19], v[140:143], v[132:135], v[4:19]
	v_mfma_f32_32x32x16_bf16 v[68:83], v[140:143], v[136:139], v[68:83]
	v_mfma_f32_32x32x16_bf16 v[20:35], v[144:147], v[132:135], v[20:35]
	v_mfma_f32_32x32x16_bf16 v[84:99], v[144:147], v[136:139], v[84:99]
	v_mfma_f32_32x32x16_bf16 v[36:51], v[148:151], v[132:135], v[36:51]
	v_mfma_f32_32x32x16_bf16 v[100:115], v[148:151], v[136:139], v[100:115]
	v_mfma_f32_32x32x16_bf16 v[52:67], v[158:161], v[132:135], v[52:67]
	v_mfma_f32_32x32x16_bf16 v[116:131], v[158:161], v[136:139], v[116:131]
	s_mov_b32 m0, s46
	s_nop 0
	global_load_lds_dwordx4 v208, s[76:77]
	global_load_lds_dwordx4 v209, s[78:79] offset:1024
	global_load_lds_dwordx4 v208, s[80:81] offset:2048
	global_load_lds_dwordx4 v209, s[82:83] offset:3072
	v_add_u32_e32 v208, 0x80, v208
	v_add_u32_e32 v209, 0x80, v209
	ds_read_b128 v[132:135], v212 offset:32768
	ds_read_b128 v[136:139], v212 offset:36864
	ds_read_b128 v[140:143], v216 offset:32768
	ds_read_b128 v[144:147], v216 offset:36864
	ds_read_b128 v[148:151], v216 offset:49152
	ds_read_b128 v[158:161], v216 offset:53248
	s_waitcnt lgkmcnt(6)
	v_mfma_f32_32x32x16_bf16 v[4:19], v[172:175], v[162:165], v[4:19]
	v_mfma_f32_32x32x16_bf16 v[68:83], v[172:175], v[168:171], v[68:83]
	v_mfma_f32_32x32x16_bf16 v[20:35], v[176:179], v[162:165], v[20:35]
	v_mfma_f32_32x32x16_bf16 v[84:99], v[176:179], v[168:171], v[84:99]
	v_mfma_f32_32x32x16_bf16 v[36:51], v[180:183], v[162:165], v[36:51]
	v_mfma_f32_32x32x16_bf16 v[100:115], v[180:183], v[168:171], v[100:115]
	v_mfma_f32_32x32x16_bf16 v[52:67], v[184:187], v[162:165], v[52:67]
	v_mfma_f32_32x32x16_bf16 v[116:131], v[184:187], v[168:171], v[116:131]
	ds_read_b128 v[162:165], v213 offset:32768
	ds_read_b128 v[168:171], v213 offset:36864
	ds_read_b128 v[172:175], v217 offset:32768
	ds_read_b128 v[176:179], v217 offset:36864
	ds_read_b128 v[180:183], v217 offset:49152
	ds_read_b128 v[184:187], v217 offset:53248
	s_waitcnt lgkmcnt(6)
	v_mfma_f32_32x32x16_bf16 v[4:19], v[140:143], v[132:135], v[4:19]
	v_mfma_f32_32x32x16_bf16 v[68:83], v[140:143], v[136:139], v[68:83]
	v_mfma_f32_32x32x16_bf16 v[20:35], v[144:147], v[132:135], v[20:35]
	v_mfma_f32_32x32x16_bf16 v[84:99], v[144:147], v[136:139], v[84:99]
	v_mfma_f32_32x32x16_bf16 v[36:51], v[148:151], v[132:135], v[36:51]
	v_mfma_f32_32x32x16_bf16 v[100:115], v[148:151], v[136:139], v[100:115]
	v_mfma_f32_32x32x16_bf16 v[52:67], v[158:161], v[132:135], v[52:67]
	v_mfma_f32_32x32x16_bf16 v[116:131], v[158:161], v[136:139], v[116:131]
	s_waitcnt lgkmcnt(0)
	v_mfma_f32_32x32x16_bf16 v[4:19], v[172:175], v[162:165], v[4:19]
	v_mfma_f32_32x32x16_bf16 v[68:83], v[172:175], v[168:171], v[68:83]
	v_mfma_f32_32x32x16_bf16 v[20:35], v[176:179], v[162:165], v[20:35]
	v_mfma_f32_32x32x16_bf16 v[84:99], v[176:179], v[168:171], v[84:99]
	v_mfma_f32_32x32x16_bf16 v[36:51], v[180:183], v[162:165], v[36:51]
	v_mfma_f32_32x32x16_bf16 v[100:115], v[180:183], v[168:171], v[100:115]
	v_mfma_f32_32x32x16_bf16 v[52:67], v[184:187], v[162:165], v[52:67]
	v_mfma_f32_32x32x16_bf16 v[116:131], v[184:187], v[168:171], v[116:131]
	s_waitcnt vmcnt(0) lgkmcnt(0)
	s_barrier
; #define MFMA32(a, b, c) __builtin_amdgcn_mfma_f32_32x32x16_bf16((a), (b), (c), 0, 0, 0)
; template <bool SWAP, class Epi>
; DI void gemm_tile(const u16* __restrict__ A, int lda, const u16* __restrict__ Bw, int ldb, int K, char* lds, Epi epi) {
;     ...
;   auto compute = [&](int st) {
;     const char* as = lds + st * GEMM_STAGE;
;     const char* bs = as + 36864;
; #pragma unroll
;     for (int ks = 0; ks < 4; ++ks) {
;       bf16x8 af[2], bfr[2];
; #pragma unroll
;       for (int mi = 0; mi < 2; ++mi) af[mi] = *(const bf16x8*)(as + ((wm * 64 + mi * 32 + r) * 72 + ks * 16 + 8 * h) * 2);
; #pragma unroll
;       for (int ni = 0; ni < 2; ++ni) bfr[ni] = *(const bf16x8*)(bs + ((wn * 64 + ni * 32 + r) * 72 + ks * 16 + 8 * h) * 2);
; #pragma unroll
;       for (int mi = 0; mi < 2; ++mi)
; #pragma unroll
;         for (int ni = 0; ni < 2; ++ni) {
;           if (SWAP) acc[mi][ni] = MFMA32(bfr[ni], af[mi], acc[mi][ni]);
;           else acc[mi][ni] = MFMA32(af[mi], bfr[ni], acc[mi][ni]);
;         }
;     }
;   };
;   gload(0, ra0, rb0);
;   lstore(0, ra0, rb0);
;   gload(1, ra1, rb1);
;   __syncthreads();
;   for (int kt = 0; kt < nk; kt += 2) {
;     if (kt + 2 < nk) gload(kt + 2, ra0, rb0);
;     compute(0);
;     lstore(1, ra1, rb1);
;     __syncthreads();
;     if (kt + 3 < nk) gload(kt + 3, ra1, rb1);
;     compute(1);
;     if (kt + 2 < nk) lstore(0, ra0, rb0);
;     __syncthreads();
	ds_read_b128 v[132:135], v210 offset:0
	ds_read_b128 v[136:139], v210 offset:4096
	ds_read_b128 v[140:143], v214 offset:0
	ds_read_b128 v[144:147], v214 offset:4096
	ds_read_b128 v[148:151], v214 offset:16384
	ds_read_b128 v[158:161], v214 offset:20480
	s_mov_b32 m0, s45
	s_nop 0
	global_load_lds_dwordx4 v208, s[68:69]
	global_load_lds_dwordx4 v209, s[70:71] offset:1024
	global_load_lds_dwordx4 v208, s[72:73] offset:2048
	global_load_lds_dwordx4 v209, s[74:75] offset:3072
	ds_read_b128 v[162:165], v211 offset:0
	ds_read_b128 v[168:171], v211 offset:4096
	ds_read_b128 v[172:175], v215 offset:0
	ds_read_b128 v[176:179], v215 offset:4096
	ds_read_b128 v[180:183], v215 offset:16384
	ds_read_b128 v[184:187], v215 offset:20480
	s_waitcnt lgkmcnt(6)
	v_mfma_f32_32x32x16_bf16 v[4:19], v[140:143], v[132:135], v[4:19]
	v_mfma_f32_32x32x16_bf16 v[68:83], v[140:143], v[136:139], v[68:83]
	v_mfma_f32_32x32x16_bf16 v[20:35], v[144:147], v[132:135], v[20:35]
	v_mfma_f32_32x32x16_bf16 v[84:99], v[144:147], v[136:139], v[84:99]
	v_mfma_f32_32x32x16_bf16 v[36:51], v[148:151], v[132:135], v[36:51]
	v_mfma_f32_32x32x16_bf16 v[100:115], v[148:151], v[136:139], v[100:115]
	v_mfma_f32_32x32x16_bf16 v[52:67], v[158:161], v[132:135], v[52:67]
	v_mfma_f32_32x32x16_bf16 v[116:131], v[158:161], v[136:139], v[116:131]
	s_mov_b32 m0, s47
	s_nop 0
	global_load_lds_dwordx4 v208, s[76:77]
	global_load_lds_dwordx4 v209, s[78:79] offset:1024
	global_load_lds_dwordx4 v208, s[80:81] offset:2048
	global_load_lds_dwordx4 v209, s[82:83] offset:3072
	v_add_u32_e32 v208, 0x80, v208
	v_add_u32_e32 v209, 0x80, v209
	ds_read_b128 v[132:135], v212 offset:0
	ds_read_b128 v[136:139], v212 offset:4096
	ds_read_b128 v[140:143], v216 offset:0
	ds_read_b128 v[144:147], v216 offset:4096
	ds_read_b128 v[148:151], v216 offset:16384
	ds_read_b128 v[158:161], v216 offset:20480
	s_waitcnt lgkmcnt(6)
	v_mfma_f32_32x32x16_bf16 v[4:19], v[172:175], v[162:165], v[4:19]
	v_mfma_f32_32x32x16_bf16 v[68:83], v[172:175], v[168:171], v[68:83]
	v_mfma_f32_32x32x16_bf16 v[20:35], v[176:179], v[162:165], v[20:35]
	v_mfma_f32_32x32x16_bf16 v[84:99], v[176:179], v[168:171], v[84:99]
	v_mfma_f32_32x32x16_bf16 v[36:51], v[180:183], v[162:165], v[36:51]
	v_mfma_f32_32x32x16_bf16 v[100:115], v[180:183], v[168:171], v[100:115]
	v_mfma_f32_32x32x16_bf16 v[52:67], v[184:187], v[162:165], v[52:67]
	v_mfma_f32_32x32x16_bf16 v[116:131], v[184:187], v[168:171], v[116:131]
	ds_read_b128 v[162:165], v213 offset:0
	ds_read_b128 v[168:171], v213 offset:4096
	ds_read_b128 v[172:175], v217 offset:0
	ds_read_b128 v[176:179], v217 offset:4096
	ds_read_b128 v[180:183], v217 offset:16384
	ds_read_b128 v[184:187], v217 offset:20480
	s_waitcnt lgkmcnt(6)
	v_mfma_f32_32x32x16_bf16 v[4:19], v[140:143], v[132:135], v[4:19]
	v_mfma_f32_32x32x16_bf16 v[68:83], v[140:143], v[136:139], v[68:83]
	v_mfma_f32_32x32x16_bf16 v[20:35], v[144:147], v[132:135], v[20:35]
	v_mfma_f32_32x32x16_bf16 v[84:99], v[144:147], v[136:139], v[84:99]
	v_mfma_f32_32x32x16_bf16 v[36:51], v[148:151], v[132:135], v[36:51]
	v_mfma_f32_32x32x16_bf16 v[100:115], v[148:151], v[136:139], v[100:115]
	v_mfma_f32_32x32x16_bf16 v[52:67], v[158:161], v[132:135], v[52:67]
	v_mfma_f32_32x32x16_bf16 v[116:131], v[158:161], v[136:139], v[116:131]
	s_waitcnt lgkmcnt(0)
	v_mfma_f32_32x32x16_bf16 v[4:19], v[172:175], v[162:165], v[4:19]
	v_mfma_f32_32x32x16_bf16 v[68:83], v[172:175], v[168:171], v[68:83]
	v_mfma_f32_32x32x16_bf16 v[20:35], v[176:179], v[162:165], v[20:35]
	v_mfma_f32_32x32x16_bf16 v[84:99], v[176:179], v[168:171], v[84:99]
	v_mfma_f32_32x32x16_bf16 v[36:51], v[180:183], v[162:165], v[36:51]
	v_mfma_f32_32x32x16_bf16 v[100:115], v[180:183], v[168:171], v[100:115]
	v_mfma_f32_32x32x16_bf16 v[52:67], v[184:187], v[162:165], v[52:67]
	v_mfma_f32_32x32x16_bf16 v[116:131], v[184:187], v[168:171], v[116:131]
	s_waitcnt vmcnt(0) lgkmcnt(0)
	s_barrier
	ds_read_b128 v[132:135], v210 offset:32768
	ds_read_b128 v[136:139], v210 offset:36864
	ds_read_b128 v[140:143], v214 offset:32768
	ds_read_b128 v[144:147], v214 offset:36864
	ds_read_b128 v[148:151], v214 offset:49152
	ds_read_b128 v[158:161], v214 offset:53248
	ds_read_b128 v[162:165], v211 offset:32768
	ds_read_b128 v[168:171], v211 offset:36864
	ds_read_b128 v[172:175], v215 offset:32768
	ds_read_b128 v[176:179], v215 offset:36864
	ds_read_b128 v[180:183], v215 offset:49152
	ds_read_b128 v[184:187], v215 offset:53248
	s_waitcnt lgkmcnt(6)
	v_mfma_f32_32x32x16_bf16 v[4:19], v[140:143], v[132:135], v[4:19]
	v_mfma_f32_32x32x16_bf16 v[68:83], v[140:143], v[136:139], v[68:83]
	v_mfma_f32_32x32x16_bf16 v[20:35], v[144:147], v[132:135], v[20:35]
	v_mfma_f32_32x32x16_bf16 v[84:99], v[144:147], v[136:139], v[84:99]
	v_mfma_f32_32x32x16_bf16 v[36:51], v[148:151], v[132:135], v[36:51]
	v_mfma_f32_32x32x16_bf16 v[100:115], v[148:151], v[136:139], v[100:115]
	v_mfma_f32_32x32x16_bf16 v[52:67], v[158:161], v[132:135], v[52:67]
	v_mfma_f32_32x32x16_bf16 v[116:131], v[158:161], v[136:139], v[116:131]
	ds_read_b128 v[132:135], v212 offset:32768
	ds_read_b128 v[136:139], v212 offset:36864
	ds_read_b128 v[140:143], v216 offset:32768
	ds_read_b128 v[144:147], v216 offset:36864
	ds_read_b128 v[148:151], v216 offset:49152
	ds_read_b128 v[158:161], v216 offset:53248
	s_waitcnt lgkmcnt(6)
; DI unsigned pk2(float a, float b) { f32x2 v = {a, b}; return __builtin_bit_cast(unsigned, __builtin_convertvector(v, bf2_t)); }
; DI void store_rowmajor(u16* dst, const f32x16& a, int h, float sc) {
; #pragma unroll
;   for (int kp = 0; kp < 2; ++kp) {
;     const int g = 2 * kp;
;     unsigned ax = pk2(a[4 * g] * sc, a[4 * g + 1] * sc), ay = pk2(a[4 * g + 2] * sc, a[4 * g + 3] * sc);
;     unsigned bx = pk2(a[4 * g + 4] * sc, a[4 * g + 5] * sc), by = pk2(a[4 * g + 6] * sc, a[4 * g + 7] * sc);
;     const u32x2 rx = __builtin_amdgcn_permlane32_swap(ax, bx, false, false);
;     const u32x2 ry = __builtin_amdgcn_permlane32_swap(ay, by, false, false);
;     const u32x4 v = {rx[0], ry[0], rx[1], ry[1]};
;     *(u32x4*)(dst + 8 * (g + h)) = v;
;   }
; }
; DI void inproj_tile(const Params& p, int l, int mt, int nt, char* lds) {
;     ...
;     gemm_tile<true>(A, DM, Bw, DM, DM, lds, [&](int mi, int ni, const f32x16& a) {
;       const int tok = m0 + wm * 64 + mi * 32 + r;
;       store_rowmajor(p.H + (size_t)tok * LDH + nt * 128 + wn * 64 + ni * 32, a, h, 1.f);
	v_mfma_f32_32x32x16_bf16 v[4:19], v[172:175], v[162:165], v[4:19]
	v_mfma_f32_32x32x16_bf16 v[68:83], v[172:175], v[168:171], v[68:83]
	v_mfma_f32_32x32x16_bf16 v[20:35], v[176:179], v[162:165], v[20:35]
	v_mfma_f32_32x32x16_bf16 v[84:99], v[176:179], v[168:171], v[84:99]
	v_mfma_f32_32x32x16_bf16 v[36:51], v[180:183], v[162:165], v[36:51]
	v_mfma_f32_32x32x16_bf16 v[100:115], v[180:183], v[168:171], v[100:115]
	v_mfma_f32_32x32x16_bf16 v[52:67], v[184:187], v[162:165], v[52:67]
	v_mfma_f32_32x32x16_bf16 v[116:131], v[184:187], v[168:171], v[116:131]
	ds_read_b128 v[162:165], v213 offset:32768
	ds_read_b128 v[168:171], v213 offset:36864
	ds_read_b128 v[172:175], v217 offset:32768
	ds_read_b128 v[176:179], v217 offset:36864
	ds_read_b128 v[180:183], v217 offset:49152
	ds_read_b128 v[184:187], v217 offset:53248
	s_waitcnt lgkmcnt(6)
	v_mfma_f32_32x32x16_bf16 v[4:19], v[140:143], v[132:135], v[4:19]
	v_mfma_f32_32x32x16_bf16 v[68:83], v[140:143], v[136:139], v[68:83]
	v_mfma_f32_32x32x16_bf16 v[20:35], v[144:147], v[132:135], v[20:35]
	v_mfma_f32_32x32x16_bf16 v[84:99], v[144:147], v[136:139], v[84:99]
	v_mfma_f32_32x32x16_bf16 v[36:51], v[148:151], v[132:135], v[36:51]
	v_mfma_f32_32x32x16_bf16 v[100:115], v[148:151], v[136:139], v[100:115]
	v_mfma_f32_32x32x16_bf16 v[52:67], v[158:161], v[132:135], v[52:67]
	v_mfma_f32_32x32x16_bf16 v[116:131], v[158:161], v[136:139], v[116:131]
	s_waitcnt lgkmcnt(0)
	v_mfma_f32_32x32x16_bf16 v[4:19], v[172:175], v[162:165], v[4:19]
	v_mfma_f32_32x32x16_bf16 v[68:83], v[172:175], v[168:171], v[68:83]
	v_mfma_f32_32x32x16_bf16 v[20:35], v[176:179], v[162:165], v[20:35]
	v_mfma_f32_32x32x16_bf16 v[84:99], v[176:179], v[168:171], v[84:99]
	v_mfma_f32_32x32x16_bf16 v[36:51], v[180:183], v[162:165], v[36:51]
	v_mfma_f32_32x32x16_bf16 v[100:115], v[180:183], v[168:171], v[100:115]
	v_mfma_f32_32x32x16_bf16 v[52:67], v[184:187], v[162:165], v[52:67]
	v_mfma_f32_32x32x16_bf16 v[116:131], v[184:187], v[168:171], v[116:131]
	s_waitcnt lgkmcnt(0)
	s_barrier
	s_nop 7
	s_nop 7
	v_cvt_pk_bf16_f32 v224, v4, v5
	v_cvt_pk_bf16_f32 v225, v6, v7
	v_cvt_pk_bf16_f32 v226, v8, v9
	v_cvt_pk_bf16_f32 v227, v10, v11
	s_nop 1
	v_permlane32_swap_b32_e32 v224, v226
	v_permlane32_swap_b32_e32 v225, v227
	s_nop 0
	global_store_dwordx4 v218, v[224:227], s[8:9]
	v_cvt_pk_bf16_f32 v228, v12, v13
	v_cvt_pk_bf16_f32 v229, v14, v15
	v_cvt_pk_bf16_f32 v230, v16, v17
	v_cvt_pk_bf16_f32 v231, v18, v19
	s_nop 1
	v_permlane32_swap_b32_e32 v228, v230
	v_permlane32_swap_b32_e32 v229, v231
	s_nop 0
	global_store_dwordx4 v218, v[228:231], s[8:9] offset:32
	v_cvt_pk_bf16_f32 v224, v68, v69
	v_cvt_pk_bf16_f32 v225, v70, v71
	v_cvt_pk_bf16_f32 v226, v72, v73
	v_cvt_pk_bf16_f32 v227, v74, v75
	s_nop 1
	v_permlane32_swap_b32_e32 v224, v226
	v_permlane32_swap_b32_e32 v225, v227
	s_nop 0
	global_store_dwordx4 v219, v[224:227], s[8:9]
	v_cvt_pk_bf16_f32 v228, v76, v77
	v_cvt_pk_bf16_f32 v229, v78, v79
	v_cvt_pk_bf16_f32 v230, v80, v81
	v_cvt_pk_bf16_f32 v231, v82, v83
	s_nop 1
	v_permlane32_swap_b32_e32 v228, v230
	v_permlane32_swap_b32_e32 v229, v231
	s_nop 0
	global_store_dwordx4 v219, v[228:231], s[8:9] offset:32
	v_cvt_pk_bf16_f32 v224, v20, v21
	v_cvt_pk_bf16_f32 v225, v22, v23
	v_cvt_pk_bf16_f32 v226, v24, v25
	v_cvt_pk_bf16_f32 v227, v26, v27
	s_nop 1
	v_permlane32_swap_b32_e32 v224, v226
	v_permlane32_swap_b32_e32 v225, v227
	s_nop 0
	global_store_dwordx4 v218, v[224:227], s[8:9] offset:64
	v_cvt_pk_bf16_f32 v228, v28, v29
	v_cvt_pk_bf16_f32 v229, v30, v31
	v_cvt_pk_bf16_f32 v230, v32, v33
	v_cvt_pk_bf16_f32 v231, v34, v35
	s_nop 1
	v_permlane32_swap_b32_e32 v228, v230
	v_permlane32_swap_b32_e32 v229, v231
	s_nop 0
	global_store_dwordx4 v218, v[228:231], s[8:9] offset:96
	v_cvt_pk_bf16_f32 v224, v84, v85
	v_cvt_pk_bf16_f32 v225, v86, v87
	v_cvt_pk_bf16_f32 v226, v88, v89
	v_cvt_pk_bf16_f32 v227, v90, v91
	s_nop 1
	v_permlane32_swap_b32_e32 v224, v226
	v_permlane32_swap_b32_e32 v225, v227
	s_nop 0
	global_store_dwordx4 v219, v[224:227], s[8:9] offset:64
	v_cvt_pk_bf16_f32 v228, v92, v93
	v_cvt_pk_bf16_f32 v229, v94, v95
	v_cvt_pk_bf16_f32 v230, v96, v97
	v_cvt_pk_bf16_f32 v231, v98, v99
	s_nop 1
	v_permlane32_swap_b32_e32 v228, v230
	v_permlane32_swap_b32_e32 v229, v231
	s_nop 0
	global_store_dwordx4 v219, v[228:231], s[8:9] offset:96
	v_cvt_pk_bf16_f32 v224, v36, v37
	v_cvt_pk_bf16_f32 v225, v38, v39
	v_cvt_pk_bf16_f32 v226, v40, v41
	v_cvt_pk_bf16_f32 v227, v42, v43
	s_nop 1
	v_permlane32_swap_b32_e32 v224, v226
	v_permlane32_swap_b32_e32 v225, v227
	s_nop 0
	global_store_dwordx4 v218, v[224:227], s[8:9] offset:256
	v_cvt_pk_bf16_f32 v228, v44, v45
	v_cvt_pk_bf16_f32 v229, v46, v47
	v_cvt_pk_bf16_f32 v230, v48, v49
	v_cvt_pk_bf16_f32 v231, v50, v51
	s_nop 1
	v_permlane32_swap_b32_e32 v228, v230
	v_permlane32_swap_b32_e32 v229, v231
	s_nop 0
	global_store_dwordx4 v218, v[228:231], s[8:9] offset:288
	v_cvt_pk_bf16_f32 v224, v100, v101
	v_cvt_pk_bf16_f32 v225, v102, v103
	v_cvt_pk_bf16_f32 v226, v104, v105
	v_cvt_pk_bf16_f32 v227, v106, v107
	s_nop 1
	v_permlane32_swap_b32_e32 v224, v226
	v_permlane32_swap_b32_e32 v225, v227
	s_nop 0
	global_store_dwordx4 v219, v[224:227], s[8:9] offset:256
	v_cvt_pk_bf16_f32 v228, v108, v109
	v_cvt_pk_bf16_f32 v229, v110, v111
	v_cvt_pk_bf16_f32 v230, v112, v113
	v_cvt_pk_bf16_f32 v231, v114, v115
	s_nop 1
	v_permlane32_swap_b32_e32 v228, v230
	v_permlane32_swap_b32_e32 v229, v231
	s_nop 0
	global_store_dwordx4 v219, v[228:231], s[8:9] offset:288
	v_cvt_pk_bf16_f32 v224, v52, v53
	v_cvt_pk_bf16_f32 v225, v54, v55
	v_cvt_pk_bf16_f32 v226, v56, v57
	v_cvt_pk_bf16_f32 v227, v58, v59
	s_nop 1
	v_permlane32_swap_b32_e32 v224, v226
	v_permlane32_swap_b32_e32 v225, v227
	s_nop 0
	global_store_dwordx4 v218, v[224:227], s[8:9] offset:320
	v_cvt_pk_bf16_f32 v228, v60, v61
	v_cvt_pk_bf16_f32 v229, v62, v63
	v_cvt_pk_bf16_f32 v230, v64, v65
	v_cvt_pk_bf16_f32 v231, v66, v67
	s_nop 1
	v_permlane32_swap_b32_e32 v228, v230
	v_permlane32_swap_b32_e32 v229, v231
	s_nop 0
	global_store_dwordx4 v218, v[228:231], s[8:9] offset:352
	v_cvt_pk_bf16_f32 v224, v116, v117
	v_cvt_pk_bf16_f32 v225, v118, v119
	v_cvt_pk_bf16_f32 v226, v120, v121
	v_cvt_pk_bf16_f32 v227, v122, v123
	s_nop 1
	v_permlane32_swap_b32_e32 v224, v226
	v_permlane32_swap_b32_e32 v225, v227
	s_nop 0
	global_store_dwordx4 v219, v[224:227], s[8:9] offset:320
	v_cvt_pk_bf16_f32 v228, v124, v125
	v_cvt_pk_bf16_f32 v229, v126, v127
	v_cvt_pk_bf16_f32 v230, v128, v129
	v_cvt_pk_bf16_f32 v231, v130, v131
	s_nop 1
	v_permlane32_swap_b32_e32 v228, v230
	v_permlane32_swap_b32_e32 v229, v231
	s_nop 0
	global_store_dwordx4 v219, v[228:231], s[8:9] offset:352
	s_addk_i32 s101, 0x20
	s_branch .Lpp_loop
; #define MFMA32(a, b, c) __builtin_amdgcn_mfma_f32_32x32x16_bf16((a), (b), (c), 0, 0, 0)
; template <bool SWAP, class Epi>
; DI void gemm_tile(const u16* __restrict__ A, int lda, const u16* __restrict__ Bw, int ldb, int K, char* lds, Epi epi) {
;     ...
;   const int lrow = tid >> 3, lkc = tid & 7;
;   u32x4 ra0[4], rb0[2], ra1[4], rb1[2];
;   const u16* ap = A + (size_t)lrow * lda + lkc * 8;
;   const u16* bp = Bw + (size_t)lrow * ldb + lkc * 8;
;   const int nk = K >> 6;
;   auto gload = [&](int kt, u32x4* ra, u32x4* rb) {
; #pragma unroll
;     for (int j = 0; j < 4; ++j) ra[j] = *(const u32x4*)(ap + (size_t)(64 * j) * lda + kt * 64);
; #pragma unroll
;     for (int j = 0; j < 2; ++j) rb[j] = *(const u32x4*)(bp + (size_t)(64 * j) * ldb + kt * 64);
;   };
;   auto lstore = [&](int st, const u32x4* ra, const u32x4* rb) {
;     char* base = lds + st * GEMM_STAGE;
; #pragma unroll
;     for (int j = 0; j < 4; ++j) *(u32x4*)(base + ((lrow + 64 * j) * 72 + lkc * 8) * 2) = ra[j];
; #pragma unroll
;     for (int j = 0; j < 2; ++j) *(u32x4*)(base + 36864 + ((lrow + 64 * j) * 72 + lkc * 8) * 2) = rb[j];
;   };
;   auto compute = [&](int st) {
;     const char* as = lds + st * GEMM_STAGE;
;     const char* bs = as + 36864;
; #pragma unroll
;     for (int ks = 0; ks < 4; ++ks) {
;       bf16x8 af[2], bfr[2];
; #pragma unroll
;       for (int mi = 0; mi < 2; ++mi) af[mi] = *(const bf16x8*)(as + ((wm * 64 + mi * 32 + r) * 72 + ks * 16 + 8 * h) * 2);
; #pragma unroll
;       for (int ni = 0; ni < 2; ++ni) bfr[ni] = *(const bf16x8*)(bs + ((wn * 64 + ni * 32 + r) * 72 + ks * 16 + 8 * h) * 2);
; #pragma unroll
;       for (int mi = 0; mi < 2; ++mi)
; #pragma unroll
;         for (int ni = 0; ni < 2; ++ni) {
;           if (SWAP) acc[mi][ni] = MFMA32(bfr[ni], af[mi], acc[mi][ni]);
;           else acc[mi][ni] = MFMA32(af[mi], bfr[ni], acc[mi][ni]);
;         }
;     }
;   };
;   gload(0, ra0, rb0);
;   lstore(0, ra0, rb0);
;   gload(1, ra1, rb1);
;   __syncthreads();
; __global__ void __launch_bounds__(NTHREADS) mega(Params p) {
;     ...
;       for (int j = blockIdx.x; j < 66 * 48; j += gridDim.x) inproj_tile(p, l, j / 48, j % 48, lds);
.Lpp_done:
	v_readlane_b32 s25, v238, 16
	s_and_b32 s0, s25, 7
	s_lshr_b32 s25, s25, 3
	s_cmp_gt_u32 s0, 5
	s_cbranch_scc1 .Lsg_go
	s_cmp_lt_u32 s25, 17
	s_cbranch_scc1 .LBB0_370
	s_cmp_gt_u32 s25, 27
	s_cbranch_scc1 .LBB0_370
.Lsg_go:
	s_branch .LBB0_324
.LBB0_322:
	s_or_b64 exec, exec, s[2:3]
.LBB0_323:
	s_mov_b32 s25, s101
	v_readlane_b32 s0, v238, 18
	s_add_i32 s25, s25, 32
	s_add_i32 s24, s24, s0
	s_add_i32 s23, s23, s22
	v_readlane_b32 s0, v238, 16
	s_and_b32 s0, s0, 7
	s_movk_i32 s1, 264
	s_cmp_eq_u32 s0, 6
	s_cselect_b32 s1, 330, s1
	s_cmp_lt_u32 s0, 6
	s_cselect_b32 s0, 28, s1
	s_cmp_ge_u32 s25, s0
	s_cbranch_scc1 .LBB0_370
.LBB0_324:
	s_mov_b32 s101, s25
	v_readlane_b32 s0, v238, 16
	s_and_b32 s0, s0, 7
	s_lshr_b32 s1, s25, 2
	s_and_b32 s2, s25, 3
	s_cmp_eq_u32 s0, 7
	s_cselect_b32 s3, 43, 4
	s_add_i32 s2, s2, s3
	s_cmp_lt_u32 s0, 6
	s_cbranch_scc0 .Lsg_67
	s_mul_i32 s1, s0, 11
	s_add_i32 s1, s1, s25
	s_sub_i32 s1, s1, 17
	s_movk_i32 s2, 47
	s_branch .Lsg_map
.Lsg_67:
	s_cmpk_lt_u32 s25, 0x108
	s_cbranch_scc1 .Lsg_map
	s_sub_i32 s1, s25, 0x108
	s_movk_i32 s2, 42
.Lsg_map:
	s_mul_i32 s1, s1, 48
	s_add_i32 s25, s1, s2
	s_lshl_b32 s24, s25, 1
	s_lshl_b32 s23, s25, 7
	s_mul_hi_i32 s0, s25, 0x2aaaaaab
	s_lshr_b32 s1, s0, 31
	s_ashr_i32 s26, s0, 3
	s_add_i32 s26, s26, s1
	s_lshl_b32 s4, s26, 8
	s_mul_i32 s0, s26, 0xffffffd0
	s_ashr_i32 s5, s4, 31
	s_add_i32 s2, s25, s0
	s_lshl_b64 s[0:1], s[4:5], 11
	v_readlane_b32 s78, v241, 26
	v_readlane_b32 s79, v241, 27
	s_add_u32 s6, s78, s0
	s_addc_u32 s7, s79, s1
	s_ashr_i32 s3, s2, 31
	s_lshl_b64 s[0:1], s[2:3], 18
	s_add_u32 s8, s18, s0
	v_mov_b32_e32 v1, v152
	s_addc_u32 s9, s19, s1
	s_cmp_gt_i32 s2, 41
	v_and_b32_e32 v107, 31, v1
	v_bfe_u32 v106, v1, 5, 1
	v_bfe_u32 v108, v1, 6, 2
	v_ashrrev_i32_e32 v0, 8, v1
	s_mov_b64 s[0:1], -1
	s_cbranch_scc0 .LBB0_358
	s_cmp_lg_u32 s2, 42
	s_cbranch_scc0 .LBB0_327
	v_mov_b32_e32 v30, v152
	s_mov_b32 s0, 0x40000
	v_ashrrev_i32_e32 v28, 3, v30
	v_ashrrev_i32_e32 v29, 31, v28
	s_waitcnt vmcnt(3)
	v_lshlrev_b64 v[4:5], 11, v[28:29]
	v_lshlrev_b32_e32 v2, 4, v30
	v_lshl_add_u64 v[6:7], s[6:7], 0, v[4:5]
	v_and_b32_e32 v2, 0x70, v2
	v_lshl_add_u64 v[70:71], v[6:7], 0, v[2:3]
	v_add_co_u32_e32 v72, vcc, s60, v70
	v_lshl_add_u64 v[4:5], s[8:9], 0, v[4:5]
	s_nop 0
	v_addc_co_u32_e32 v73, vcc, 0, v71, vcc
	v_add_co_u32_e32 v74, vcc, s0, v70
	s_mov_b32 s0, 0x60000
	s_nop 0
	v_addc_co_u32_e32 v75, vcc, 0, v71, vcc
	v_add_co_u32_e32 v76, vcc, s0, v70
	v_lshl_add_u64 v[68:69], v[4:5], 0, v[2:3]
	s_nop 0
	v_addc_co_u32_e32 v77, vcc, 0, v71, vcc
	global_load_dwordx4 v[4:7], v[70:71], off
	global_load_dwordx4 v[8:11], v[72:73], off
	global_load_dwordx4 v[12:15], v[74:75], off
	global_load_dwordx4 v[16:19], v[76:77], off
	global_load_dwordx4 v[20:23], v[68:69], off
	v_add_co_u32_e32 v78, vcc, s60, v68
	v_and_b32_e32 v29, 31, v30
	s_nop 0
	v_addc_co_u32_e32 v79, vcc, 0, v69, vcc
	global_load_dwordx4 v[24:27], v[78:79], off
	global_load_dwordx4 v[94:97], v[70:71], off offset:128
	global_load_dwordx4 v[98:101], v[68:69], off offset:128
	global_load_dwordx4 v[102:105], v[72:73], off offset:128
	global_load_dwordx4 v[110:113], v[74:75], off offset:128
	global_load_dwordx4 v[114:117], v[76:77], off offset:128
	global_load_dwordx4 v[118:121], v[78:79], off offset:128
	v_and_b32_e32 v31, 0xdf, v30
	v_lshrrev_b32_e32 v32, 1, v30
	v_lshrrev_b32_e32 v30, 2, v30
	s_mov_b32 s0, 0xfffffc0
	v_and_b32_e32 v85, 16, v32
	v_mul_u32_u24_e32 v83, 0x90, v31
	v_and_or_b32 v29, v30, s0, v29
	v_mad_u64_u32 v[86:87], s[0:1], v28, s57, v[2:3]
	v_add3_u32 v2, v83, v85, 0
	v_add_u32_e32 v80, 0, v86
	v_mul_lo_u32 v92, v29, s57
	v_add_u32_e32 v109, v92, v85
	v_add_u32_e32 v84, 0, v109
	v_or_b32_e32 v150, 32, v85
	v_add3_u32 v82, v83, v150, 0
	v_add_u32_e32 v151, v92, v150
	v_add_u32_e32 v87, 0, v151
	v_or_b32_e32 v153, 64, v85
	v_add3_u32 v81, v83, v153, 0
	v_or_b32_e32 v162, 0x60, v85
	v_add3_u32 v83, v83, v162, 0
	v_add_u32_e32 v163, v92, v162
	v_add_u32_e32 v93, 0, v163
	v_readlane_b32 s0, v238, 25
	s_cmp_lt_u32 s2, 47
	v_readlane_b32 s64, v240, 1
	v_readlane_b32 s82, v241, 30
	v_readlane_b32 s83, v241, 31
	v_readlane_b32 s65, v240, 2
	s_mul_i32 s3, s26, 0xffffe800
	s_mul_hi_i32 s5, s25, 0xa57eb503
	v_readlane_b32 s66, v240, 3
	v_readlane_b32 s67, v240, 4
	s_waitcnt vmcnt(11)
	ds_write_b128 v80, v[4:7]
	s_waitcnt vmcnt(7)
	ds_write_b128 v80, v[20:23] offset:36864
	ds_write_b128 v80, v[8:11] offset:9216
	ds_write_b128 v80, v[12:15] offset:18432
	ds_write_b128 v80, v[16:19] offset:27648
	s_waitcnt vmcnt(6)
	ds_write_b128 v80, v[24:27] offset:46080
	s_waitcnt lgkmcnt(0)
	s_barrier
; #define MFMA32(a, b, c) __builtin_amdgcn_mfma_f32_32x32x16_bf16((a), (b), (c), 0, 0, 0)
; template <bool SWAP, class Epi>
; DI void gemm_tile(const u16* __restrict__ A, int lda, const u16* __restrict__ Bw, int ldb, int K, char* lds, Epi epi) {
;     ...
;   auto compute = [&](int st) {
;     const char* as = lds + st * GEMM_STAGE;
;     const char* bs = as + 36864;
; #pragma unroll
;     for (int ks = 0; ks < 4; ++ks) {
;       bf16x8 af[2], bfr[2];
; #pragma unroll
;       for (int mi = 0; mi < 2; ++mi) af[mi] = *(const bf16x8*)(as + ((wm * 64 + mi * 32 + r) * 72 + ks * 16 + 8 * h) * 2);
; #pragma unroll
;       for (int ni = 0; ni < 2; ++ni) bfr[ni] = *(const bf16x8*)(bs + ((wn * 64 + ni * 32 + r) * 72 + ks * 16 + 8 * h) * 2);
; #pragma unroll
;       for (int mi = 0; mi < 2; ++mi)
; #pragma unroll
;         for (int ni = 0; ni < 2; ++ni) {
;           if (SWAP) acc[mi][ni] = MFMA32(bfr[ni], af[mi], acc[mi][ni]);
;           else acc[mi][ni] = MFMA32(af[mi], bfr[ni], acc[mi][ni]);
;         }
;     }
;   };
;   gload(0, ra0, rb0);
;   lstore(0, ra0, rb0);
;   gload(1, ra1, rb1);
;   __syncthreads();
;   for (int kt = 0; kt < nk; kt += 2) {
;     if (kt + 2 < nk) gload(kt + 2, ra0, rb0);
;     compute(0);
;     lstore(1, ra1, rb1);
;     __syncthreads();
;     if (kt + 3 < nk) gload(kt + 3, ra1, rb1);
;     compute(1);
;     if (kt + 2 < nk) lstore(0, ra0, rb0);
;     __syncthreads();
	ds_read_b128 v[4:7], v2
	ds_read_b128 v[8:11], v84 offset:36864
	ds_read_b128 v[88:91], v2 offset:32
	ds_read_b128 v[12:15], v2 offset:4608
	ds_read_b128 v[16:19], v84 offset:41472
	ds_read_b128 v[122:125], v84 offset:36960
	ds_read_b128 v[138:141], v82 offset:4608
	ds_read_b128 v[142:145], v81 offset:4608
	s_waitcnt lgkmcnt(6)
	v_mfma_f32_32x32x16_bf16 v[52:67], v[4:7], v[8:11], 0
	ds_read_b128 v[126:129], v84 offset:36896
	ds_read_b128 v[130:133], v84 offset:36928
	ds_read_b128 v[134:137], v87 offset:41472
	s_waitcnt lgkmcnt(7)
	v_mfma_f32_32x32x16_bf16 v[20:35], v[12:15], v[8:11], 0
	s_waitcnt lgkmcnt(6)
	v_mfma_f32_32x32x16_bf16 v[36:51], v[4:7], v[16:19], 0
	v_mfma_f32_32x32x16_bf16 v[4:19], v[12:15], v[16:19], 0
	s_waitcnt lgkmcnt(2)
	v_mfma_f32_32x32x16_bf16 v[52:67], v[88:91], v[126:129], v[52:67]
	v_mfma_f32_32x32x16_bf16 v[20:35], v[138:141], v[126:129], v[20:35]
	ds_read_b128 v[126:129], v2 offset:64
	s_waitcnt lgkmcnt(1)
	v_mfma_f32_32x32x16_bf16 v[36:51], v[88:91], v[134:137], v[36:51]
	v_add_u32_e32 v88, v92, v153
	v_add_u32_e32 v90, 0, v88
	v_add_u32_e32 v89, s0, v86
	v_add_u32_e32 v91, s59, v86
	v_add_u32_e32 v88, s59, v88
	s_cselect_b64 s[0:1], -1, 0
	s_and_b64 s[10:11], s[0:1], exec
	v_mfma_f32_32x32x16_bf16 v[4:19], v[138:141], v[134:137], v[4:19]
	ds_read_b128 v[138:141], v90 offset:41472
	ds_read_b128 v[134:137], v2 offset:96
	s_cselect_b32 s11, s83, s65
	s_cselect_b32 s10, s82, s64
	s_add_i32 s3, s23, s3
	s_addk_i32 s3, 0xea80
	s_and_b64 s[12:13], s[0:1], exec
	s_waitcnt lgkmcnt(2)
	v_mfma_f32_32x32x16_bf16 v[52:67], v[126:129], v[130:133], v[52:67]
	s_cselect_b32 s3, s3, 0
	s_add_i32 s5, s5, s25
	s_lshr_b32 s12, s5, 31
	s_ashr_i32 s5, s5, 10
	s_add_i32 s12, s5, s12
	s_mul_i32 s5, s12, 0xffffdf00
	s_add_i32 s5, s5, s4
	v_mfma_f32_32x32x16_bf16 v[20:35], v[142:145], v[130:133], v[20:35]
	ds_read_b128 v[130:133], v83 offset:4608
	s_ashr_i32 s13, s12, 31
	s_and_b64 s[0:1], s[0:1], exec
	s_cselect_b32 s0, 9, 7
	s_lshl_b64 s[0:1], s[12:13], s0
	s_movk_i32 s12, 0x4200
	s_waitcnt lgkmcnt(2)
	v_mfma_f32_32x32x16_bf16 v[36:51], v[126:129], v[138:141], v[36:51]
	ds_read_b128 v[126:129], v93 offset:41472
	v_mfma_f32_32x32x16_bf16 v[4:19], v[142:145], v[138:141], v[4:19]
	s_waitcnt lgkmcnt(2)
	v_mfma_f32_32x32x16_bf16 v[52:67], v[134:137], v[122:125], v[52:67]
	s_waitcnt lgkmcnt(0)
	v_mfma_f32_32x32x16_bf16 v[36:51], v[134:137], v[126:129], v[36:51]
	v_mfma_f32_32x32x16_bf16 v[20:35], v[130:133], v[122:125], v[20:35]
	global_load_dwordx4 v[122:125], v[70:71], off offset:256
	global_load_dwordx4 v[134:137], v[72:73], off offset:256
	global_load_dwordx4 v[138:141], v[74:75], off offset:256
	global_load_dwordx4 v[142:145], v[76:77], off offset:256
	global_load_dwordx4 v[146:149], v[68:69], off offset:256
	global_load_dwordx4 v[158:161], v[78:79], off offset:256
	s_waitcnt vmcnt(11)
	ds_write_b128 v80, v[94:97] offset:55296
	s_waitcnt vmcnt(9)
	ds_write_b128 v80, v[102:105] offset:64512
	s_waitcnt vmcnt(8)
	ds_write_b128 v89, v[110:113] offset:18432
	s_waitcnt vmcnt(7)
	ds_write_b128 v89, v[114:117] offset:27648
	ds_write_b128 v91, v[98:101]
	s_waitcnt vmcnt(6)
	ds_write_b128 v91, v[118:121] offset:9216
	s_waitcnt lgkmcnt(0)
	s_barrier
	ds_read_b128 v[98:101], v2 offset:55296
	v_add_u32_e32 v96, s59, v109
	v_add_u32_e32 v95, 0x1200, v92
	ds_read_b128 v[102:105], v96
	v_add3_u32 v97, v95, v85, s59
	ds_read_b128 v[110:113], v97
	ds_read_b128 v[114:117], v2 offset:55328
	v_mfma_f32_32x32x16_bf16 v[4:19], v[130:133], v[126:129], v[4:19]
	v_add_u32_e32 v85, s59, v151
	v_add3_u32 v86, v95, v150, s59
	v_add3_u32 v92, v95, v153, s59
	v_add_u32_e32 v94, s59, v163
	v_add3_u32 v95, v95, v162, s59
	s_waitcnt lgkmcnt(2)
	v_mfma_f32_32x32x16_bf16 v[52:67], v[98:101], v[102:105], v[52:67]
	s_waitcnt lgkmcnt(1)
	v_mfma_f32_32x32x16_bf16 v[36:51], v[98:101], v[110:113], v[36:51]
	ds_read_b128 v[98:101], v2 offset:59904
	ds_read_b128 v[118:121], v82 offset:59904
	s_waitcnt lgkmcnt(1)
	v_mfma_f32_32x32x16_bf16 v[20:35], v[98:101], v[102:105], v[20:35]
	ds_read_b128 v[102:105], v86
	v_mfma_f32_32x32x16_bf16 v[4:19], v[98:101], v[110:113], v[4:19]
	ds_read_b128 v[98:101], v85
	s_waitcnt lgkmcnt(0)
	v_mfma_f32_32x32x16_bf16 v[52:67], v[114:117], v[98:101], v[52:67]
	v_mfma_f32_32x32x16_bf16 v[20:35], v[118:121], v[98:101], v[20:35]
	ds_read_b128 v[98:101], v2 offset:55360
	v_mfma_f32_32x32x16_bf16 v[36:51], v[114:117], v[102:105], v[36:51]
	v_mfma_f32_32x32x16_bf16 v[4:19], v[118:121], v[102:105], v[4:19]
	ds_read_b128 v[102:105], v88
	ds_read_b128 v[110:113], v92
	ds_read_b128 v[114:117], v2 offset:55392
	s_waitcnt lgkmcnt(2)
	v_mfma_f32_32x32x16_bf16 v[52:67], v[98:101], v[102:105], v[52:67]
	s_waitcnt lgkmcnt(1)
	v_mfma_f32_32x32x16_bf16 v[36:51], v[98:101], v[110:113], v[36:51]
	ds_read_b128 v[98:101], v81 offset:59904
	ds_read_b128 v[118:121], v83 offset:59904
	s_waitcnt lgkmcnt(1)
	v_mfma_f32_32x32x16_bf16 v[20:35], v[98:101], v[102:105], v[20:35]
	ds_read_b128 v[102:105], v95
	v_mfma_f32_32x32x16_bf16 v[4:19], v[98:101], v[110:113], v[4:19]
	ds_read_b128 v[98:101], v94
	s_waitcnt lgkmcnt(0)
	v_mfma_f32_32x32x16_bf16 v[52:67], v[114:117], v[98:101], v[52:67]
	v_mfma_f32_32x32x16_bf16 v[36:51], v[114:117], v[102:105], v[36:51]
	v_mfma_f32_32x32x16_bf16 v[20:35], v[118:121], v[98:101], v[20:35]
	global_load_dwordx4 v[98:101], v[70:71], off offset:384
	global_load_dwordx4 v[110:113], v[72:73], off offset:384
	global_load_dwordx4 v[114:117], v[74:75], off offset:384
	global_load_dwordx4 v[126:129], v[76:77], off offset:384
	global_load_dwordx4 v[130:133], v[68:69], off offset:384
	global_load_dwordx4 v[162:165], v[78:79], off offset:384
	s_waitcnt vmcnt(11)
	ds_write_b128 v80, v[122:125]
	s_waitcnt vmcnt(10)
	ds_write_b128 v80, v[134:137] offset:9216
	s_waitcnt vmcnt(9)
	ds_write_b128 v80, v[138:141] offset:18432
	s_waitcnt vmcnt(8)
	ds_write_b128 v80, v[142:145] offset:27648
	s_waitcnt vmcnt(7)
	ds_write_b128 v80, v[146:149] offset:36864
	s_waitcnt vmcnt(6)
	ds_write_b128 v80, v[158:161] offset:46080
	s_waitcnt lgkmcnt(0)
	s_barrier
; #define MFMA32(a, b, c) __builtin_amdgcn_mfma_f32_32x32x16_bf16((a), (b), (c), 0, 0, 0)
; template <bool SWAP, class Epi>
; DI void gemm_tile(const u16* __restrict__ A, int lda, const u16* __restrict__ Bw, int ldb, int K, char* lds, Epi epi) {
;     ...
;   auto compute = [&](int st) {
;     const char* as = lds + st * GEMM_STAGE;
;     const char* bs = as + 36864;
; #pragma unroll
;     for (int ks = 0; ks < 4; ++ks) {
;       bf16x8 af[2], bfr[2];
; #pragma unroll
;       for (int mi = 0; mi < 2; ++mi) af[mi] = *(const bf16x8*)(as + ((wm * 64 + mi * 32 + r) * 72 + ks * 16 + 8 * h) * 2);
; #pragma unroll
;       for (int ni = 0; ni < 2; ++ni) bfr[ni] = *(const bf16x8*)(bs + ((wn * 64 + ni * 32 + r) * 72 + ks * 16 + 8 * h) * 2);
; #pragma unroll
;       for (int mi = 0; mi < 2; ++mi)
; #pragma unroll
;         for (int ni = 0; ni < 2; ++ni) {
;           if (SWAP) acc[mi][ni] = MFMA32(bfr[ni], af[mi], acc[mi][ni]);
;           else acc[mi][ni] = MFMA32(af[mi], bfr[ni], acc[mi][ni]);
;         }
;     }
;   };
;   gload(0, ra0, rb0);
;   lstore(0, ra0, rb0);
;   gload(1, ra1, rb1);
;   __syncthreads();
;   for (int kt = 0; kt < nk; kt += 2) {
;     if (kt + 2 < nk) gload(kt + 2, ra0, rb0);
;     compute(0);
;     lstore(1, ra1, rb1);
;     __syncthreads();
;     if (kt + 3 < nk) gload(kt + 3, ra1, rb1);
;     compute(1);
;     if (kt + 2 < nk) lstore(0, ra0, rb0);
;     __syncthreads();
	v_mfma_f32_32x32x16_bf16 v[4:19], v[118:121], v[102:105], v[4:19]
	ds_read_b128 v[102:105], v2
	ds_read_b128 v[118:121], v84 offset:36864
	ds_read_b128 v[122:125], v2 offset:32
	ds_read_b128 v[134:137], v2 offset:4608
	ds_read_b128 v[138:141], v84 offset:41472
	ds_read_b128 v[142:145], v84 offset:36960
	s_waitcnt lgkmcnt(4)
	v_mfma_f32_32x32x16_bf16 v[52:67], v[102:105], v[118:121], v[52:67]
	s_waitcnt lgkmcnt(1)
	v_mfma_f32_32x32x16_bf16 v[36:51], v[102:105], v[138:141], v[36:51]
	v_mfma_f32_32x32x16_bf16 v[20:35], v[134:137], v[118:121], v[20:35]
	ds_read_b128 v[102:105], v84 offset:36896
	ds_read_b128 v[118:121], v84 offset:36928
	v_mfma_f32_32x32x16_bf16 v[4:19], v[134:137], v[138:141], v[4:19]
	ds_read_b128 v[134:137], v87 offset:41472
	ds_read_b128 v[138:141], v82 offset:4608
	s_waitcnt lgkmcnt(3)
	v_mfma_f32_32x32x16_bf16 v[52:67], v[122:125], v[102:105], v[52:67]
	s_waitcnt lgkmcnt(1)
	v_mfma_f32_32x32x16_bf16 v[36:51], v[122:125], v[134:137], v[36:51]
	s_waitcnt lgkmcnt(0)
	v_mfma_f32_32x32x16_bf16 v[20:35], v[138:141], v[102:105], v[20:35]
	ds_read_b128 v[102:105], v2 offset:64
	ds_read_b128 v[122:125], v2 offset:96
	v_mfma_f32_32x32x16_bf16 v[4:19], v[138:141], v[134:137], v[4:19]
	ds_read_b128 v[134:137], v90 offset:41472
	ds_read_b128 v[138:141], v81 offset:4608
	s_waitcnt lgkmcnt(3)
	v_mfma_f32_32x32x16_bf16 v[52:67], v[102:105], v[118:121], v[52:67]
	s_waitcnt lgkmcnt(1)
	v_mfma_f32_32x32x16_bf16 v[36:51], v[102:105], v[134:137], v[36:51]
	s_waitcnt lgkmcnt(0)
	v_mfma_f32_32x32x16_bf16 v[20:35], v[138:141], v[118:121], v[20:35]
	ds_read_b128 v[102:105], v93 offset:41472
	ds_read_b128 v[118:121], v83 offset:4608
	v_mfma_f32_32x32x16_bf16 v[4:19], v[138:141], v[134:137], v[4:19]
	v_mfma_f32_32x32x16_bf16 v[52:67], v[122:125], v[142:145], v[52:67]
	s_waitcnt lgkmcnt(1)
	v_mfma_f32_32x32x16_bf16 v[36:51], v[122:125], v[102:105], v[36:51]
	s_waitcnt lgkmcnt(0)
	v_mfma_f32_32x32x16_bf16 v[20:35], v[118:121], v[142:145], v[20:35]
	global_load_dwordx4 v[122:125], v[70:71], off offset:512
	global_load_dwordx4 v[134:137], v[72:73], off offset:512
	global_load_dwordx4 v[138:141], v[74:75], off offset:512
	global_load_dwordx4 v[142:145], v[76:77], off offset:512
	global_load_dwordx4 v[146:149], v[68:69], off offset:512
	global_load_dwordx4 v[158:161], v[78:79], off offset:512
	s_waitcnt vmcnt(11)
	ds_write_b128 v80, v[98:101] offset:55296
	s_waitcnt vmcnt(10)
	ds_write_b128 v80, v[110:113] offset:64512
	s_waitcnt vmcnt(9)
	ds_write_b128 v89, v[114:117] offset:18432
	s_waitcnt vmcnt(8)
	ds_write_b128 v89, v[126:129] offset:27648
	s_waitcnt vmcnt(7)
	ds_write_b128 v91, v[130:133]
	s_waitcnt vmcnt(6)
	ds_write_b128 v91, v[162:165] offset:9216
	s_waitcnt lgkmcnt(0)
	s_barrier
	v_mfma_f32_32x32x16_bf16 v[4:19], v[118:121], v[102:105], v[4:19]
	ds_read_b128 v[98:101], v2 offset:55296
	ds_read_b128 v[102:105], v96
	ds_read_b128 v[110:113], v97
	ds_read_b128 v[114:117], v2 offset:55328
	s_waitcnt lgkmcnt(2)
	v_mfma_f32_32x32x16_bf16 v[52:67], v[98:101], v[102:105], v[52:67]
	s_waitcnt lgkmcnt(1)
	v_mfma_f32_32x32x16_bf16 v[36:51], v[98:101], v[110:113], v[36:51]
	ds_read_b128 v[98:101], v2 offset:59904
	ds_read_b128 v[118:121], v82 offset:59904
	s_waitcnt lgkmcnt(1)
	v_mfma_f32_32x32x16_bf16 v[20:35], v[98:101], v[102:105], v[20:35]
	v_mfma_f32_32x32x16_bf16 v[4:19], v[98:101], v[110:113], v[4:19]
	ds_read_b128 v[98:101], v85
	ds_read_b128 v[102:105], v86
	s_waitcnt lgkmcnt(1)
	v_mfma_f32_32x32x16_bf16 v[52:67], v[114:117], v[98:101], v[52:67]
	s_waitcnt lgkmcnt(0)
	v_mfma_f32_32x32x16_bf16 v[36:51], v[114:117], v[102:105], v[36:51]
	v_mfma_f32_32x32x16_bf16 v[20:35], v[118:121], v[98:101], v[20:35]
	v_mfma_f32_32x32x16_bf16 v[4:19], v[118:121], v[102:105], v[4:19]
	ds_read_b128 v[98:101], v2 offset:55360
	ds_read_b128 v[102:105], v88
	ds_read_b128 v[110:113], v92
	ds_read_b128 v[114:117], v2 offset:55392
	s_waitcnt lgkmcnt(2)
	v_mfma_f32_32x32x16_bf16 v[52:67], v[98:101], v[102:105], v[52:67]
	s_waitcnt lgkmcnt(1)
	v_mfma_f32_32x32x16_bf16 v[36:51], v[98:101], v[110:113], v[36:51]
	ds_read_b128 v[98:101], v81 offset:59904
	ds_read_b128 v[118:121], v83 offset:59904
	s_waitcnt lgkmcnt(1)
	v_mfma_f32_32x32x16_bf16 v[20:35], v[98:101], v[102:105], v[20:35]
	v_mfma_f32_32x32x16_bf16 v[4:19], v[98:101], v[110:113], v[4:19]
	ds_read_b128 v[98:101], v94
	ds_read_b128 v[102:105], v95
	s_waitcnt lgkmcnt(1)
	v_mfma_f32_32x32x16_bf16 v[52:67], v[114:117], v[98:101], v[52:67]
	s_waitcnt lgkmcnt(0)
	v_mfma_f32_32x32x16_bf16 v[36:51], v[114:117], v[102:105], v[36:51]
	v_mfma_f32_32x32x16_bf16 v[20:35], v[118:121], v[98:101], v[20:35]
	global_load_dwordx4 v[98:101], v[70:71], off offset:640
	global_load_dwordx4 v[110:113], v[72:73], off offset:640
	global_load_dwordx4 v[114:117], v[74:75], off offset:640
	global_load_dwordx4 v[126:129], v[76:77], off offset:640
	global_load_dwordx4 v[130:133], v[68:69], off offset:640
	global_load_dwordx4 v[162:165], v[78:79], off offset:640
	s_waitcnt vmcnt(11)
	ds_write_b128 v80, v[122:125]
	s_waitcnt vmcnt(10)
	ds_write_b128 v80, v[134:137] offset:9216
	s_waitcnt vmcnt(9)
	ds_write_b128 v80, v[138:141] offset:18432
	s_waitcnt vmcnt(8)
	ds_write_b128 v80, v[142:145] offset:27648
	s_waitcnt vmcnt(7)
	ds_write_b128 v80, v[146:149] offset:36864
	s_waitcnt vmcnt(6)
	ds_write_b128 v80, v[158:161] offset:46080
	s_waitcnt lgkmcnt(0)
	s_barrier
; #define MFMA32(a, b, c) __builtin_amdgcn_mfma_f32_32x32x16_bf16((a), (b), (c), 0, 0, 0)
; template <bool SWAP, class Epi>
; DI void gemm_tile(const u16* __restrict__ A, int lda, const u16* __restrict__ Bw, int ldb, int K, char* lds, Epi epi) {
;     ...
;   auto compute = [&](int st) {
;     const char* as = lds + st * GEMM_STAGE;
;     const char* bs = as + 36864;
; #pragma unroll
;     for (int ks = 0; ks < 4; ++ks) {
;       bf16x8 af[2], bfr[2];
; #pragma unroll
;       for (int mi = 0; mi < 2; ++mi) af[mi] = *(const bf16x8*)(as + ((wm * 64 + mi * 32 + r) * 72 + ks * 16 + 8 * h) * 2);
; #pragma unroll
;       for (int ni = 0; ni < 2; ++ni) bfr[ni] = *(const bf16x8*)(bs + ((wn * 64 + ni * 32 + r) * 72 + ks * 16 + 8 * h) * 2);
; #pragma unroll
;       for (int mi = 0; mi < 2; ++mi)
; #pragma unroll
;         for (int ni = 0; ni < 2; ++ni) {
;           if (SWAP) acc[mi][ni] = MFMA32(bfr[ni], af[mi], acc[mi][ni]);
;           else acc[mi][ni] = MFMA32(af[mi], bfr[ni], acc[mi][ni]);
;         }
;     }
;   };
;   gload(0, ra0, rb0);
;   lstore(0, ra0, rb0);
;   gload(1, ra1, rb1);
;   __syncthreads();
;   for (int kt = 0; kt < nk; kt += 2) {
;     if (kt + 2 < nk) gload(kt + 2, ra0, rb0);
;     compute(0);
;     lstore(1, ra1, rb1);
;     __syncthreads();
;     if (kt + 3 < nk) gload(kt + 3, ra1, rb1);
;     compute(1);
;     if (kt + 2 < nk) lstore(0, ra0, rb0);
;     __syncthreads();
	v_mfma_f32_32x32x16_bf16 v[4:19], v[118:121], v[102:105], v[4:19]
	ds_read_b128 v[102:105], v2
	ds_read_b128 v[118:121], v84 offset:36864
	ds_read_b128 v[122:125], v2 offset:32
	ds_read_b128 v[134:137], v2 offset:4608
	ds_read_b128 v[138:141], v84 offset:41472
	ds_read_b128 v[142:145], v84 offset:36960
	s_waitcnt lgkmcnt(4)
	v_mfma_f32_32x32x16_bf16 v[52:67], v[102:105], v[118:121], v[52:67]
	s_waitcnt lgkmcnt(1)
	v_mfma_f32_32x32x16_bf16 v[36:51], v[102:105], v[138:141], v[36:51]
	v_mfma_f32_32x32x16_bf16 v[20:35], v[134:137], v[118:121], v[20:35]
	ds_read_b128 v[102:105], v84 offset:36896
	ds_read_b128 v[118:121], v84 offset:36928
	v_mfma_f32_32x32x16_bf16 v[4:19], v[134:137], v[138:141], v[4:19]
	ds_read_b128 v[134:137], v87 offset:41472
	ds_read_b128 v[138:141], v82 offset:4608
	s_waitcnt lgkmcnt(3)
	v_mfma_f32_32x32x16_bf16 v[52:67], v[122:125], v[102:105], v[52:67]
	s_waitcnt lgkmcnt(1)
	v_mfma_f32_32x32x16_bf16 v[36:51], v[122:125], v[134:137], v[36:51]
	s_waitcnt lgkmcnt(0)
	v_mfma_f32_32x32x16_bf16 v[20:35], v[138:141], v[102:105], v[20:35]
	ds_read_b128 v[102:105], v2 offset:64
	ds_read_b128 v[122:125], v2 offset:96
	v_mfma_f32_32x32x16_bf16 v[4:19], v[138:141], v[134:137], v[4:19]
	ds_read_b128 v[134:137], v90 offset:41472
	ds_read_b128 v[138:141], v81 offset:4608
	s_waitcnt lgkmcnt(3)
	v_mfma_f32_32x32x16_bf16 v[52:67], v[102:105], v[118:121], v[52:67]
	s_waitcnt lgkmcnt(1)
	v_mfma_f32_32x32x16_bf16 v[36:51], v[102:105], v[134:137], v[36:51]
	s_waitcnt lgkmcnt(0)
	v_mfma_f32_32x32x16_bf16 v[20:35], v[138:141], v[118:121], v[20:35]
	ds_read_b128 v[102:105], v93 offset:41472
	ds_read_b128 v[118:121], v83 offset:4608
	v_mfma_f32_32x32x16_bf16 v[4:19], v[138:141], v[134:137], v[4:19]
	v_mfma_f32_32x32x16_bf16 v[52:67], v[122:125], v[142:145], v[52:67]
	s_waitcnt lgkmcnt(1)
	v_mfma_f32_32x32x16_bf16 v[36:51], v[122:125], v[102:105], v[36:51]
	s_waitcnt lgkmcnt(0)
	v_mfma_f32_32x32x16_bf16 v[20:35], v[118:121], v[142:145], v[20:35]
	global_load_dwordx4 v[122:125], v[70:71], off offset:768
	global_load_dwordx4 v[134:137], v[72:73], off offset:768
	global_load_dwordx4 v[138:141], v[74:75], off offset:768
	global_load_dwordx4 v[142:145], v[76:77], off offset:768
	global_load_dwordx4 v[146:149], v[68:69], off offset:768
	global_load_dwordx4 v[158:161], v[78:79], off offset:768
	s_waitcnt vmcnt(11)
	ds_write_b128 v80, v[98:101] offset:55296
	s_waitcnt vmcnt(10)
	ds_write_b128 v80, v[110:113] offset:64512
	s_waitcnt vmcnt(9)
	ds_write_b128 v89, v[114:117] offset:18432
	s_waitcnt vmcnt(8)
	ds_write_b128 v89, v[126:129] offset:27648
	s_waitcnt vmcnt(7)
	ds_write_b128 v91, v[130:133]
	s_waitcnt vmcnt(6)
	ds_write_b128 v91, v[162:165] offset:9216
	s_waitcnt lgkmcnt(0)
	s_barrier
	v_mfma_f32_32x32x16_bf16 v[4:19], v[118:121], v[102:105], v[4:19]
	ds_read_b128 v[98:101], v2 offset:55296
	ds_read_b128 v[102:105], v96
	ds_read_b128 v[110:113], v97
	ds_read_b128 v[114:117], v2 offset:55328
	s_waitcnt lgkmcnt(2)
	v_mfma_f32_32x32x16_bf16 v[52:67], v[98:101], v[102:105], v[52:67]
	s_waitcnt lgkmcnt(1)
	v_mfma_f32_32x32x16_bf16 v[36:51], v[98:101], v[110:113], v[36:51]
	ds_read_b128 v[98:101], v2 offset:59904
	ds_read_b128 v[118:121], v82 offset:59904
	s_waitcnt lgkmcnt(1)
	v_mfma_f32_32x32x16_bf16 v[20:35], v[98:101], v[102:105], v[20:35]
	v_mfma_f32_32x32x16_bf16 v[4:19], v[98:101], v[110:113], v[4:19]
	ds_read_b128 v[98:101], v85
	ds_read_b128 v[102:105], v86
	s_waitcnt lgkmcnt(1)
	v_mfma_f32_32x32x16_bf16 v[52:67], v[114:117], v[98:101], v[52:67]
	s_waitcnt lgkmcnt(0)
	v_mfma_f32_32x32x16_bf16 v[36:51], v[114:117], v[102:105], v[36:51]
	v_mfma_f32_32x32x16_bf16 v[20:35], v[118:121], v[98:101], v[20:35]
	v_mfma_f32_32x32x16_bf16 v[4:19], v[118:121], v[102:105], v[4:19]
	ds_read_b128 v[98:101], v2 offset:55360
	ds_read_b128 v[102:105], v88
	ds_read_b128 v[110:113], v92
	ds_read_b128 v[114:117], v2 offset:55392
	s_waitcnt lgkmcnt(2)
	v_mfma_f32_32x32x16_bf16 v[52:67], v[98:101], v[102:105], v[52:67]
	s_waitcnt lgkmcnt(1)
	v_mfma_f32_32x32x16_bf16 v[36:51], v[98:101], v[110:113], v[36:51]
	ds_read_b128 v[98:101], v81 offset:59904
	ds_read_b128 v[118:121], v83 offset:59904
	s_waitcnt lgkmcnt(1)
	v_mfma_f32_32x32x16_bf16 v[20:35], v[98:101], v[102:105], v[20:35]
	v_mfma_f32_32x32x16_bf16 v[4:19], v[98:101], v[110:113], v[4:19]
	ds_read_b128 v[98:101], v94
	ds_read_b128 v[102:105], v95
	s_waitcnt lgkmcnt(1)
	v_mfma_f32_32x32x16_bf16 v[52:67], v[114:117], v[98:101], v[52:67]
	s_waitcnt lgkmcnt(0)
	v_mfma_f32_32x32x16_bf16 v[36:51], v[114:117], v[102:105], v[36:51]
	v_mfma_f32_32x32x16_bf16 v[20:35], v[118:121], v[98:101], v[20:35]
	global_load_dwordx4 v[98:101], v[70:71], off offset:896
	global_load_dwordx4 v[110:113], v[72:73], off offset:896
	global_load_dwordx4 v[114:117], v[74:75], off offset:896
	global_load_dwordx4 v[126:129], v[76:77], off offset:896
	global_load_dwordx4 v[130:133], v[68:69], off offset:896
	global_load_dwordx4 v[162:165], v[78:79], off offset:896
	s_waitcnt vmcnt(11)
	ds_write_b128 v80, v[122:125]
	s_waitcnt vmcnt(10)
	ds_write_b128 v80, v[134:137] offset:9216
	s_waitcnt vmcnt(9)
	ds_write_b128 v80, v[138:141] offset:18432
	s_waitcnt vmcnt(8)
	ds_write_b128 v80, v[142:145] offset:27648
	s_waitcnt vmcnt(7)
	ds_write_b128 v80, v[146:149] offset:36864
	s_waitcnt vmcnt(6)
	ds_write_b128 v80, v[158:161] offset:46080
	s_waitcnt lgkmcnt(0)
	s_barrier
; #define MFMA32(a, b, c) __builtin_amdgcn_mfma_f32_32x32x16_bf16((a), (b), (c), 0, 0, 0)
; template <bool SWAP, class Epi>
; DI void gemm_tile(const u16* __restrict__ A, int lda, const u16* __restrict__ Bw, int ldb, int K, char* lds, Epi epi) {
;     ...
;   auto compute = [&](int st) {
;     const char* as = lds + st * GEMM_STAGE;
;     const char* bs = as + 36864;
; #pragma unroll
;     for (int ks = 0; ks < 4; ++ks) {
;       bf16x8 af[2], bfr[2];
; #pragma unroll
;       for (int mi = 0; mi < 2; ++mi) af[mi] = *(const bf16x8*)(as + ((wm * 64 + mi * 32 + r) * 72 + ks * 16 + 8 * h) * 2);
; #pragma unroll
;       for (int ni = 0; ni < 2; ++ni) bfr[ni] = *(const bf16x8*)(bs + ((wn * 64 + ni * 32 + r) * 72 + ks * 16 + 8 * h) * 2);
; #pragma unroll
;       for (int mi = 0; mi < 2; ++mi)
; #pragma unroll
;         for (int ni = 0; ni < 2; ++ni) {
;           if (SWAP) acc[mi][ni] = MFMA32(bfr[ni], af[mi], acc[mi][ni]);
;           else acc[mi][ni] = MFMA32(af[mi], bfr[ni], acc[mi][ni]);
;         }
;     }
;   };
;   gload(0, ra0, rb0);
;   lstore(0, ra0, rb0);
;   gload(1, ra1, rb1);
;   __syncthreads();
;   for (int kt = 0; kt < nk; kt += 2) {
;     if (kt + 2 < nk) gload(kt + 2, ra0, rb0);
;     compute(0);
;     lstore(1, ra1, rb1);
;     __syncthreads();
;     if (kt + 3 < nk) gload(kt + 3, ra1, rb1);
;     compute(1);
;     if (kt + 2 < nk) lstore(0, ra0, rb0);
;     __syncthreads();
	v_mfma_f32_32x32x16_bf16 v[4:19], v[118:121], v[102:105], v[4:19]
	ds_read_b128 v[102:105], v2
	ds_read_b128 v[118:121], v84 offset:36864
	ds_read_b128 v[122:125], v2 offset:32
	ds_read_b128 v[134:137], v2 offset:4608
	ds_read_b128 v[138:141], v84 offset:41472
	ds_read_b128 v[142:145], v84 offset:36960
	s_waitcnt lgkmcnt(4)
	v_mfma_f32_32x32x16_bf16 v[52:67], v[102:105], v[118:121], v[52:67]
	s_waitcnt lgkmcnt(1)
	v_mfma_f32_32x32x16_bf16 v[36:51], v[102:105], v[138:141], v[36:51]
	v_mfma_f32_32x32x16_bf16 v[20:35], v[134:137], v[118:121], v[20:35]
	ds_read_b128 v[102:105], v84 offset:36896
	ds_read_b128 v[118:121], v84 offset:36928
	v_mfma_f32_32x32x16_bf16 v[4:19], v[134:137], v[138:141], v[4:19]
	ds_read_b128 v[134:137], v87 offset:41472
	ds_read_b128 v[138:141], v82 offset:4608
	s_waitcnt lgkmcnt(3)
	v_mfma_f32_32x32x16_bf16 v[52:67], v[122:125], v[102:105], v[52:67]
	s_waitcnt lgkmcnt(1)
	v_mfma_f32_32x32x16_bf16 v[36:51], v[122:125], v[134:137], v[36:51]
	s_waitcnt lgkmcnt(0)
	v_mfma_f32_32x32x16_bf16 v[20:35], v[138:141], v[102:105], v[20:35]
	ds_read_b128 v[102:105], v2 offset:64
	ds_read_b128 v[122:125], v2 offset:96
	v_mfma_f32_32x32x16_bf16 v[4:19], v[138:141], v[134:137], v[4:19]
	ds_read_b128 v[134:137], v90 offset:41472
	ds_read_b128 v[138:141], v81 offset:4608
	s_waitcnt lgkmcnt(3)
	v_mfma_f32_32x32x16_bf16 v[52:67], v[102:105], v[118:121], v[52:67]
	s_waitcnt lgkmcnt(1)
	v_mfma_f32_32x32x16_bf16 v[36:51], v[102:105], v[134:137], v[36:51]
	s_waitcnt lgkmcnt(0)
	v_mfma_f32_32x32x16_bf16 v[20:35], v[138:141], v[118:121], v[20:35]
	ds_read_b128 v[102:105], v93 offset:41472
	ds_read_b128 v[118:121], v83 offset:4608
	v_mfma_f32_32x32x16_bf16 v[4:19], v[138:141], v[134:137], v[4:19]
	v_mfma_f32_32x32x16_bf16 v[52:67], v[122:125], v[142:145], v[52:67]
	s_waitcnt lgkmcnt(1)
	v_mfma_f32_32x32x16_bf16 v[36:51], v[122:125], v[102:105], v[36:51]
	s_waitcnt lgkmcnt(0)
	v_mfma_f32_32x32x16_bf16 v[20:35], v[118:121], v[142:145], v[20:35]
	global_load_dwordx4 v[122:125], v[70:71], off offset:1024
	global_load_dwordx4 v[134:137], v[72:73], off offset:1024
	global_load_dwordx4 v[138:141], v[74:75], off offset:1024
	global_load_dwordx4 v[142:145], v[76:77], off offset:1024
	global_load_dwordx4 v[146:149], v[68:69], off offset:1024
	global_load_dwordx4 v[158:161], v[78:79], off offset:1024
	s_waitcnt vmcnt(11)
	ds_write_b128 v80, v[98:101] offset:55296
	s_waitcnt vmcnt(10)
	ds_write_b128 v80, v[110:113] offset:64512
	s_waitcnt vmcnt(9)
	ds_write_b128 v89, v[114:117] offset:18432
	s_waitcnt vmcnt(8)
	ds_write_b128 v89, v[126:129] offset:27648
	s_waitcnt vmcnt(7)
	ds_write_b128 v91, v[130:133]
	s_waitcnt vmcnt(6)
	ds_write_b128 v91, v[162:165] offset:9216
	s_waitcnt lgkmcnt(0)
	s_barrier
	v_mfma_f32_32x32x16_bf16 v[4:19], v[118:121], v[102:105], v[4:19]
	ds_read_b128 v[98:101], v2 offset:55296
	ds_read_b128 v[102:105], v96
	ds_read_b128 v[110:113], v97
	ds_read_b128 v[114:117], v2 offset:55328
	s_waitcnt lgkmcnt(2)
	v_mfma_f32_32x32x16_bf16 v[52:67], v[98:101], v[102:105], v[52:67]
	s_waitcnt lgkmcnt(1)
	v_mfma_f32_32x32x16_bf16 v[36:51], v[98:101], v[110:113], v[36:51]
	ds_read_b128 v[98:101], v2 offset:59904
	ds_read_b128 v[118:121], v82 offset:59904
	s_waitcnt lgkmcnt(1)
	v_mfma_f32_32x32x16_bf16 v[20:35], v[98:101], v[102:105], v[20:35]
	v_mfma_f32_32x32x16_bf16 v[4:19], v[98:101], v[110:113], v[4:19]
	ds_read_b128 v[98:101], v85
	ds_read_b128 v[102:105], v86
	s_waitcnt lgkmcnt(1)
	v_mfma_f32_32x32x16_bf16 v[52:67], v[114:117], v[98:101], v[52:67]
	s_waitcnt lgkmcnt(0)
	v_mfma_f32_32x32x16_bf16 v[36:51], v[114:117], v[102:105], v[36:51]
	v_mfma_f32_32x32x16_bf16 v[20:35], v[118:121], v[98:101], v[20:35]
	v_mfma_f32_32x32x16_bf16 v[4:19], v[118:121], v[102:105], v[4:19]
	ds_read_b128 v[98:101], v2 offset:55360
	ds_read_b128 v[102:105], v88
	ds_read_b128 v[110:113], v92
	ds_read_b128 v[114:117], v2 offset:55392
	s_waitcnt lgkmcnt(2)
	v_mfma_f32_32x32x16_bf16 v[52:67], v[98:101], v[102:105], v[52:67]
	s_waitcnt lgkmcnt(1)
	v_mfma_f32_32x32x16_bf16 v[36:51], v[98:101], v[110:113], v[36:51]
	ds_read_b128 v[98:101], v81 offset:59904
	ds_read_b128 v[118:121], v83 offset:59904
	s_waitcnt lgkmcnt(1)
	v_mfma_f32_32x32x16_bf16 v[20:35], v[98:101], v[102:105], v[20:35]
	v_mfma_f32_32x32x16_bf16 v[4:19], v[98:101], v[110:113], v[4:19]
	ds_read_b128 v[98:101], v94
	ds_read_b128 v[102:105], v95
	s_waitcnt lgkmcnt(1)
	v_mfma_f32_32x32x16_bf16 v[52:67], v[114:117], v[98:101], v[52:67]
	s_waitcnt lgkmcnt(0)
	v_mfma_f32_32x32x16_bf16 v[36:51], v[114:117], v[102:105], v[36:51]
	v_mfma_f32_32x32x16_bf16 v[20:35], v[118:121], v[98:101], v[20:35]
	global_load_dwordx4 v[98:101], v[70:71], off offset:1152
	global_load_dwordx4 v[110:113], v[72:73], off offset:1152
	global_load_dwordx4 v[114:117], v[74:75], off offset:1152
	global_load_dwordx4 v[126:129], v[76:77], off offset:1152
	global_load_dwordx4 v[130:133], v[68:69], off offset:1152
	global_load_dwordx4 v[162:165], v[78:79], off offset:1152
	s_waitcnt vmcnt(11)
	ds_write_b128 v80, v[122:125]
	s_waitcnt vmcnt(10)
	ds_write_b128 v80, v[134:137] offset:9216
	s_waitcnt vmcnt(9)
	ds_write_b128 v80, v[138:141] offset:18432
	s_waitcnt vmcnt(8)
	ds_write_b128 v80, v[142:145] offset:27648
	s_waitcnt vmcnt(7)
	ds_write_b128 v80, v[146:149] offset:36864
	s_waitcnt vmcnt(6)
	ds_write_b128 v80, v[158:161] offset:46080
	s_waitcnt lgkmcnt(0)
	s_barrier
; #define MFMA32(a, b, c) __builtin_amdgcn_mfma_f32_32x32x16_bf16((a), (b), (c), 0, 0, 0)
; template <bool SWAP, class Epi>
; DI void gemm_tile(const u16* __restrict__ A, int lda, const u16* __restrict__ Bw, int ldb, int K, char* lds, Epi epi) {
;     ...
;   auto compute = [&](int st) {
;     const char* as = lds + st * GEMM_STAGE;
;     const char* bs = as + 36864;
; #pragma unroll
;     for (int ks = 0; ks < 4; ++ks) {
;       bf16x8 af[2], bfr[2];
; #pragma unroll
;       for (int mi = 0; mi < 2; ++mi) af[mi] = *(const bf16x8*)(as + ((wm * 64 + mi * 32 + r) * 72 + ks * 16 + 8 * h) * 2);
; #pragma unroll
;       for (int ni = 0; ni < 2; ++ni) bfr[ni] = *(const bf16x8*)(bs + ((wn * 64 + ni * 32 + r) * 72 + ks * 16 + 8 * h) * 2);
; #pragma unroll
;       for (int mi = 0; mi < 2; ++mi)
; #pragma unroll
;         for (int ni = 0; ni < 2; ++ni) {
;           if (SWAP) acc[mi][ni] = MFMA32(bfr[ni], af[mi], acc[mi][ni]);
;           else acc[mi][ni] = MFMA32(af[mi], bfr[ni], acc[mi][ni]);
;         }
;     }
;   };
;   gload(0, ra0, rb0);
;   lstore(0, ra0, rb0);
;   gload(1, ra1, rb1);
;   __syncthreads();
;   for (int kt = 0; kt < nk; kt += 2) {
;     if (kt + 2 < nk) gload(kt + 2, ra0, rb0);
;     compute(0);
;     lstore(1, ra1, rb1);
;     __syncthreads();
;     if (kt + 3 < nk) gload(kt + 3, ra1, rb1);
;     compute(1);
;     if (kt + 2 < nk) lstore(0, ra0, rb0);
;     __syncthreads();
	v_mfma_f32_32x32x16_bf16 v[4:19], v[118:121], v[102:105], v[4:19]
	ds_read_b128 v[102:105], v2
	ds_read_b128 v[118:121], v84 offset:36864
	ds_read_b128 v[122:125], v2 offset:32
	ds_read_b128 v[134:137], v2 offset:4608
	ds_read_b128 v[138:141], v84 offset:41472
	ds_read_b128 v[142:145], v84 offset:36960
	s_waitcnt lgkmcnt(4)
	v_mfma_f32_32x32x16_bf16 v[52:67], v[102:105], v[118:121], v[52:67]
	s_waitcnt lgkmcnt(1)
	v_mfma_f32_32x32x16_bf16 v[36:51], v[102:105], v[138:141], v[36:51]
	v_mfma_f32_32x32x16_bf16 v[20:35], v[134:137], v[118:121], v[20:35]
	ds_read_b128 v[102:105], v84 offset:36896
	ds_read_b128 v[118:121], v84 offset:36928
	v_mfma_f32_32x32x16_bf16 v[4:19], v[134:137], v[138:141], v[4:19]
	ds_read_b128 v[134:137], v87 offset:41472
	ds_read_b128 v[138:141], v82 offset:4608
	s_waitcnt lgkmcnt(3)
	v_mfma_f32_32x32x16_bf16 v[52:67], v[122:125], v[102:105], v[52:67]
	s_waitcnt lgkmcnt(1)
	v_mfma_f32_32x32x16_bf16 v[36:51], v[122:125], v[134:137], v[36:51]
	s_waitcnt lgkmcnt(0)
	v_mfma_f32_32x32x16_bf16 v[20:35], v[138:141], v[102:105], v[20:35]
	ds_read_b128 v[102:105], v2 offset:64
	ds_read_b128 v[122:125], v2 offset:96
	v_mfma_f32_32x32x16_bf16 v[4:19], v[138:141], v[134:137], v[4:19]
	ds_read_b128 v[134:137], v90 offset:41472
	ds_read_b128 v[138:141], v81 offset:4608
	s_waitcnt lgkmcnt(3)
	v_mfma_f32_32x32x16_bf16 v[52:67], v[102:105], v[118:121], v[52:67]
	s_waitcnt lgkmcnt(1)
	v_mfma_f32_32x32x16_bf16 v[36:51], v[102:105], v[134:137], v[36:51]
	s_waitcnt lgkmcnt(0)
	v_mfma_f32_32x32x16_bf16 v[20:35], v[138:141], v[118:121], v[20:35]
	ds_read_b128 v[102:105], v93 offset:41472
	ds_read_b128 v[118:121], v83 offset:4608
	v_mfma_f32_32x32x16_bf16 v[4:19], v[138:141], v[134:137], v[4:19]
	v_mfma_f32_32x32x16_bf16 v[52:67], v[122:125], v[142:145], v[52:67]
	s_waitcnt lgkmcnt(1)
	v_mfma_f32_32x32x16_bf16 v[36:51], v[122:125], v[102:105], v[36:51]
	s_waitcnt lgkmcnt(0)
	v_mfma_f32_32x32x16_bf16 v[20:35], v[118:121], v[142:145], v[20:35]
	global_load_dwordx4 v[122:125], v[70:71], off offset:1280
	global_load_dwordx4 v[134:137], v[72:73], off offset:1280
	global_load_dwordx4 v[138:141], v[74:75], off offset:1280
	global_load_dwordx4 v[142:145], v[76:77], off offset:1280
	global_load_dwordx4 v[146:149], v[68:69], off offset:1280
	global_load_dwordx4 v[158:161], v[78:79], off offset:1280
	s_waitcnt vmcnt(11)
	ds_write_b128 v80, v[98:101] offset:55296
	s_waitcnt vmcnt(10)
	ds_write_b128 v80, v[110:113] offset:64512
	s_waitcnt vmcnt(9)
	ds_write_b128 v89, v[114:117] offset:18432
	s_waitcnt vmcnt(8)
	ds_write_b128 v89, v[126:129] offset:27648
	s_waitcnt vmcnt(7)
	ds_write_b128 v91, v[130:133]
	s_waitcnt vmcnt(6)
	ds_write_b128 v91, v[162:165] offset:9216
	s_waitcnt lgkmcnt(0)
	s_barrier
	v_mfma_f32_32x32x16_bf16 v[4:19], v[118:121], v[102:105], v[4:19]
	ds_read_b128 v[98:101], v2 offset:55296
	ds_read_b128 v[102:105], v96
	ds_read_b128 v[110:113], v97
	ds_read_b128 v[114:117], v2 offset:55328
	s_waitcnt lgkmcnt(2)
	v_mfma_f32_32x32x16_bf16 v[52:67], v[98:101], v[102:105], v[52:67]
	s_waitcnt lgkmcnt(1)
	v_mfma_f32_32x32x16_bf16 v[36:51], v[98:101], v[110:113], v[36:51]
	ds_read_b128 v[98:101], v2 offset:59904
	ds_read_b128 v[118:121], v82 offset:59904
	s_waitcnt lgkmcnt(1)
	v_mfma_f32_32x32x16_bf16 v[20:35], v[98:101], v[102:105], v[20:35]
	v_mfma_f32_32x32x16_bf16 v[4:19], v[98:101], v[110:113], v[4:19]
	ds_read_b128 v[98:101], v85
	ds_read_b128 v[102:105], v86
	s_waitcnt lgkmcnt(1)
	v_mfma_f32_32x32x16_bf16 v[52:67], v[114:117], v[98:101], v[52:67]
	s_waitcnt lgkmcnt(0)
	v_mfma_f32_32x32x16_bf16 v[36:51], v[114:117], v[102:105], v[36:51]
	v_mfma_f32_32x32x16_bf16 v[20:35], v[118:121], v[98:101], v[20:35]
	v_mfma_f32_32x32x16_bf16 v[4:19], v[118:121], v[102:105], v[4:19]
	ds_read_b128 v[98:101], v2 offset:55360
	ds_read_b128 v[102:105], v88
	ds_read_b128 v[110:113], v92
	ds_read_b128 v[114:117], v2 offset:55392
	s_waitcnt lgkmcnt(2)
	v_mfma_f32_32x32x16_bf16 v[52:67], v[98:101], v[102:105], v[52:67]
	s_waitcnt lgkmcnt(1)
	v_mfma_f32_32x32x16_bf16 v[36:51], v[98:101], v[110:113], v[36:51]
	ds_read_b128 v[98:101], v81 offset:59904
	ds_read_b128 v[118:121], v83 offset:59904
	s_waitcnt lgkmcnt(1)
	v_mfma_f32_32x32x16_bf16 v[20:35], v[98:101], v[102:105], v[20:35]
	v_mfma_f32_32x32x16_bf16 v[4:19], v[98:101], v[110:113], v[4:19]
	ds_read_b128 v[98:101], v94
	ds_read_b128 v[102:105], v95
	s_waitcnt lgkmcnt(1)
	v_mfma_f32_32x32x16_bf16 v[52:67], v[114:117], v[98:101], v[52:67]
	s_waitcnt lgkmcnt(0)
	v_mfma_f32_32x32x16_bf16 v[36:51], v[114:117], v[102:105], v[36:51]
	v_mfma_f32_32x32x16_bf16 v[20:35], v[118:121], v[98:101], v[20:35]
	global_load_dwordx4 v[98:101], v[70:71], off offset:1408
	global_load_dwordx4 v[110:113], v[72:73], off offset:1408
	global_load_dwordx4 v[114:117], v[74:75], off offset:1408
	global_load_dwordx4 v[126:129], v[76:77], off offset:1408
	global_load_dwordx4 v[130:133], v[68:69], off offset:1408
	global_load_dwordx4 v[162:165], v[78:79], off offset:1408
	s_waitcnt vmcnt(11)
	ds_write_b128 v80, v[122:125]
	s_waitcnt vmcnt(10)
	ds_write_b128 v80, v[134:137] offset:9216
	s_waitcnt vmcnt(9)
	ds_write_b128 v80, v[138:141] offset:18432
	s_waitcnt vmcnt(8)
	ds_write_b128 v80, v[142:145] offset:27648
	s_waitcnt vmcnt(7)
	ds_write_b128 v80, v[146:149] offset:36864
	s_waitcnt vmcnt(6)
	ds_write_b128 v80, v[158:161] offset:46080
	s_waitcnt lgkmcnt(0)
	s_barrier
; #define MFMA32(a, b, c) __builtin_amdgcn_mfma_f32_32x32x16_bf16((a), (b), (c), 0, 0, 0)
; template <bool SWAP, class Epi>
; DI void gemm_tile(const u16* __restrict__ A, int lda, const u16* __restrict__ Bw, int ldb, int K, char* lds, Epi epi) {
;     ...
;   auto compute = [&](int st) {
;     const char* as = lds + st * GEMM_STAGE;
;     const char* bs = as + 36864;
; #pragma unroll
;     for (int ks = 0; ks < 4; ++ks) {
;       bf16x8 af[2], bfr[2];
; #pragma unroll
;       for (int mi = 0; mi < 2; ++mi) af[mi] = *(const bf16x8*)(as + ((wm * 64 + mi * 32 + r) * 72 + ks * 16 + 8 * h) * 2);
; #pragma unroll
;       for (int ni = 0; ni < 2; ++ni) bfr[ni] = *(const bf16x8*)(bs + ((wn * 64 + ni * 32 + r) * 72 + ks * 16 + 8 * h) * 2);
; #pragma unroll
;       for (int mi = 0; mi < 2; ++mi)
; #pragma unroll
;         for (int ni = 0; ni < 2; ++ni) {
;           if (SWAP) acc[mi][ni] = MFMA32(bfr[ni], af[mi], acc[mi][ni]);
;           else acc[mi][ni] = MFMA32(af[mi], bfr[ni], acc[mi][ni]);
;         }
;     }
;   };
;   gload(0, ra0, rb0);
;   lstore(0, ra0, rb0);
;   gload(1, ra1, rb1);
;   __syncthreads();
;   for (int kt = 0; kt < nk; kt += 2) {
;     if (kt + 2 < nk) gload(kt + 2, ra0, rb0);
;     compute(0);
;     lstore(1, ra1, rb1);
;     __syncthreads();
;     if (kt + 3 < nk) gload(kt + 3, ra1, rb1);
;     compute(1);
;     if (kt + 2 < nk) lstore(0, ra0, rb0);
;     __syncthreads();
	v_mfma_f32_32x32x16_bf16 v[4:19], v[118:121], v[102:105], v[4:19]
	ds_read_b128 v[102:105], v2
	ds_read_b128 v[118:121], v84 offset:36864
	ds_read_b128 v[122:125], v2 offset:32
	ds_read_b128 v[134:137], v2 offset:4608
	ds_read_b128 v[138:141], v84 offset:41472
	ds_read_b128 v[142:145], v84 offset:36960
	s_waitcnt lgkmcnt(4)
	v_mfma_f32_32x32x16_bf16 v[52:67], v[102:105], v[118:121], v[52:67]
	s_waitcnt lgkmcnt(1)
	v_mfma_f32_32x32x16_bf16 v[36:51], v[102:105], v[138:141], v[36:51]
	v_mfma_f32_32x32x16_bf16 v[20:35], v[134:137], v[118:121], v[20:35]
	ds_read_b128 v[102:105], v84 offset:36896
	ds_read_b128 v[118:121], v84 offset:36928
	v_mfma_f32_32x32x16_bf16 v[4:19], v[134:137], v[138:141], v[4:19]
	ds_read_b128 v[134:137], v87 offset:41472
	ds_read_b128 v[138:141], v82 offset:4608
	s_waitcnt lgkmcnt(3)
	v_mfma_f32_32x32x16_bf16 v[52:67], v[122:125], v[102:105], v[52:67]
	s_waitcnt lgkmcnt(1)
	v_mfma_f32_32x32x16_bf16 v[36:51], v[122:125], v[134:137], v[36:51]
	s_waitcnt lgkmcnt(0)
	v_mfma_f32_32x32x16_bf16 v[20:35], v[138:141], v[102:105], v[20:35]
	ds_read_b128 v[102:105], v2 offset:64
	ds_read_b128 v[122:125], v2 offset:96
	v_mfma_f32_32x32x16_bf16 v[4:19], v[138:141], v[134:137], v[4:19]
	ds_read_b128 v[134:137], v90 offset:41472
	ds_read_b128 v[138:141], v81 offset:4608
	s_waitcnt lgkmcnt(3)
	v_mfma_f32_32x32x16_bf16 v[52:67], v[102:105], v[118:121], v[52:67]
	s_waitcnt lgkmcnt(1)
	v_mfma_f32_32x32x16_bf16 v[36:51], v[102:105], v[134:137], v[36:51]
	s_waitcnt lgkmcnt(0)
	v_mfma_f32_32x32x16_bf16 v[20:35], v[138:141], v[118:121], v[20:35]
	ds_read_b128 v[102:105], v93 offset:41472
	ds_read_b128 v[118:121], v83 offset:4608
	v_mfma_f32_32x32x16_bf16 v[4:19], v[138:141], v[134:137], v[4:19]
	v_mfma_f32_32x32x16_bf16 v[52:67], v[122:125], v[142:145], v[52:67]
	s_waitcnt lgkmcnt(1)
	v_mfma_f32_32x32x16_bf16 v[36:51], v[122:125], v[102:105], v[36:51]
	s_waitcnt lgkmcnt(0)
	v_mfma_f32_32x32x16_bf16 v[20:35], v[118:121], v[142:145], v[20:35]
	global_load_dwordx4 v[122:125], v[70:71], off offset:1536
	global_load_dwordx4 v[134:137], v[72:73], off offset:1536
	global_load_dwordx4 v[138:141], v[74:75], off offset:1536
	global_load_dwordx4 v[142:145], v[76:77], off offset:1536
	global_load_dwordx4 v[146:149], v[68:69], off offset:1536
	global_load_dwordx4 v[158:161], v[78:79], off offset:1536
	s_waitcnt vmcnt(11)
	ds_write_b128 v80, v[98:101] offset:55296
	s_waitcnt vmcnt(10)
	ds_write_b128 v80, v[110:113] offset:64512
	s_waitcnt vmcnt(9)
	ds_write_b128 v89, v[114:117] offset:18432
	s_waitcnt vmcnt(8)
	ds_write_b128 v89, v[126:129] offset:27648
	s_waitcnt vmcnt(7)
	ds_write_b128 v91, v[130:133]
	s_waitcnt vmcnt(6)
	ds_write_b128 v91, v[162:165] offset:9216
	s_waitcnt lgkmcnt(0)
	s_barrier
	v_mfma_f32_32x32x16_bf16 v[4:19], v[118:121], v[102:105], v[4:19]
	ds_read_b128 v[98:101], v2 offset:55296
	ds_read_b128 v[102:105], v96
	ds_read_b128 v[110:113], v97
	ds_read_b128 v[114:117], v2 offset:55328
	s_waitcnt lgkmcnt(2)
	v_mfma_f32_32x32x16_bf16 v[52:67], v[98:101], v[102:105], v[52:67]
	s_waitcnt lgkmcnt(1)
	v_mfma_f32_32x32x16_bf16 v[36:51], v[98:101], v[110:113], v[36:51]
	ds_read_b128 v[98:101], v2 offset:59904
	ds_read_b128 v[118:121], v82 offset:59904
	s_waitcnt lgkmcnt(1)
	v_mfma_f32_32x32x16_bf16 v[20:35], v[98:101], v[102:105], v[20:35]
	v_mfma_f32_32x32x16_bf16 v[4:19], v[98:101], v[110:113], v[4:19]
	ds_read_b128 v[98:101], v85
	ds_read_b128 v[102:105], v86
	s_waitcnt lgkmcnt(1)
	v_mfma_f32_32x32x16_bf16 v[52:67], v[114:117], v[98:101], v[52:67]
	s_waitcnt lgkmcnt(0)
	v_mfma_f32_32x32x16_bf16 v[36:51], v[114:117], v[102:105], v[36:51]
	v_mfma_f32_32x32x16_bf16 v[20:35], v[118:121], v[98:101], v[20:35]
	v_mfma_f32_32x32x16_bf16 v[4:19], v[118:121], v[102:105], v[4:19]
	ds_read_b128 v[98:101], v2 offset:55360
	ds_read_b128 v[102:105], v88
	ds_read_b128 v[110:113], v92
	ds_read_b128 v[114:117], v2 offset:55392
	s_waitcnt lgkmcnt(2)
	v_mfma_f32_32x32x16_bf16 v[52:67], v[98:101], v[102:105], v[52:67]
	s_waitcnt lgkmcnt(1)
	v_mfma_f32_32x32x16_bf16 v[36:51], v[98:101], v[110:113], v[36:51]
	ds_read_b128 v[98:101], v81 offset:59904
	ds_read_b128 v[118:121], v83 offset:59904
	s_waitcnt lgkmcnt(1)
	v_mfma_f32_32x32x16_bf16 v[20:35], v[98:101], v[102:105], v[20:35]
	v_mfma_f32_32x32x16_bf16 v[4:19], v[98:101], v[110:113], v[4:19]
	ds_read_b128 v[98:101], v94
	ds_read_b128 v[102:105], v95
	s_waitcnt lgkmcnt(1)
	v_mfma_f32_32x32x16_bf16 v[52:67], v[114:117], v[98:101], v[52:67]
	s_waitcnt lgkmcnt(0)
	v_mfma_f32_32x32x16_bf16 v[36:51], v[114:117], v[102:105], v[36:51]
	v_mfma_f32_32x32x16_bf16 v[20:35], v[118:121], v[98:101], v[20:35]
	global_load_dwordx4 v[98:101], v[70:71], off offset:1664
	global_load_dwordx4 v[110:113], v[72:73], off offset:1664
	global_load_dwordx4 v[114:117], v[74:75], off offset:1664
	global_load_dwordx4 v[126:129], v[76:77], off offset:1664
	global_load_dwordx4 v[130:133], v[68:69], off offset:1664
	global_load_dwordx4 v[162:165], v[78:79], off offset:1664
	s_waitcnt vmcnt(11)
	ds_write_b128 v80, v[122:125]
	s_waitcnt vmcnt(10)
	ds_write_b128 v80, v[134:137] offset:9216
	s_waitcnt vmcnt(9)
	ds_write_b128 v80, v[138:141] offset:18432
	s_waitcnt vmcnt(8)
	ds_write_b128 v80, v[142:145] offset:27648
	s_waitcnt vmcnt(7)
	ds_write_b128 v80, v[146:149] offset:36864
	s_waitcnt vmcnt(6)
	ds_write_b128 v80, v[158:161] offset:46080
	s_waitcnt lgkmcnt(0)
	s_barrier
; #define MFMA32(a, b, c) __builtin_amdgcn_mfma_f32_32x32x16_bf16((a), (b), (c), 0, 0, 0)
; template <bool SWAP, class Epi>
; DI void gemm_tile(const u16* __restrict__ A, int lda, const u16* __restrict__ Bw, int ldb, int K, char* lds, Epi epi) {
;     ...
;   auto compute = [&](int st) {
;     const char* as = lds + st * GEMM_STAGE;
;     const char* bs = as + 36864;
; #pragma unroll
;     for (int ks = 0; ks < 4; ++ks) {
;       bf16x8 af[2], bfr[2];
; #pragma unroll
;       for (int mi = 0; mi < 2; ++mi) af[mi] = *(const bf16x8*)(as + ((wm * 64 + mi * 32 + r) * 72 + ks * 16 + 8 * h) * 2);
; #pragma unroll
;       for (int ni = 0; ni < 2; ++ni) bfr[ni] = *(const bf16x8*)(bs + ((wn * 64 + ni * 32 + r) * 72 + ks * 16 + 8 * h) * 2);
; #pragma unroll
;       for (int mi = 0; mi < 2; ++mi)
; #pragma unroll
;         for (int ni = 0; ni < 2; ++ni) {
;           if (SWAP) acc[mi][ni] = MFMA32(bfr[ni], af[mi], acc[mi][ni]);
;           else acc[mi][ni] = MFMA32(af[mi], bfr[ni], acc[mi][ni]);
;         }
;     }
;   };
;   gload(0, ra0, rb0);
;   lstore(0, ra0, rb0);
;   gload(1, ra1, rb1);
;   __syncthreads();
;   for (int kt = 0; kt < nk; kt += 2) {
;     if (kt + 2 < nk) gload(kt + 2, ra0, rb0);
;     compute(0);
;     lstore(1, ra1, rb1);
;     __syncthreads();
;     if (kt + 3 < nk) gload(kt + 3, ra1, rb1);
;     compute(1);
;     if (kt + 2 < nk) lstore(0, ra0, rb0);
;     __syncthreads();
	v_mfma_f32_32x32x16_bf16 v[4:19], v[118:121], v[102:105], v[4:19]
	ds_read_b128 v[102:105], v2
	ds_read_b128 v[118:121], v84 offset:36864
	ds_read_b128 v[122:125], v2 offset:32
	ds_read_b128 v[134:137], v2 offset:4608
	ds_read_b128 v[138:141], v84 offset:41472
	ds_read_b128 v[142:145], v84 offset:36960
	s_waitcnt lgkmcnt(4)
	v_mfma_f32_32x32x16_bf16 v[52:67], v[102:105], v[118:121], v[52:67]
	s_waitcnt lgkmcnt(1)
	v_mfma_f32_32x32x16_bf16 v[36:51], v[102:105], v[138:141], v[36:51]
	v_mfma_f32_32x32x16_bf16 v[20:35], v[134:137], v[118:121], v[20:35]
	ds_read_b128 v[102:105], v84 offset:36896
	ds_read_b128 v[118:121], v84 offset:36928
	v_mfma_f32_32x32x16_bf16 v[4:19], v[134:137], v[138:141], v[4:19]
	ds_read_b128 v[134:137], v87 offset:41472
	ds_read_b128 v[138:141], v82 offset:4608
	s_waitcnt lgkmcnt(3)
	v_mfma_f32_32x32x16_bf16 v[52:67], v[122:125], v[102:105], v[52:67]
	s_waitcnt lgkmcnt(1)
	v_mfma_f32_32x32x16_bf16 v[36:51], v[122:125], v[134:137], v[36:51]
	s_waitcnt lgkmcnt(0)
	v_mfma_f32_32x32x16_bf16 v[20:35], v[138:141], v[102:105], v[20:35]
	ds_read_b128 v[102:105], v2 offset:64
	ds_read_b128 v[122:125], v2 offset:96
	v_mfma_f32_32x32x16_bf16 v[4:19], v[138:141], v[134:137], v[4:19]
	ds_read_b128 v[134:137], v90 offset:41472
	ds_read_b128 v[138:141], v81 offset:4608
	s_waitcnt lgkmcnt(3)
	v_mfma_f32_32x32x16_bf16 v[52:67], v[102:105], v[118:121], v[52:67]
	s_waitcnt lgkmcnt(1)
	v_mfma_f32_32x32x16_bf16 v[36:51], v[102:105], v[134:137], v[36:51]
	s_waitcnt lgkmcnt(0)
	v_mfma_f32_32x32x16_bf16 v[20:35], v[138:141], v[118:121], v[20:35]
	ds_read_b128 v[102:105], v93 offset:41472
	ds_read_b128 v[118:121], v83 offset:4608
	v_mfma_f32_32x32x16_bf16 v[4:19], v[138:141], v[134:137], v[4:19]
	v_mfma_f32_32x32x16_bf16 v[52:67], v[122:125], v[142:145], v[52:67]
	s_waitcnt lgkmcnt(1)
	v_mfma_f32_32x32x16_bf16 v[36:51], v[122:125], v[102:105], v[36:51]
	s_waitcnt lgkmcnt(0)
	v_mfma_f32_32x32x16_bf16 v[20:35], v[118:121], v[142:145], v[20:35]
	global_load_dwordx4 v[122:125], v[70:71], off offset:1792
	global_load_dwordx4 v[134:137], v[72:73], off offset:1792
	global_load_dwordx4 v[138:141], v[74:75], off offset:1792
	global_load_dwordx4 v[142:145], v[76:77], off offset:1792
	global_load_dwordx4 v[146:149], v[68:69], off offset:1792
	global_load_dwordx4 v[158:161], v[78:79], off offset:1792
	s_waitcnt vmcnt(11)
	ds_write_b128 v80, v[98:101] offset:55296
	s_waitcnt vmcnt(10)
	ds_write_b128 v80, v[110:113] offset:64512
	s_waitcnt vmcnt(9)
	ds_write_b128 v89, v[114:117] offset:18432
	s_waitcnt vmcnt(8)
	ds_write_b128 v89, v[126:129] offset:27648
	s_waitcnt vmcnt(7)
	ds_write_b128 v91, v[130:133]
	s_waitcnt vmcnt(6)
	ds_write_b128 v91, v[162:165] offset:9216
	s_waitcnt lgkmcnt(0)
	s_barrier
	v_mfma_f32_32x32x16_bf16 v[4:19], v[118:121], v[102:105], v[4:19]
	ds_read_b128 v[98:101], v2 offset:55296
	ds_read_b128 v[102:105], v96
	ds_read_b128 v[110:113], v97
	ds_read_b128 v[114:117], v2 offset:55328
	s_waitcnt lgkmcnt(2)
	v_mfma_f32_32x32x16_bf16 v[52:67], v[98:101], v[102:105], v[52:67]
	s_waitcnt lgkmcnt(1)
	v_mfma_f32_32x32x16_bf16 v[36:51], v[98:101], v[110:113], v[36:51]
	ds_read_b128 v[98:101], v2 offset:59904
	ds_read_b128 v[118:121], v82 offset:59904
	s_waitcnt lgkmcnt(1)
	v_mfma_f32_32x32x16_bf16 v[20:35], v[98:101], v[102:105], v[20:35]
	v_mfma_f32_32x32x16_bf16 v[4:19], v[98:101], v[110:113], v[4:19]
	ds_read_b128 v[98:101], v85
	ds_read_b128 v[102:105], v86
	s_waitcnt lgkmcnt(1)
	v_mfma_f32_32x32x16_bf16 v[52:67], v[114:117], v[98:101], v[52:67]
	s_waitcnt lgkmcnt(0)
	v_mfma_f32_32x32x16_bf16 v[36:51], v[114:117], v[102:105], v[36:51]
	v_mfma_f32_32x32x16_bf16 v[20:35], v[118:121], v[98:101], v[20:35]
	v_mfma_f32_32x32x16_bf16 v[4:19], v[118:121], v[102:105], v[4:19]
	ds_read_b128 v[98:101], v2 offset:55360
	ds_read_b128 v[102:105], v88
	ds_read_b128 v[110:113], v92
	ds_read_b128 v[114:117], v2 offset:55392
	s_waitcnt lgkmcnt(2)
	v_mfma_f32_32x32x16_bf16 v[52:67], v[98:101], v[102:105], v[52:67]
	s_waitcnt lgkmcnt(1)
	v_mfma_f32_32x32x16_bf16 v[36:51], v[98:101], v[110:113], v[36:51]
	ds_read_b128 v[98:101], v81 offset:59904
	ds_read_b128 v[118:121], v83 offset:59904
	s_waitcnt lgkmcnt(1)
	v_mfma_f32_32x32x16_bf16 v[20:35], v[98:101], v[102:105], v[20:35]
	v_mfma_f32_32x32x16_bf16 v[4:19], v[98:101], v[110:113], v[4:19]
	ds_read_b128 v[98:101], v94
	ds_read_b128 v[102:105], v95
	s_waitcnt lgkmcnt(1)
	v_mfma_f32_32x32x16_bf16 v[52:67], v[114:117], v[98:101], v[52:67]
	s_waitcnt lgkmcnt(0)
	v_mfma_f32_32x32x16_bf16 v[36:51], v[114:117], v[102:105], v[36:51]
	v_mfma_f32_32x32x16_bf16 v[20:35], v[118:121], v[98:101], v[20:35]
	global_load_dwordx4 v[98:101], v[70:71], off offset:1920
	s_nop 0
	global_load_dwordx4 v[70:73], v[72:73], off offset:1920
	s_nop 0
	global_load_dwordx4 v[110:113], v[74:75], off offset:1920
	s_nop 0
	global_load_dwordx4 v[74:77], v[76:77], off offset:1920
	s_nop 0
	global_load_dwordx4 v[114:117], v[68:69], off offset:1920
	global_load_dwordx4 v[126:129], v[78:79], off offset:1920
	s_waitcnt vmcnt(11)
	ds_write_b128 v80, v[122:125]
	s_waitcnt vmcnt(10)
	ds_write_b128 v80, v[134:137] offset:9216
	s_waitcnt vmcnt(9)
	ds_write_b128 v80, v[138:141] offset:18432
	s_waitcnt vmcnt(8)
	ds_write_b128 v80, v[142:145] offset:27648
	s_waitcnt vmcnt(7)
	ds_write_b128 v80, v[146:149] offset:36864
	s_waitcnt vmcnt(6)
	ds_write_b128 v80, v[158:161] offset:46080
	s_waitcnt lgkmcnt(0)
	s_barrier
; #define MFMA32(a, b, c) __builtin_amdgcn_mfma_f32_32x32x16_bf16((a), (b), (c), 0, 0, 0)
; template <bool SWAP, class Epi>
; DI void gemm_tile(const u16* __restrict__ A, int lda, const u16* __restrict__ Bw, int ldb, int K, char* lds, Epi epi) {
;     ...
;   auto compute = [&](int st) {
;     const char* as = lds + st * GEMM_STAGE;
;     const char* bs = as + 36864;
; #pragma unroll
;     for (int ks = 0; ks < 4; ++ks) {
;       bf16x8 af[2], bfr[2];
; #pragma unroll
;       for (int mi = 0; mi < 2; ++mi) af[mi] = *(const bf16x8*)(as + ((wm * 64 + mi * 32 + r) * 72 + ks * 16 + 8 * h) * 2);
; #pragma unroll
;       for (int ni = 0; ni < 2; ++ni) bfr[ni] = *(const bf16x8*)(bs + ((wn * 64 + ni * 32 + r) * 72 + ks * 16 + 8 * h) * 2);
; #pragma unroll
;       for (int mi = 0; mi < 2; ++mi)
; #pragma unroll
;         for (int ni = 0; ni < 2; ++ni) {
;           if (SWAP) acc[mi][ni] = MFMA32(bfr[ni], af[mi], acc[mi][ni]);
;           else acc[mi][ni] = MFMA32(af[mi], bfr[ni], acc[mi][ni]);
;         }
;     }
;   };
;   gload(0, ra0, rb0);
;   lstore(0, ra0, rb0);
;   gload(1, ra1, rb1);
;   __syncthreads();
;   for (int kt = 0; kt < nk; kt += 2) {
;     if (kt + 2 < nk) gload(kt + 2, ra0, rb0);
;     compute(0);
;     lstore(1, ra1, rb1);
;     __syncthreads();
;     if (kt + 3 < nk) gload(kt + 3, ra1, rb1);
;     compute(1);
;     if (kt + 2 < nk) lstore(0, ra0, rb0);
;     __syncthreads();
	v_mfma_f32_32x32x16_bf16 v[4:19], v[118:121], v[102:105], v[4:19]
	ds_read_b128 v[102:105], v2
	ds_read_b128 v[118:121], v84 offset:36864
	ds_read_b128 v[122:125], v2 offset:32
	ds_read_b128 v[130:133], v2 offset:4608
	ds_read_b128 v[134:137], v84 offset:41472
	ds_read_b128 v[138:141], v84 offset:36960
	s_waitcnt lgkmcnt(4)
	v_mfma_f32_32x32x16_bf16 v[52:67], v[102:105], v[118:121], v[52:67]
	s_waitcnt lgkmcnt(1)
	v_mfma_f32_32x32x16_bf16 v[36:51], v[102:105], v[134:137], v[36:51]
	v_mfma_f32_32x32x16_bf16 v[20:35], v[130:133], v[118:121], v[20:35]
	ds_read_b128 v[102:105], v84 offset:36896
	ds_read_b128 v[118:121], v84 offset:36928
	v_mfma_f32_32x32x16_bf16 v[4:19], v[130:133], v[134:137], v[4:19]
	ds_read_b128 v[130:133], v87 offset:41472
	ds_read_b128 v[134:137], v82 offset:4608
	s_waitcnt lgkmcnt(3)
	v_mfma_f32_32x32x16_bf16 v[52:67], v[122:125], v[102:105], v[52:67]
	s_waitcnt lgkmcnt(1)
	v_mfma_f32_32x32x16_bf16 v[36:51], v[122:125], v[130:133], v[36:51]
	s_waitcnt lgkmcnt(0)
	v_mfma_f32_32x32x16_bf16 v[20:35], v[134:137], v[102:105], v[20:35]
	ds_read_b128 v[102:105], v2 offset:64
	ds_read_b128 v[122:125], v2 offset:96
	s_waitcnt lgkmcnt(1)
	v_mfma_f32_32x32x16_bf16 v[52:67], v[102:105], v[118:121], v[52:67]
	v_mfma_f32_32x32x16_bf16 v[4:19], v[134:137], v[130:133], v[4:19]
	ds_read_b128 v[130:133], v90 offset:41472
	ds_read_b128 v[134:137], v81 offset:4608
	s_waitcnt lgkmcnt(1)
	v_mfma_f32_32x32x16_bf16 v[36:51], v[102:105], v[130:133], v[36:51]
	v_mfma_f32_32x32x16_bf16 v[52:67], v[122:125], v[138:141], v[52:67]
	s_waitcnt lgkmcnt(0)
	v_mfma_f32_32x32x16_bf16 v[20:35], v[134:137], v[118:121], v[20:35]
	ds_read_b128 v[102:105], v93 offset:41472
	ds_read_b128 v[118:121], v83 offset:4608
	s_waitcnt vmcnt(5)
	ds_write_b128 v80, v[98:101] offset:55296
	s_waitcnt vmcnt(4)
	ds_write_b128 v80, v[70:73] offset:64512
	s_waitcnt vmcnt(3)
	ds_write_b128 v89, v[110:113] offset:18432
	s_waitcnt vmcnt(2)
	ds_write_b128 v89, v[74:77] offset:27648
	s_waitcnt vmcnt(1)
	ds_write_b128 v91, v[114:117]
	s_waitcnt vmcnt(0)
	ds_write_b128 v91, v[126:129] offset:9216
	s_waitcnt lgkmcnt(0)
	s_barrier
	ds_read_b128 v[68:71], v2 offset:55296
	ds_read_b128 v[72:75], v96
	ds_read_b128 v[76:79], v97
	ds_read_b128 v[96:99], v2 offset:55328
	v_mfma_f32_32x32x16_bf16 v[4:19], v[134:137], v[130:133], v[4:19]
	v_mfma_f32_32x32x16_bf16 v[36:51], v[122:125], v[102:105], v[36:51]
	s_waitcnt lgkmcnt(2)
	v_mfma_f32_32x32x16_bf16 v[52:67], v[68:71], v[72:75], v[52:67]
	v_mfma_f32_32x32x16_bf16 v[20:35], v[118:121], v[138:141], v[20:35]
	v_mfma_f32_32x32x16_bf16 v[4:19], v[118:121], v[102:105], v[4:19]
	ds_read_b128 v[100:103], v2 offset:59904
	s_waitcnt lgkmcnt(2)
	v_mfma_f32_32x32x16_bf16 v[36:51], v[68:71], v[76:79], v[36:51]
	ds_read_b128 v[68:71], v82 offset:59904
	ds_read_b128 v[110:113], v85
	ds_read_b128 v[84:87], v86
	ds_read_b128 v[88:91], v88
	ds_read_b128 v[114:117], v92
	ds_read_b128 v[118:121], v2 offset:55360
	ds_read_b128 v[122:125], v2 offset:55392
	s_waitcnt lgkmcnt(5)
	v_mfma_f32_32x32x16_bf16 v[52:67], v[96:99], v[110:113], v[52:67]
	s_waitcnt lgkmcnt(1)
	v_mfma_f32_32x32x16_bf16 v[52:67], v[118:121], v[88:91], v[52:67]
	v_mfma_f32_32x32x16_bf16 v[20:35], v[100:103], v[72:75], v[20:35]
	ds_read_b128 v[72:75], v81 offset:59904
	ds_read_b128 v[80:83], v83 offset:59904
	ds_read_b128 v[126:129], v94
	ds_read_b128 v[92:95], v95
	s_waitcnt lgkmcnt(0)
	s_barrier
; DI unsigned pk2(float a, float b) { f32x2 v = {a, b}; return __builtin_bit_cast(unsigned, __builtin_convertvector(v, bf2_t)); }
; DI void store_transposed(u16* dst, const f32x16& a, int h, const float* rs  ) {
; #pragma unroll
;   for (int g = 0; g < 4; ++g) {
;     float s0 = 1.f, s1 = 1.f, s2 = 1.f, s3 = 1.f;
;     if (rs) { f32x4 sv = *(const f32x4*)(rs + 8 * g + 4 * h); s0 = sv[0]; s1 = sv[1]; s2 = sv[2]; s3 = sv[3]; }
;     u32x2 v = {pk2(a[4 * g] * s0, a[4 * g + 1] * s1), pk2(a[4 * g + 2] * s2, a[4 * g + 3] * s3)};
;     *(u32x2*)(dst + 8 * g + 4 * h) = v;
;   }
; }
; DI void inproj_tile(const Params& p, int l, int mt, int nt, char* lds) {
;     ...
;     gemm_tile<false>(A, DM, Bw, DM, DM, lds, [&](int mi, int ni, const f32x16& a) {
;       const int b = m0 / PP, t0 = m0 - b * PP + wm * 64 + mi * 32;
;       const int col = c0 + wn * 64 + ni * 32 + r;
;       store_transposed(vt + ((size_t)b * nv + col) * PP + t0, a, h, nullptr);
;     });
	v_mfma_f32_32x32x16_bf16 v[36:51], v[96:99], v[84:87], v[36:51]
	v_mov_b64_e32 v[96:97], s[10:11]
	v_mfma_f32_32x32x16_bf16 v[4:19], v[100:103], v[76:79], v[4:19]
	v_lshlrev_b32_e32 v101, 6, v0
	v_add_u32_e32 v2, s3, v101
	v_or_b32_e32 v78, v2, v107
	v_lshlrev_b32_e32 v100, 6, v108
	v_ashrrev_i32_e32 v79, 31, v78
	v_or_b32_e32 v76, s5, v100
	v_lshl_add_u64 v[78:79], s[0:1], 0, v[78:79]
	v_mfma_f32_32x32x16_bf16 v[52:67], v[122:125], v[126:129], v[52:67]
	v_mad_u64_u32 v[98:99], s[10:11], v78, s12, v[96:97]
	v_ashrrev_i32_e32 v77, 31, v76
	v_mad_i32_i24 v99, v79, s12, v99
	v_lshlrev_b64 v[76:77], 1, v[76:77]
	v_lshl_add_u64 v[78:79], v[98:99], 0, v[76:77]
	v_lshlrev_b32_e32 v2, 3, v106
	v_mfma_f32_32x32x16_bf16 v[20:35], v[68:71], v[110:113], v[20:35]
	v_lshl_add_u64 v[78:79], v[78:79], 0, v[2:3]
	s_nop 3
	v_cvt_pk_bf16_f32 v52, v52, v53
	v_cvt_pk_bf16_f32 v53, v54, v55
	global_store_dwordx2 v[78:79], v[52:53], off
	v_cvt_pk_bf16_f32 v52, v56, v57
	v_cvt_pk_bf16_f32 v53, v58, v59
	global_store_dwordx2 v[78:79], v[52:53], off offset:16
	v_mfma_f32_32x32x16_bf16 v[36:51], v[118:121], v[114:117], v[36:51]
	v_cvt_pk_bf16_f32 v52, v60, v61
	v_cvt_pk_bf16_f32 v53, v62, v63
	global_store_dwordx2 v[78:79], v[52:53], off offset:32
	v_cvt_pk_bf16_f32 v52, v64, v65
	v_cvt_pk_bf16_f32 v53, v66, v67
	global_store_dwordx2 v[78:79], v[52:53], off offset:48
	v_or_b32_e32 v52, s3, v107
	v_mfma_f32_32x32x16_bf16 v[4:19], v[68:71], v[84:87], v[4:19]
	v_add3_u32 v52, v101, v52, 32
	v_ashrrev_i32_e32 v53, 31, v52
	v_lshl_add_u64 v[52:53], s[0:1], 0, v[52:53]
	v_mad_u64_u32 v[54:55], s[0:1], v52, s12, v[96:97]
	v_mad_i32_i24 v55, v53, s12, v55
	v_lshl_add_u64 v[52:53], v[54:55], 0, v[76:77]
	v_mfma_f32_32x32x16_bf16 v[36:51], v[122:125], v[92:95], v[36:51]
	v_lshl_add_u64 v[52:53], v[52:53], 0, v[2:3]
	s_add_i32 s5, s5, 32
	s_mov_b64 s[0:1], 0
	v_mfma_f32_32x32x16_bf16 v[20:35], v[72:75], v[88:91], v[20:35]
	s_nop 7
	v_cvt_pk_bf16_f32 v36, v36, v37
	v_cvt_pk_bf16_f32 v37, v38, v39
	global_store_dwordx2 v[52:53], v[36:37], off
	v_cvt_pk_bf16_f32 v36, v40, v41
	v_cvt_pk_bf16_f32 v37, v42, v43
	global_store_dwordx2 v[52:53], v[36:37], off offset:16
	v_cvt_pk_bf16_f32 v36, v44, v45
	v_mfma_f32_32x32x16_bf16 v[4:19], v[72:75], v[114:117], v[4:19]
	v_cvt_pk_bf16_f32 v37, v46, v47
	global_store_dwordx2 v[52:53], v[36:37], off offset:32
	v_cvt_pk_bf16_f32 v36, v48, v49
	v_cvt_pk_bf16_f32 v37, v50, v51
	global_store_dwordx2 v[52:53], v[36:37], off offset:48
	v_or_b32_e32 v36, s5, v100
	v_ashrrev_i32_e32 v37, 31, v36
	v_mfma_f32_32x32x16_bf16 v[20:35], v[80:83], v[126:129], v[20:35]
	v_lshlrev_b64 v[36:37], 1, v[36:37]
	v_lshl_add_u64 v[38:39], v[98:99], 0, v[36:37]
	v_lshl_add_u64 v[38:39], v[38:39], 0, v[2:3]
	v_mfma_f32_32x32x16_bf16 v[4:19], v[80:83], v[92:95], v[4:19]
	s_nop 7
	v_cvt_pk_bf16_f32 v20, v20, v21
	v_cvt_pk_bf16_f32 v21, v22, v23
	global_store_dwordx2 v[38:39], v[20:21], off
	v_cvt_pk_bf16_f32 v20, v24, v25
	v_cvt_pk_bf16_f32 v21, v26, v27
	global_store_dwordx2 v[38:39], v[20:21], off offset:16
	v_cvt_pk_bf16_f32 v20, v28, v29
	v_cvt_pk_bf16_f32 v21, v30, v31
	global_store_dwordx2 v[38:39], v[20:21], off offset:32
	v_cvt_pk_bf16_f32 v20, v32, v33
	v_cvt_pk_bf16_f32 v21, v34, v35
	global_store_dwordx2 v[38:39], v[20:21], off offset:48
	v_lshl_add_u64 v[20:21], v[54:55], 0, v[36:37]
	v_lshl_add_u64 v[20:21], v[20:21], 0, v[2:3]
	v_cvt_pk_bf16_f32 v4, v4, v5
	v_cvt_pk_bf16_f32 v5, v6, v7
	global_store_dwordx2 v[20:21], v[4:5], off
	v_cvt_pk_bf16_f32 v4, v8, v9
	v_cvt_pk_bf16_f32 v5, v10, v11
	global_store_dwordx2 v[20:21], v[4:5], off offset:16
	v_cvt_pk_bf16_f32 v4, v12, v13
	v_cvt_pk_bf16_f32 v5, v14, v15
	global_store_dwordx2 v[20:21], v[4:5], off offset:32
	v_cvt_pk_bf16_f32 v4, v16, v17
	v_cvt_pk_bf16_f32 v5, v18, v19
	global_store_dwordx2 v[20:21], v[4:5], off offset:48
